# LDS-DMA loads of the A operand marked sc1 (bypass the vector L1 so the partner-shared B tile stays resident)
# speedup vs baseline: 1.0207x; 1.0207x over previous
.LBB0_232:
	s_mul_hi_i32 s2, s8, 0x66666667
	s_lshr_b32 s3, s2, 31
	s_ashr_i32 s2, s2, 3
	s_add_i32 s34, s2, s3
	s_ashr_i32 s35, s34, 31
	v_readlane_b32 s36, v210, 50
	v_mov_b32_e32 v36, v133
	s_lshl_b64 s[2:3], s[34:35], 18
	v_readlane_b32 s38, v210, 52
	v_readlane_b32 s39, v210, 53
	v_ashrrev_i32_e32 v34, 3, v36
	s_add_u32 s2, s38, s2
	v_ashrrev_i32_e32 v35, 31, v34
	s_addc_u32 s3, s39, s3
	v_lshlrev_b64 v[2:3], 11, v[34:35]
	s_waitcnt vmcnt(0)
	v_lshlrev_b32_e32 v0, 4, v36
	v_lshl_add_u64 v[2:3], s[2:3], 0, v[2:3]
	v_and_b32_e32 v0, 0x70, v0
	s_mul_i32 s2, s34, 0xa00
	v_lshl_add_u64 v[66:67], v[2:3], 0, v[0:1]
	v_subrev_u32_e32 v2, s2, v34
	v_add_u32_e32 v2, s7, v2
	v_ashrrev_i32_e32 v3, 31, v2
	v_lshlrev_b64 v[2:3], 11, v[2:3]
	v_lshl_add_u64 v[2:3], s[0:1], 0, v[2:3]
	v_add_co_u32_e32 v70, vcc, s56, v66
	v_lshl_add_u64 v[68:69], v[2:3], 0, v[0:1]
	s_nop 0
	v_addc_co_u32_e32 v71, vcc, 0, v67, vcc
	v_add_co_u32_e32 v72, vcc, s56, v68
	v_addc_co_u32_e32 v73, vcc, 0, v69, vcc
	v_add_co_u32_e32 v74, vcc, s57, v66
	s_nop 0
	v_addc_co_u32_e32 v75, vcc, 0, v67, vcc
	v_add_co_u32_e32 v76, vcc, s57, v68
	s_nop 0
	v_addc_co_u32_e32 v77, vcc, 0, v69, vcc
	v_add_co_u32_e32 v78, vcc, s58, v66
	s_nop 0
	v_addc_co_u32_e32 v79, vcc, 0, v67, vcc
	v_add_co_u32_e32 v80, vcc, s58, v68
	v_lshlrev_b32_e32 v0, 7, v34
	s_nop 0
	v_addc_co_u32_e32 v81, vcc, 0, v69, vcc
	v_lshrrev_b32_e32 v216, 4, v133
	v_xor_b32_e32 v216, v216, v133
	v_and_b32_e32 v216, 7, v216
	v_lshlrev_b32_e32 v216, 4, v216
	v_mov_b32_e32 v217, 0x70
	v_lshrrev_b32_e32 v218, 6, v133
	v_lshlrev_b32_e32 v218, 10, v218
	s_nop 0
	v_readfirstlane_b32 s32, v218
	v_bfi_b32 v66, v217, v216, v66
	v_bfi_b32 v70, v217, v216, v70
	v_bfi_b32 v74, v217, v216, v74
	v_bfi_b32 v78, v217, v216, v78
	v_bfi_b32 v68, v217, v216, v68
	v_bfi_b32 v72, v217, v216, v72
	v_bfi_b32 v76, v217, v216, v76
	v_bfi_b32 v80, v217, v216, v80
	s_mov_b64 s[98:99], 0x80
	s_add_u32 m0, s32, 0x0
	s_nop 0
	global_load_lds_dwordx4 v[66:67], off sc1
	s_add_u32 m0, s32, 0x1000
	s_nop 0
	global_load_lds_dwordx4 v[70:71], off sc1
	s_add_u32 m0, s32, 0x2000
	s_nop 0
	global_load_lds_dwordx4 v[74:75], off sc1
	s_add_u32 m0, s32, 0x3000
	s_nop 0
	global_load_lds_dwordx4 v[78:79], off sc1
	s_add_u32 m0, s32, 0x8000
	s_nop 0
	global_load_lds_dwordx4 v[68:69], off
	s_add_u32 m0, s32, 0x9000
	s_nop 0
	global_load_lds_dwordx4 v[72:73], off
	s_add_u32 m0, s32, 0xa000
	s_nop 0
	global_load_lds_dwordx4 v[76:77], off
	s_add_u32 m0, s32, 0xb000
	s_nop 0
	global_load_lds_dwordx4 v[80:81], off
	v_lshl_add_u64 v[66:67], v[66:67], 0, s[98:99]
	v_lshl_add_u64 v[70:71], v[70:71], 0, s[98:99]
	v_lshl_add_u64 v[74:75], v[74:75], 0, s[98:99]
	v_lshl_add_u64 v[78:79], v[78:79], 0, s[98:99]
	v_lshl_add_u64 v[68:69], v[68:69], 0, s[98:99]
	v_lshl_add_u64 v[72:73], v[72:73], 0, s[98:99]
	v_lshl_add_u64 v[76:77], v[76:77], 0, s[98:99]
	v_lshl_add_u64 v[80:81], v[80:81], 0, s[98:99]
	s_add_u32 m0, s32, 0x4000
	s_nop 0
	global_load_lds_dwordx4 v[66:67], off sc1
	s_add_u32 m0, s32, 0x5000
	s_nop 0
	global_load_lds_dwordx4 v[70:71], off sc1
	s_add_u32 m0, s32, 0x6000
	s_nop 0
	global_load_lds_dwordx4 v[74:75], off sc1
	s_add_u32 m0, s32, 0x7000
	s_nop 0
	global_load_lds_dwordx4 v[78:79], off sc1
	s_add_u32 m0, s32, 0xc000
	s_nop 0
	global_load_lds_dwordx4 v[68:69], off
	s_add_u32 m0, s32, 0xd000
	s_nop 0
	global_load_lds_dwordx4 v[72:73], off
	s_add_u32 m0, s32, 0xe000
	s_nop 0
	global_load_lds_dwordx4 v[76:77], off
	s_add_u32 m0, s32, 0xf000
	s_nop 0
	global_load_lds_dwordx4 v[80:81], off
	v_lshrrev_b32_e32 v34, 1, v34
	v_xor_b32_e32 v34, v34, v36
	v_lshlrev_b32_e32 v34, 4, v34
	v_and_or_b32 v0, v34, s59, v0
	v_and_b32_e32 v84, 31, v36
	v_bfe_u32 v82, v36, 5, 1
	v_ashrrev_i32_e32 v83, 7, v36
	v_bfe_u32 v85, v36, 6, 1
	v_readlane_b32 s40, v210, 54
	v_readlane_b32 s41, v210, 55
	v_readlane_b32 s37, v210, 51
	v_readlane_b32 s42, v210, 56
	v_readlane_b32 s43, v210, 57
	v_readlane_b32 s44, v210, 58
	v_readlane_b32 s45, v210, 59
	v_readlane_b32 s46, v210, 60
	v_readlane_b32 s47, v210, 61
	v_readlane_b32 s48, v210, 62
	v_readlane_b32 s49, v210, 63
	v_readlane_b32 s50, v209, 0
	v_readlane_b32 s51, v209, 1
	v_lshl_add_u64 v[66:67], v[66:67], 0, s[98:99]
	v_lshl_add_u64 v[70:71], v[70:71], 0, s[98:99]
	v_lshl_add_u64 v[74:75], v[74:75], 0, s[98:99]
	v_lshl_add_u64 v[78:79], v[78:79], 0, s[98:99]
	v_lshl_add_u64 v[68:69], v[68:69], 0, s[98:99]
	v_lshl_add_u64 v[72:73], v[72:73], 0, s[98:99]
	v_lshl_add_u64 v[76:77], v[76:77], 0, s[98:99]
	v_lshl_add_u64 v[80:81], v[80:81], 0, s[98:99]
	s_waitcnt vmcnt(8)
	s_waitcnt lgkmcnt(0)
	s_barrier
	v_lshrrev_b32_e32 v4, 1, v36
	v_lshlrev_b32_e32 v2, 7, v84
	v_bitop3_b32 v4, v4, v82, 7 bitop3:0x6c
	v_lshl_or_b32 v3, v83, 13, v2
	v_bfe_u32 v5, v36, 1, 3
	v_lshlrev_b32_e32 v4, 4, v4
	v_lshl_or_b32 v2, v85, 13, v2
	v_or_b32_e32 v91, v3, v4
	v_or_b32_e32 v92, v2, v4
	v_bitop3_b32 v4, v82, v5, 2 bitop3:0x36
	v_lshlrev_b32_e32 v4, 4, v4
	v_or_b32_e32 v93, v3, v4
	v_or_b32_e32 v90, v2, v4
	v_bitop3_b32 v4, v82, v5, 4 bitop3:0x36
	v_lshlrev_b32_e32 v4, 4, v4
	v_or_b32_e32 v89, v3, v4
	v_or_b32_e32 v88, v2, v4
	v_bitop3_b32 v4, v82, v5, 6 bitop3:0x36
	v_lshlrev_b32_e32 v4, 4, v4
	v_or_b32_e32 v87, v3, v4
	v_or_b32_e32 v86, v2, v4
	ds_read_b128 v[2:5], v91
	ds_read_b128 v[6:9], v92 offset:32768
	ds_read_b128 v[10:13], v91 offset:4096
	ds_read_b128 v[14:17], v92 offset:36864
	ds_read_b128 v[162:165], v93
	ds_read_b128 v[166:169], v90 offset:32768
	ds_read_b128 v[182:185], v93 offset:4096
	ds_read_b128 v[186:189], v90 offset:36864
	s_waitcnt lgkmcnt(6)
	v_mfma_f32_32x32x16_bf16 v[50:65], v[2:5], v[6:9], 0
	s_waitcnt lgkmcnt(4)
	v_mfma_f32_32x32x16_bf16 v[34:49], v[2:5], v[14:17], 0
	v_mfma_f32_32x32x16_bf16 v[18:33], v[10:13], v[6:9], 0
	v_mfma_f32_32x32x16_bf16 v[2:17], v[10:13], v[14:17], 0
	ds_read_b128 v[190:193], v89
	ds_read_b128 v[194:197], v89 offset:4096
	ds_read_b128 v[198:201], v88 offset:32768
	ds_read_b128 v[202:205], v88 offset:36864
	s_waitcnt lgkmcnt(6)
	v_mfma_f32_32x32x16_bf16 v[50:65], v[162:165], v[166:169], v[50:65]
	s_waitcnt lgkmcnt(4)
	v_mfma_f32_32x32x16_bf16 v[34:49], v[162:165], v[186:189], v[34:49]
	v_mfma_f32_32x32x16_bf16 v[18:33], v[182:185], v[166:169], v[18:33]
	v_mfma_f32_32x32x16_bf16 v[2:17], v[182:185], v[186:189], v[2:17]
	ds_read_b128 v[162:165], v87
	ds_read_b128 v[166:169], v87 offset:4096
	ds_read_b128 v[182:185], v86 offset:32768
	ds_read_b128 v[186:189], v86 offset:36864
	s_waitcnt lgkmcnt(0)
	s_barrier
	s_add_u32 m0, s32, 0x0
	v_mfma_f32_32x32x16_bf16 v[50:65], v[190:193], v[198:201], v[50:65]
	global_load_lds_dwordx4 v[66:67], off sc1
	s_add_u32 m0, s32, 0x1000
	v_mfma_f32_32x32x16_bf16 v[34:49], v[190:193], v[202:205], v[34:49]
	global_load_lds_dwordx4 v[70:71], off sc1
	s_add_u32 m0, s32, 0x2000
	v_mfma_f32_32x32x16_bf16 v[18:33], v[194:197], v[198:201], v[18:33]
	global_load_lds_dwordx4 v[74:75], off sc1
	s_add_u32 m0, s32, 0x3000
	v_mfma_f32_32x32x16_bf16 v[2:17], v[194:197], v[202:205], v[2:17]
	global_load_lds_dwordx4 v[78:79], off sc1
	s_add_u32 m0, s32, 0x8000
	v_mfma_f32_32x32x16_bf16 v[50:65], v[162:165], v[182:185], v[50:65]
	global_load_lds_dwordx4 v[68:69], off
	s_add_u32 m0, s32, 0x9000
	v_mfma_f32_32x32x16_bf16 v[34:49], v[162:165], v[186:189], v[34:49]
	global_load_lds_dwordx4 v[72:73], off
	s_add_u32 m0, s32, 0xa000
	v_mfma_f32_32x32x16_bf16 v[18:33], v[166:169], v[182:185], v[18:33]
	global_load_lds_dwordx4 v[76:77], off
	s_add_u32 m0, s32, 0xb000
	v_mfma_f32_32x32x16_bf16 v[2:17], v[166:169], v[186:189], v[2:17]
	global_load_lds_dwordx4 v[80:81], off
	s_waitcnt vmcnt(8)
	s_barrier
	ds_read_b128 v[162:165], v91 offset:16384
	ds_read_b128 v[166:169], v92 offset:49152
	ds_read_b128 v[182:185], v91 offset:20480
	ds_read_b128 v[186:189], v92 offset:53248
	ds_read_b128 v[190:193], v93 offset:16384
	ds_read_b128 v[194:197], v90 offset:49152
	ds_read_b128 v[198:201], v93 offset:20480
	ds_read_b128 v[202:205], v90 offset:53248
	s_waitcnt lgkmcnt(6)
	v_mfma_f32_32x32x16_bf16 v[50:65], v[162:165], v[166:169], v[50:65]
	s_waitcnt lgkmcnt(4)
	v_mfma_f32_32x32x16_bf16 v[34:49], v[162:165], v[186:189], v[34:49]
	v_mfma_f32_32x32x16_bf16 v[18:33], v[182:185], v[166:169], v[18:33]
	v_mfma_f32_32x32x16_bf16 v[2:17], v[182:185], v[186:189], v[2:17]
	ds_read_b128 v[162:165], v89 offset:16384
	ds_read_b128 v[166:169], v89 offset:20480
	ds_read_b128 v[182:185], v88 offset:49152
	ds_read_b128 v[186:189], v88 offset:53248
	s_waitcnt lgkmcnt(6)
	v_mfma_f32_32x32x16_bf16 v[50:65], v[190:193], v[194:197], v[50:65]
	s_waitcnt lgkmcnt(4)
	v_mfma_f32_32x32x16_bf16 v[34:49], v[190:193], v[202:205], v[34:49]
	v_mfma_f32_32x32x16_bf16 v[18:33], v[198:201], v[194:197], v[18:33]
	v_mfma_f32_32x32x16_bf16 v[2:17], v[198:201], v[202:205], v[2:17]
	ds_read_b128 v[190:193], v87 offset:16384
	ds_read_b128 v[194:197], v87 offset:20480
	ds_read_b128 v[198:201], v86 offset:49152
	ds_read_b128 v[202:205], v86 offset:53248
	v_lshl_add_u64 v[66:67], v[66:67], 0, s[98:99]
	v_lshl_add_u64 v[70:71], v[70:71], 0, s[98:99]
	v_lshl_add_u64 v[74:75], v[74:75], 0, s[98:99]
	v_lshl_add_u64 v[78:79], v[78:79], 0, s[98:99]
	v_lshl_add_u64 v[68:69], v[68:69], 0, s[98:99]
	v_lshl_add_u64 v[72:73], v[72:73], 0, s[98:99]
	v_lshl_add_u64 v[76:77], v[76:77], 0, s[98:99]
	v_lshl_add_u64 v[80:81], v[80:81], 0, s[98:99]
	s_waitcnt lgkmcnt(0)
	s_barrier
	s_add_u32 m0, s32, 0x4000
	v_mfma_f32_32x32x16_bf16 v[50:65], v[162:165], v[182:185], v[50:65]
	global_load_lds_dwordx4 v[66:67], off sc1
	s_add_u32 m0, s32, 0x5000
	v_mfma_f32_32x32x16_bf16 v[34:49], v[162:165], v[186:189], v[34:49]
	global_load_lds_dwordx4 v[70:71], off sc1
	s_add_u32 m0, s32, 0x6000
	v_mfma_f32_32x32x16_bf16 v[18:33], v[166:169], v[182:185], v[18:33]
	global_load_lds_dwordx4 v[74:75], off sc1
	s_add_u32 m0, s32, 0x7000
	v_mfma_f32_32x32x16_bf16 v[2:17], v[166:169], v[186:189], v[2:17]
	global_load_lds_dwordx4 v[78:79], off sc1
	s_add_u32 m0, s32, 0xc000
	v_mfma_f32_32x32x16_bf16 v[50:65], v[190:193], v[198:201], v[50:65]
	global_load_lds_dwordx4 v[68:69], off
	s_add_u32 m0, s32, 0xd000
	v_mfma_f32_32x32x16_bf16 v[34:49], v[190:193], v[202:205], v[34:49]
	global_load_lds_dwordx4 v[72:73], off
	s_add_u32 m0, s32, 0xe000
	v_mfma_f32_32x32x16_bf16 v[18:33], v[194:197], v[198:201], v[18:33]
	global_load_lds_dwordx4 v[76:77], off
	s_add_u32 m0, s32, 0xf000
	v_mfma_f32_32x32x16_bf16 v[2:17], v[194:197], v[202:205], v[2:17]
	global_load_lds_dwordx4 v[80:81], off
	s_waitcnt vmcnt(8)
	s_barrier
	ds_read_b128 v[162:165], v91
	ds_read_b128 v[166:169], v92 offset:32768
	ds_read_b128 v[182:185], v91 offset:4096
	ds_read_b128 v[186:189], v92 offset:36864
	ds_read_b128 v[190:193], v93
	ds_read_b128 v[194:197], v90 offset:32768
	ds_read_b128 v[198:201], v93 offset:4096
	ds_read_b128 v[202:205], v90 offset:36864
	s_waitcnt lgkmcnt(6)
	v_mfma_f32_32x32x16_bf16 v[50:65], v[162:165], v[166:169], v[50:65]
	s_waitcnt lgkmcnt(4)
	v_mfma_f32_32x32x16_bf16 v[34:49], v[162:165], v[186:189], v[34:49]
	v_mfma_f32_32x32x16_bf16 v[18:33], v[182:185], v[166:169], v[18:33]
	v_mfma_f32_32x32x16_bf16 v[2:17], v[182:185], v[186:189], v[2:17]
	ds_read_b128 v[162:165], v89
	ds_read_b128 v[166:169], v89 offset:4096
	ds_read_b128 v[182:185], v88 offset:32768
	ds_read_b128 v[186:189], v88 offset:36864
	s_waitcnt lgkmcnt(6)
	v_mfma_f32_32x32x16_bf16 v[50:65], v[190:193], v[194:197], v[50:65]
	s_waitcnt lgkmcnt(4)
	v_mfma_f32_32x32x16_bf16 v[34:49], v[190:193], v[202:205], v[34:49]
	v_mfma_f32_32x32x16_bf16 v[18:33], v[198:201], v[194:197], v[18:33]
	v_mfma_f32_32x32x16_bf16 v[2:17], v[198:201], v[202:205], v[2:17]
	ds_read_b128 v[190:193], v87
	ds_read_b128 v[194:197], v87 offset:4096
	ds_read_b128 v[198:201], v86 offset:32768
	ds_read_b128 v[202:205], v86 offset:36864
	v_lshl_add_u64 v[66:67], v[66:67], 0, s[98:99]
	v_lshl_add_u64 v[70:71], v[70:71], 0, s[98:99]
	v_lshl_add_u64 v[74:75], v[74:75], 0, s[98:99]
	v_lshl_add_u64 v[78:79], v[78:79], 0, s[98:99]
	v_lshl_add_u64 v[68:69], v[68:69], 0, s[98:99]
	v_lshl_add_u64 v[72:73], v[72:73], 0, s[98:99]
	v_lshl_add_u64 v[76:77], v[76:77], 0, s[98:99]
	v_lshl_add_u64 v[80:81], v[80:81], 0, s[98:99]
	s_waitcnt lgkmcnt(0)
	s_barrier
	s_add_u32 m0, s32, 0x0
	v_mfma_f32_32x32x16_bf16 v[50:65], v[162:165], v[182:185], v[50:65]
	global_load_lds_dwordx4 v[66:67], off sc1
	s_add_u32 m0, s32, 0x1000
	v_mfma_f32_32x32x16_bf16 v[34:49], v[162:165], v[186:189], v[34:49]
	global_load_lds_dwordx4 v[70:71], off sc1
	s_add_u32 m0, s32, 0x2000
	v_mfma_f32_32x32x16_bf16 v[18:33], v[166:169], v[182:185], v[18:33]
	global_load_lds_dwordx4 v[74:75], off sc1
	s_add_u32 m0, s32, 0x3000
	v_mfma_f32_32x32x16_bf16 v[2:17], v[166:169], v[186:189], v[2:17]
	global_load_lds_dwordx4 v[78:79], off sc1
	s_add_u32 m0, s32, 0x8000
	v_mfma_f32_32x32x16_bf16 v[50:65], v[190:193], v[198:201], v[50:65]
	global_load_lds_dwordx4 v[68:69], off
	s_add_u32 m0, s32, 0x9000
	v_mfma_f32_32x32x16_bf16 v[34:49], v[190:193], v[202:205], v[34:49]
	global_load_lds_dwordx4 v[72:73], off
	s_add_u32 m0, s32, 0xa000
	v_mfma_f32_32x32x16_bf16 v[18:33], v[194:197], v[198:201], v[18:33]
	global_load_lds_dwordx4 v[76:77], off
	s_add_u32 m0, s32, 0xb000
	v_mfma_f32_32x32x16_bf16 v[2:17], v[194:197], v[202:205], v[2:17]
	global_load_lds_dwordx4 v[80:81], off
	s_waitcnt vmcnt(8)
	s_barrier
	ds_read_b128 v[162:165], v91 offset:16384
	ds_read_b128 v[166:169], v92 offset:49152
	ds_read_b128 v[182:185], v91 offset:20480
	ds_read_b128 v[186:189], v92 offset:53248
	ds_read_b128 v[190:193], v93 offset:16384
	ds_read_b128 v[194:197], v90 offset:49152
	ds_read_b128 v[198:201], v93 offset:20480
	ds_read_b128 v[202:205], v90 offset:53248
	s_waitcnt lgkmcnt(6)
	v_mfma_f32_32x32x16_bf16 v[50:65], v[162:165], v[166:169], v[50:65]
	s_waitcnt lgkmcnt(4)
	v_mfma_f32_32x32x16_bf16 v[34:49], v[162:165], v[186:189], v[34:49]
	v_mfma_f32_32x32x16_bf16 v[18:33], v[182:185], v[166:169], v[18:33]
	v_mfma_f32_32x32x16_bf16 v[2:17], v[182:185], v[186:189], v[2:17]
	ds_read_b128 v[162:165], v89 offset:16384
	ds_read_b128 v[166:169], v89 offset:20480
	ds_read_b128 v[182:185], v88 offset:49152
	ds_read_b128 v[186:189], v88 offset:53248
	s_waitcnt lgkmcnt(6)
	v_mfma_f32_32x32x16_bf16 v[50:65], v[190:193], v[194:197], v[50:65]
	s_waitcnt lgkmcnt(4)
	v_mfma_f32_32x32x16_bf16 v[34:49], v[190:193], v[202:205], v[34:49]
	v_mfma_f32_32x32x16_bf16 v[18:33], v[198:201], v[194:197], v[18:33]
	v_mfma_f32_32x32x16_bf16 v[2:17], v[198:201], v[202:205], v[2:17]
	ds_read_b128 v[190:193], v87 offset:16384
	ds_read_b128 v[194:197], v87 offset:20480
	ds_read_b128 v[198:201], v86 offset:49152
	ds_read_b128 v[202:205], v86 offset:53248
	v_lshl_add_u64 v[66:67], v[66:67], 0, s[98:99]
	v_lshl_add_u64 v[70:71], v[70:71], 0, s[98:99]
	v_lshl_add_u64 v[74:75], v[74:75], 0, s[98:99]
	v_lshl_add_u64 v[78:79], v[78:79], 0, s[98:99]
	v_lshl_add_u64 v[68:69], v[68:69], 0, s[98:99]
	v_lshl_add_u64 v[72:73], v[72:73], 0, s[98:99]
	v_lshl_add_u64 v[76:77], v[76:77], 0, s[98:99]
	v_lshl_add_u64 v[80:81], v[80:81], 0, s[98:99]
	s_waitcnt lgkmcnt(0)
	s_barrier
	s_add_u32 m0, s32, 0x4000
	v_mfma_f32_32x32x16_bf16 v[50:65], v[162:165], v[182:185], v[50:65]
	global_load_lds_dwordx4 v[66:67], off sc1
	s_add_u32 m0, s32, 0x5000
	v_mfma_f32_32x32x16_bf16 v[34:49], v[162:165], v[186:189], v[34:49]
	global_load_lds_dwordx4 v[70:71], off sc1
	s_add_u32 m0, s32, 0x6000
	v_mfma_f32_32x32x16_bf16 v[18:33], v[166:169], v[182:185], v[18:33]
	global_load_lds_dwordx4 v[74:75], off sc1
	s_add_u32 m0, s32, 0x7000
	v_mfma_f32_32x32x16_bf16 v[2:17], v[166:169], v[186:189], v[2:17]
	global_load_lds_dwordx4 v[78:79], off sc1
	s_add_u32 m0, s32, 0xc000
	v_mfma_f32_32x32x16_bf16 v[50:65], v[190:193], v[198:201], v[50:65]
	global_load_lds_dwordx4 v[68:69], off
	s_add_u32 m0, s32, 0xd000
	v_mfma_f32_32x32x16_bf16 v[34:49], v[190:193], v[202:205], v[34:49]
	global_load_lds_dwordx4 v[72:73], off
	s_add_u32 m0, s32, 0xe000
	v_mfma_f32_32x32x16_bf16 v[18:33], v[194:197], v[198:201], v[18:33]
	global_load_lds_dwordx4 v[76:77], off
	s_add_u32 m0, s32, 0xf000
	v_mfma_f32_32x32x16_bf16 v[2:17], v[194:197], v[202:205], v[2:17]
	global_load_lds_dwordx4 v[80:81], off
	s_waitcnt vmcnt(8)
	s_barrier
	ds_read_b128 v[162:165], v91
	ds_read_b128 v[166:169], v92 offset:32768
	ds_read_b128 v[182:185], v91 offset:4096
	ds_read_b128 v[186:189], v92 offset:36864
	ds_read_b128 v[190:193], v93
	ds_read_b128 v[194:197], v90 offset:32768
	ds_read_b128 v[198:201], v93 offset:4096
	ds_read_b128 v[202:205], v90 offset:36864
	s_waitcnt lgkmcnt(6)
	v_mfma_f32_32x32x16_bf16 v[50:65], v[162:165], v[166:169], v[50:65]
	s_waitcnt lgkmcnt(4)
	v_mfma_f32_32x32x16_bf16 v[34:49], v[162:165], v[186:189], v[34:49]
	v_mfma_f32_32x32x16_bf16 v[18:33], v[182:185], v[166:169], v[18:33]
	v_mfma_f32_32x32x16_bf16 v[2:17], v[182:185], v[186:189], v[2:17]
	ds_read_b128 v[162:165], v89
	ds_read_b128 v[166:169], v89 offset:4096
	ds_read_b128 v[182:185], v88 offset:32768
	ds_read_b128 v[186:189], v88 offset:36864
	s_waitcnt lgkmcnt(6)
	v_mfma_f32_32x32x16_bf16 v[50:65], v[190:193], v[194:197], v[50:65]
	s_waitcnt lgkmcnt(4)
	v_mfma_f32_32x32x16_bf16 v[34:49], v[190:193], v[202:205], v[34:49]
	v_mfma_f32_32x32x16_bf16 v[18:33], v[198:201], v[194:197], v[18:33]
	v_mfma_f32_32x32x16_bf16 v[2:17], v[198:201], v[202:205], v[2:17]
	ds_read_b128 v[190:193], v87
	ds_read_b128 v[194:197], v87 offset:4096
	ds_read_b128 v[198:201], v86 offset:32768
	ds_read_b128 v[202:205], v86 offset:36864
	v_lshl_add_u64 v[66:67], v[66:67], 0, s[98:99]
	v_lshl_add_u64 v[70:71], v[70:71], 0, s[98:99]
	v_lshl_add_u64 v[74:75], v[74:75], 0, s[98:99]
	v_lshl_add_u64 v[78:79], v[78:79], 0, s[98:99]
	v_lshl_add_u64 v[68:69], v[68:69], 0, s[98:99]
	v_lshl_add_u64 v[72:73], v[72:73], 0, s[98:99]
	v_lshl_add_u64 v[76:77], v[76:77], 0, s[98:99]
	v_lshl_add_u64 v[80:81], v[80:81], 0, s[98:99]
	s_waitcnt lgkmcnt(0)
	s_barrier
	s_add_u32 m0, s32, 0x0
	v_mfma_f32_32x32x16_bf16 v[50:65], v[162:165], v[182:185], v[50:65]
	global_load_lds_dwordx4 v[66:67], off sc1
	s_add_u32 m0, s32, 0x1000
	v_mfma_f32_32x32x16_bf16 v[34:49], v[162:165], v[186:189], v[34:49]
	global_load_lds_dwordx4 v[70:71], off sc1
	s_add_u32 m0, s32, 0x2000
	v_mfma_f32_32x32x16_bf16 v[18:33], v[166:169], v[182:185], v[18:33]
	global_load_lds_dwordx4 v[74:75], off sc1
	s_add_u32 m0, s32, 0x3000
	v_mfma_f32_32x32x16_bf16 v[2:17], v[166:169], v[186:189], v[2:17]
	global_load_lds_dwordx4 v[78:79], off sc1
	s_add_u32 m0, s32, 0x8000
	v_mfma_f32_32x32x16_bf16 v[50:65], v[190:193], v[198:201], v[50:65]
	global_load_lds_dwordx4 v[68:69], off
	s_add_u32 m0, s32, 0x9000
	v_mfma_f32_32x32x16_bf16 v[34:49], v[190:193], v[202:205], v[34:49]
	global_load_lds_dwordx4 v[72:73], off
	s_add_u32 m0, s32, 0xa000
	v_mfma_f32_32x32x16_bf16 v[18:33], v[194:197], v[198:201], v[18:33]
	global_load_lds_dwordx4 v[76:77], off
	s_add_u32 m0, s32, 0xb000
	v_mfma_f32_32x32x16_bf16 v[2:17], v[194:197], v[202:205], v[2:17]
	global_load_lds_dwordx4 v[80:81], off
	s_waitcnt vmcnt(8)
	s_barrier
	ds_read_b128 v[162:165], v91 offset:16384
	ds_read_b128 v[166:169], v92 offset:49152
	ds_read_b128 v[182:185], v91 offset:20480
	ds_read_b128 v[186:189], v92 offset:53248
	ds_read_b128 v[190:193], v93 offset:16384
	ds_read_b128 v[194:197], v90 offset:49152
	ds_read_b128 v[198:201], v93 offset:20480
	ds_read_b128 v[202:205], v90 offset:53248
	s_waitcnt lgkmcnt(6)
	v_mfma_f32_32x32x16_bf16 v[50:65], v[162:165], v[166:169], v[50:65]
	s_waitcnt lgkmcnt(4)
	v_mfma_f32_32x32x16_bf16 v[34:49], v[162:165], v[186:189], v[34:49]
	v_mfma_f32_32x32x16_bf16 v[18:33], v[182:185], v[166:169], v[18:33]
	v_mfma_f32_32x32x16_bf16 v[2:17], v[182:185], v[186:189], v[2:17]
	ds_read_b128 v[162:165], v89 offset:16384
	ds_read_b128 v[166:169], v89 offset:20480
	ds_read_b128 v[182:185], v88 offset:49152
	ds_read_b128 v[186:189], v88 offset:53248
	s_waitcnt lgkmcnt(6)
	v_mfma_f32_32x32x16_bf16 v[50:65], v[190:193], v[194:197], v[50:65]
	s_waitcnt lgkmcnt(4)
	v_mfma_f32_32x32x16_bf16 v[34:49], v[190:193], v[202:205], v[34:49]
	v_mfma_f32_32x32x16_bf16 v[18:33], v[198:201], v[194:197], v[18:33]
	v_mfma_f32_32x32x16_bf16 v[2:17], v[198:201], v[202:205], v[2:17]
	ds_read_b128 v[190:193], v87 offset:16384
	ds_read_b128 v[194:197], v87 offset:20480
	ds_read_b128 v[198:201], v86 offset:49152
	ds_read_b128 v[202:205], v86 offset:53248
	v_lshl_add_u64 v[66:67], v[66:67], 0, s[98:99]
	v_lshl_add_u64 v[70:71], v[70:71], 0, s[98:99]
	v_lshl_add_u64 v[74:75], v[74:75], 0, s[98:99]
	v_lshl_add_u64 v[78:79], v[78:79], 0, s[98:99]
	v_lshl_add_u64 v[68:69], v[68:69], 0, s[98:99]
	v_lshl_add_u64 v[72:73], v[72:73], 0, s[98:99]
	v_lshl_add_u64 v[76:77], v[76:77], 0, s[98:99]
	v_lshl_add_u64 v[80:81], v[80:81], 0, s[98:99]
	s_waitcnt lgkmcnt(0)
	s_barrier
	s_add_u32 m0, s32, 0x4000
	v_mfma_f32_32x32x16_bf16 v[50:65], v[162:165], v[182:185], v[50:65]
	global_load_lds_dwordx4 v[66:67], off sc1
	s_add_u32 m0, s32, 0x5000
	v_mfma_f32_32x32x16_bf16 v[34:49], v[162:165], v[186:189], v[34:49]
	global_load_lds_dwordx4 v[70:71], off sc1
	s_add_u32 m0, s32, 0x6000
	v_mfma_f32_32x32x16_bf16 v[18:33], v[166:169], v[182:185], v[18:33]
	global_load_lds_dwordx4 v[74:75], off sc1
	s_add_u32 m0, s32, 0x7000
	v_mfma_f32_32x32x16_bf16 v[2:17], v[166:169], v[186:189], v[2:17]
	global_load_lds_dwordx4 v[78:79], off sc1
	s_add_u32 m0, s32, 0xc000
	v_mfma_f32_32x32x16_bf16 v[50:65], v[190:193], v[198:201], v[50:65]
	global_load_lds_dwordx4 v[68:69], off
	s_add_u32 m0, s32, 0xd000
	v_mfma_f32_32x32x16_bf16 v[34:49], v[190:193], v[202:205], v[34:49]
	global_load_lds_dwordx4 v[72:73], off
	s_add_u32 m0, s32, 0xe000
	v_mfma_f32_32x32x16_bf16 v[18:33], v[194:197], v[198:201], v[18:33]
	global_load_lds_dwordx4 v[76:77], off
	s_add_u32 m0, s32, 0xf000
	v_mfma_f32_32x32x16_bf16 v[2:17], v[194:197], v[202:205], v[2:17]
	global_load_lds_dwordx4 v[80:81], off
	s_waitcnt vmcnt(8)
	s_barrier
	ds_read_b128 v[162:165], v91
	ds_read_b128 v[166:169], v92 offset:32768
	ds_read_b128 v[182:185], v91 offset:4096
	ds_read_b128 v[186:189], v92 offset:36864
	ds_read_b128 v[190:193], v93
	ds_read_b128 v[194:197], v90 offset:32768
	ds_read_b128 v[198:201], v93 offset:4096
	ds_read_b128 v[202:205], v90 offset:36864
	s_waitcnt lgkmcnt(6)
	v_mfma_f32_32x32x16_bf16 v[50:65], v[162:165], v[166:169], v[50:65]
	s_waitcnt lgkmcnt(4)
	v_mfma_f32_32x32x16_bf16 v[34:49], v[162:165], v[186:189], v[34:49]
	v_mfma_f32_32x32x16_bf16 v[18:33], v[182:185], v[166:169], v[18:33]
	v_mfma_f32_32x32x16_bf16 v[2:17], v[182:185], v[186:189], v[2:17]
	ds_read_b128 v[162:165], v89
	ds_read_b128 v[166:169], v89 offset:4096
	ds_read_b128 v[182:185], v88 offset:32768
	ds_read_b128 v[186:189], v88 offset:36864
	s_waitcnt lgkmcnt(6)
	v_mfma_f32_32x32x16_bf16 v[50:65], v[190:193], v[194:197], v[50:65]
	s_waitcnt lgkmcnt(4)
	v_mfma_f32_32x32x16_bf16 v[34:49], v[190:193], v[202:205], v[34:49]
	v_mfma_f32_32x32x16_bf16 v[18:33], v[198:201], v[194:197], v[18:33]
	v_mfma_f32_32x32x16_bf16 v[2:17], v[198:201], v[202:205], v[2:17]
	ds_read_b128 v[190:193], v87
	ds_read_b128 v[194:197], v87 offset:4096
	ds_read_b128 v[198:201], v86 offset:32768
	ds_read_b128 v[202:205], v86 offset:36864
	v_lshl_add_u64 v[66:67], v[66:67], 0, s[98:99]
	v_lshl_add_u64 v[70:71], v[70:71], 0, s[98:99]
	v_lshl_add_u64 v[74:75], v[74:75], 0, s[98:99]
	v_lshl_add_u64 v[78:79], v[78:79], 0, s[98:99]
	v_lshl_add_u64 v[68:69], v[68:69], 0, s[98:99]
	v_lshl_add_u64 v[72:73], v[72:73], 0, s[98:99]
	v_lshl_add_u64 v[76:77], v[76:77], 0, s[98:99]
	v_lshl_add_u64 v[80:81], v[80:81], 0, s[98:99]
	s_waitcnt lgkmcnt(0)
	s_barrier
	s_add_u32 m0, s32, 0x0
	v_mfma_f32_32x32x16_bf16 v[50:65], v[162:165], v[182:185], v[50:65]
	global_load_lds_dwordx4 v[66:67], off sc1
	s_add_u32 m0, s32, 0x1000
	v_mfma_f32_32x32x16_bf16 v[34:49], v[162:165], v[186:189], v[34:49]
	global_load_lds_dwordx4 v[70:71], off sc1
	s_add_u32 m0, s32, 0x2000
	v_mfma_f32_32x32x16_bf16 v[18:33], v[166:169], v[182:185], v[18:33]
	global_load_lds_dwordx4 v[74:75], off sc1
	s_add_u32 m0, s32, 0x3000
	v_mfma_f32_32x32x16_bf16 v[2:17], v[166:169], v[186:189], v[2:17]
	global_load_lds_dwordx4 v[78:79], off sc1
	s_add_u32 m0, s32, 0x8000
	v_mfma_f32_32x32x16_bf16 v[50:65], v[190:193], v[198:201], v[50:65]
	global_load_lds_dwordx4 v[68:69], off
	s_add_u32 m0, s32, 0x9000
	v_mfma_f32_32x32x16_bf16 v[34:49], v[190:193], v[202:205], v[34:49]
	global_load_lds_dwordx4 v[72:73], off
	s_add_u32 m0, s32, 0xa000
	v_mfma_f32_32x32x16_bf16 v[18:33], v[194:197], v[198:201], v[18:33]
	global_load_lds_dwordx4 v[76:77], off
	s_add_u32 m0, s32, 0xb000
	v_mfma_f32_32x32x16_bf16 v[2:17], v[194:197], v[202:205], v[2:17]
	global_load_lds_dwordx4 v[80:81], off
	s_waitcnt vmcnt(8)
	s_barrier
	ds_read_b128 v[162:165], v91 offset:16384
	ds_read_b128 v[166:169], v92 offset:49152
	ds_read_b128 v[182:185], v91 offset:20480
	ds_read_b128 v[186:189], v92 offset:53248
	ds_read_b128 v[190:193], v93 offset:16384
	ds_read_b128 v[194:197], v90 offset:49152
	ds_read_b128 v[198:201], v93 offset:20480
	ds_read_b128 v[202:205], v90 offset:53248
	s_waitcnt lgkmcnt(6)
	v_mfma_f32_32x32x16_bf16 v[50:65], v[162:165], v[166:169], v[50:65]
	s_waitcnt lgkmcnt(4)
	v_mfma_f32_32x32x16_bf16 v[34:49], v[162:165], v[186:189], v[34:49]
	v_mfma_f32_32x32x16_bf16 v[18:33], v[182:185], v[166:169], v[18:33]
	v_mfma_f32_32x32x16_bf16 v[2:17], v[182:185], v[186:189], v[2:17]
	ds_read_b128 v[162:165], v89 offset:16384
	ds_read_b128 v[166:169], v89 offset:20480
	ds_read_b128 v[182:185], v88 offset:49152
	ds_read_b128 v[186:189], v88 offset:53248
	s_waitcnt lgkmcnt(6)
	v_mfma_f32_32x32x16_bf16 v[50:65], v[190:193], v[194:197], v[50:65]
	s_waitcnt lgkmcnt(4)
	v_mfma_f32_32x32x16_bf16 v[34:49], v[190:193], v[202:205], v[34:49]
	v_mfma_f32_32x32x16_bf16 v[18:33], v[198:201], v[194:197], v[18:33]
	v_mfma_f32_32x32x16_bf16 v[2:17], v[198:201], v[202:205], v[2:17]
	ds_read_b128 v[190:193], v87 offset:16384
	ds_read_b128 v[194:197], v87 offset:20480
	ds_read_b128 v[198:201], v86 offset:49152
	ds_read_b128 v[202:205], v86 offset:53248
	v_lshl_add_u64 v[66:67], v[66:67], 0, s[98:99]
	v_lshl_add_u64 v[70:71], v[70:71], 0, s[98:99]
	v_lshl_add_u64 v[74:75], v[74:75], 0, s[98:99]
	v_lshl_add_u64 v[78:79], v[78:79], 0, s[98:99]
	v_lshl_add_u64 v[68:69], v[68:69], 0, s[98:99]
	v_lshl_add_u64 v[72:73], v[72:73], 0, s[98:99]
	v_lshl_add_u64 v[76:77], v[76:77], 0, s[98:99]
	v_lshl_add_u64 v[80:81], v[80:81], 0, s[98:99]
	s_waitcnt lgkmcnt(0)
	s_barrier
	s_add_u32 m0, s32, 0x4000
	v_mfma_f32_32x32x16_bf16 v[50:65], v[162:165], v[182:185], v[50:65]
	global_load_lds_dwordx4 v[66:67], off sc1
	s_add_u32 m0, s32, 0x5000
	v_mfma_f32_32x32x16_bf16 v[34:49], v[162:165], v[186:189], v[34:49]
	global_load_lds_dwordx4 v[70:71], off sc1
	s_add_u32 m0, s32, 0x6000
	v_mfma_f32_32x32x16_bf16 v[18:33], v[166:169], v[182:185], v[18:33]
	global_load_lds_dwordx4 v[74:75], off sc1
	s_add_u32 m0, s32, 0x7000
	v_mfma_f32_32x32x16_bf16 v[2:17], v[166:169], v[186:189], v[2:17]
	global_load_lds_dwordx4 v[78:79], off sc1
	s_add_u32 m0, s32, 0xc000
	v_mfma_f32_32x32x16_bf16 v[50:65], v[190:193], v[198:201], v[50:65]
	global_load_lds_dwordx4 v[68:69], off
	s_add_u32 m0, s32, 0xd000
	v_mfma_f32_32x32x16_bf16 v[34:49], v[190:193], v[202:205], v[34:49]
	global_load_lds_dwordx4 v[72:73], off
	s_add_u32 m0, s32, 0xe000
	v_mfma_f32_32x32x16_bf16 v[18:33], v[194:197], v[198:201], v[18:33]
	global_load_lds_dwordx4 v[76:77], off
	s_add_u32 m0, s32, 0xf000
	v_mfma_f32_32x32x16_bf16 v[2:17], v[194:197], v[202:205], v[2:17]
	global_load_lds_dwordx4 v[80:81], off
	s_waitcnt vmcnt(8)
	s_barrier
	ds_read_b128 v[162:165], v91
	ds_read_b128 v[166:169], v92 offset:32768
	ds_read_b128 v[182:185], v91 offset:4096
	ds_read_b128 v[186:189], v92 offset:36864
	ds_read_b128 v[190:193], v93
	ds_read_b128 v[194:197], v90 offset:32768
	ds_read_b128 v[198:201], v93 offset:4096
	ds_read_b128 v[202:205], v90 offset:36864
	s_waitcnt lgkmcnt(6)
	v_mfma_f32_32x32x16_bf16 v[50:65], v[162:165], v[166:169], v[50:65]
	s_waitcnt lgkmcnt(4)
	v_mfma_f32_32x32x16_bf16 v[34:49], v[162:165], v[186:189], v[34:49]
	v_mfma_f32_32x32x16_bf16 v[18:33], v[182:185], v[166:169], v[18:33]
	v_mfma_f32_32x32x16_bf16 v[2:17], v[182:185], v[186:189], v[2:17]
	ds_read_b128 v[162:165], v89
	ds_read_b128 v[166:169], v89 offset:4096
	ds_read_b128 v[182:185], v88 offset:32768
	ds_read_b128 v[186:189], v88 offset:36864
	s_waitcnt lgkmcnt(6)
	v_mfma_f32_32x32x16_bf16 v[50:65], v[190:193], v[194:197], v[50:65]
	s_waitcnt lgkmcnt(4)
	v_mfma_f32_32x32x16_bf16 v[34:49], v[190:193], v[202:205], v[34:49]
	v_mfma_f32_32x32x16_bf16 v[18:33], v[198:201], v[194:197], v[18:33]
	v_mfma_f32_32x32x16_bf16 v[2:17], v[198:201], v[202:205], v[2:17]
	ds_read_b128 v[190:193], v87
	ds_read_b128 v[194:197], v87 offset:4096
	ds_read_b128 v[198:201], v86 offset:32768
	ds_read_b128 v[202:205], v86 offset:36864
	v_lshl_add_u64 v[66:67], v[66:67], 0, s[98:99]
	v_lshl_add_u64 v[70:71], v[70:71], 0, s[98:99]
	v_lshl_add_u64 v[74:75], v[74:75], 0, s[98:99]
	v_lshl_add_u64 v[78:79], v[78:79], 0, s[98:99]
	v_lshl_add_u64 v[68:69], v[68:69], 0, s[98:99]
	v_lshl_add_u64 v[72:73], v[72:73], 0, s[98:99]
	v_lshl_add_u64 v[76:77], v[76:77], 0, s[98:99]
	v_lshl_add_u64 v[80:81], v[80:81], 0, s[98:99]
	s_waitcnt lgkmcnt(0)
	s_barrier
	s_add_u32 m0, s32, 0x0
	v_mfma_f32_32x32x16_bf16 v[50:65], v[162:165], v[182:185], v[50:65]
	global_load_lds_dwordx4 v[66:67], off sc1
	s_add_u32 m0, s32, 0x1000
	v_mfma_f32_32x32x16_bf16 v[34:49], v[162:165], v[186:189], v[34:49]
	global_load_lds_dwordx4 v[70:71], off sc1
	s_add_u32 m0, s32, 0x2000
	v_mfma_f32_32x32x16_bf16 v[18:33], v[166:169], v[182:185], v[18:33]
	global_load_lds_dwordx4 v[74:75], off sc1
	s_add_u32 m0, s32, 0x3000
	v_mfma_f32_32x32x16_bf16 v[2:17], v[166:169], v[186:189], v[2:17]
	global_load_lds_dwordx4 v[78:79], off sc1
	s_add_u32 m0, s32, 0x8000
	v_mfma_f32_32x32x16_bf16 v[50:65], v[190:193], v[198:201], v[50:65]
	global_load_lds_dwordx4 v[68:69], off
	s_add_u32 m0, s32, 0x9000
	v_mfma_f32_32x32x16_bf16 v[34:49], v[190:193], v[202:205], v[34:49]
	global_load_lds_dwordx4 v[72:73], off
	s_add_u32 m0, s32, 0xa000
	v_mfma_f32_32x32x16_bf16 v[18:33], v[194:197], v[198:201], v[18:33]
	global_load_lds_dwordx4 v[76:77], off
	s_add_u32 m0, s32, 0xb000
	v_mfma_f32_32x32x16_bf16 v[2:17], v[194:197], v[202:205], v[2:17]
	global_load_lds_dwordx4 v[80:81], off
	s_waitcnt vmcnt(8)
	s_barrier
	ds_read_b128 v[162:165], v91 offset:16384
	ds_read_b128 v[166:169], v92 offset:49152
	ds_read_b128 v[182:185], v91 offset:20480
	ds_read_b128 v[186:189], v92 offset:53248
	ds_read_b128 v[190:193], v93 offset:16384
	ds_read_b128 v[194:197], v90 offset:49152
	ds_read_b128 v[198:201], v93 offset:20480
	ds_read_b128 v[202:205], v90 offset:53248
	s_waitcnt lgkmcnt(6)
	v_mfma_f32_32x32x16_bf16 v[50:65], v[162:165], v[166:169], v[50:65]
	s_waitcnt lgkmcnt(4)
	v_mfma_f32_32x32x16_bf16 v[34:49], v[162:165], v[186:189], v[34:49]
	v_mfma_f32_32x32x16_bf16 v[18:33], v[182:185], v[166:169], v[18:33]
	v_mfma_f32_32x32x16_bf16 v[2:17], v[182:185], v[186:189], v[2:17]
	ds_read_b128 v[162:165], v89 offset:16384
	ds_read_b128 v[166:169], v89 offset:20480
	ds_read_b128 v[182:185], v88 offset:49152
	ds_read_b128 v[186:189], v88 offset:53248
	s_waitcnt lgkmcnt(6)
	v_mfma_f32_32x32x16_bf16 v[50:65], v[190:193], v[194:197], v[50:65]
	s_waitcnt lgkmcnt(4)
	v_mfma_f32_32x32x16_bf16 v[34:49], v[190:193], v[202:205], v[34:49]
	v_mfma_f32_32x32x16_bf16 v[18:33], v[198:201], v[194:197], v[18:33]
	v_mfma_f32_32x32x16_bf16 v[2:17], v[198:201], v[202:205], v[2:17]
	ds_read_b128 v[190:193], v87 offset:16384
	ds_read_b128 v[194:197], v87 offset:20480
	ds_read_b128 v[198:201], v86 offset:49152
	ds_read_b128 v[202:205], v86 offset:53248
	v_lshl_add_u64 v[66:67], v[66:67], 0, s[98:99]
	v_lshl_add_u64 v[70:71], v[70:71], 0, s[98:99]
	v_lshl_add_u64 v[74:75], v[74:75], 0, s[98:99]
	v_lshl_add_u64 v[78:79], v[78:79], 0, s[98:99]
	v_lshl_add_u64 v[68:69], v[68:69], 0, s[98:99]
	v_lshl_add_u64 v[72:73], v[72:73], 0, s[98:99]
	v_lshl_add_u64 v[76:77], v[76:77], 0, s[98:99]
	v_lshl_add_u64 v[80:81], v[80:81], 0, s[98:99]
	s_waitcnt lgkmcnt(0)
	s_barrier
	s_add_u32 m0, s32, 0x4000
	v_mfma_f32_32x32x16_bf16 v[50:65], v[162:165], v[182:185], v[50:65]
	global_load_lds_dwordx4 v[66:67], off sc1
	s_add_u32 m0, s32, 0x5000
	v_mfma_f32_32x32x16_bf16 v[34:49], v[162:165], v[186:189], v[34:49]
	global_load_lds_dwordx4 v[70:71], off sc1
	s_add_u32 m0, s32, 0x6000
	v_mfma_f32_32x32x16_bf16 v[18:33], v[166:169], v[182:185], v[18:33]
	global_load_lds_dwordx4 v[74:75], off sc1
	s_add_u32 m0, s32, 0x7000
	v_mfma_f32_32x32x16_bf16 v[2:17], v[166:169], v[186:189], v[2:17]
	global_load_lds_dwordx4 v[78:79], off sc1
	s_add_u32 m0, s32, 0xc000
	v_mfma_f32_32x32x16_bf16 v[50:65], v[190:193], v[198:201], v[50:65]
	global_load_lds_dwordx4 v[68:69], off
	s_add_u32 m0, s32, 0xd000
	v_mfma_f32_32x32x16_bf16 v[34:49], v[190:193], v[202:205], v[34:49]
	global_load_lds_dwordx4 v[72:73], off
	s_add_u32 m0, s32, 0xe000
	v_mfma_f32_32x32x16_bf16 v[18:33], v[194:197], v[198:201], v[18:33]
	global_load_lds_dwordx4 v[76:77], off
	s_add_u32 m0, s32, 0xf000
	v_mfma_f32_32x32x16_bf16 v[2:17], v[194:197], v[202:205], v[2:17]
	global_load_lds_dwordx4 v[80:81], off
	s_waitcnt vmcnt(8)
	s_barrier
	ds_read_b128 v[162:165], v91
	ds_read_b128 v[166:169], v92 offset:32768
	ds_read_b128 v[182:185], v91 offset:4096
	ds_read_b128 v[186:189], v92 offset:36864
	ds_read_b128 v[190:193], v93
	ds_read_b128 v[194:197], v90 offset:32768
	ds_read_b128 v[198:201], v93 offset:4096
	ds_read_b128 v[202:205], v90 offset:36864
	s_waitcnt lgkmcnt(6)
	v_mfma_f32_32x32x16_bf16 v[50:65], v[162:165], v[166:169], v[50:65]
	s_waitcnt lgkmcnt(4)
	v_mfma_f32_32x32x16_bf16 v[34:49], v[162:165], v[186:189], v[34:49]
	v_mfma_f32_32x32x16_bf16 v[18:33], v[182:185], v[166:169], v[18:33]
	v_mfma_f32_32x32x16_bf16 v[2:17], v[182:185], v[186:189], v[2:17]
	ds_read_b128 v[162:165], v89
	ds_read_b128 v[166:169], v89 offset:4096
	ds_read_b128 v[182:185], v88 offset:32768
	ds_read_b128 v[186:189], v88 offset:36864
	s_waitcnt lgkmcnt(6)
	v_mfma_f32_32x32x16_bf16 v[50:65], v[190:193], v[194:197], v[50:65]
	s_waitcnt lgkmcnt(4)
	v_mfma_f32_32x32x16_bf16 v[34:49], v[190:193], v[202:205], v[34:49]
	v_mfma_f32_32x32x16_bf16 v[18:33], v[198:201], v[194:197], v[18:33]
	v_mfma_f32_32x32x16_bf16 v[2:17], v[198:201], v[202:205], v[2:17]
	ds_read_b128 v[190:193], v87
	ds_read_b128 v[194:197], v87 offset:4096
	ds_read_b128 v[198:201], v86 offset:32768
	ds_read_b128 v[202:205], v86 offset:36864
	v_lshl_add_u64 v[66:67], v[66:67], 0, s[98:99]
	v_lshl_add_u64 v[70:71], v[70:71], 0, s[98:99]
	v_lshl_add_u64 v[74:75], v[74:75], 0, s[98:99]
	v_lshl_add_u64 v[78:79], v[78:79], 0, s[98:99]
	v_lshl_add_u64 v[68:69], v[68:69], 0, s[98:99]
	v_lshl_add_u64 v[72:73], v[72:73], 0, s[98:99]
	v_lshl_add_u64 v[76:77], v[76:77], 0, s[98:99]
	v_lshl_add_u64 v[80:81], v[80:81], 0, s[98:99]
	s_waitcnt lgkmcnt(0)
	s_barrier
	s_add_u32 m0, s32, 0x0
	v_mfma_f32_32x32x16_bf16 v[50:65], v[162:165], v[182:185], v[50:65]
	global_load_lds_dwordx4 v[66:67], off sc1
	s_add_u32 m0, s32, 0x1000
	v_mfma_f32_32x32x16_bf16 v[34:49], v[162:165], v[186:189], v[34:49]
	global_load_lds_dwordx4 v[70:71], off sc1
	s_add_u32 m0, s32, 0x2000
	v_mfma_f32_32x32x16_bf16 v[18:33], v[166:169], v[182:185], v[18:33]
	global_load_lds_dwordx4 v[74:75], off sc1
	s_add_u32 m0, s32, 0x3000
	v_mfma_f32_32x32x16_bf16 v[2:17], v[166:169], v[186:189], v[2:17]
	global_load_lds_dwordx4 v[78:79], off sc1
	s_add_u32 m0, s32, 0x8000
	v_mfma_f32_32x32x16_bf16 v[50:65], v[190:193], v[198:201], v[50:65]
	global_load_lds_dwordx4 v[68:69], off
	s_add_u32 m0, s32, 0x9000
	v_mfma_f32_32x32x16_bf16 v[34:49], v[190:193], v[202:205], v[34:49]
	global_load_lds_dwordx4 v[72:73], off
	s_add_u32 m0, s32, 0xa000
	v_mfma_f32_32x32x16_bf16 v[18:33], v[194:197], v[198:201], v[18:33]
	global_load_lds_dwordx4 v[76:77], off
	s_add_u32 m0, s32, 0xb000
	v_mfma_f32_32x32x16_bf16 v[2:17], v[194:197], v[202:205], v[2:17]
	global_load_lds_dwordx4 v[80:81], off
	s_waitcnt vmcnt(8)
	s_barrier
	ds_read_b128 v[162:165], v91 offset:16384
	ds_read_b128 v[166:169], v92 offset:49152
	ds_read_b128 v[182:185], v91 offset:20480
	ds_read_b128 v[186:189], v92 offset:53248
	ds_read_b128 v[190:193], v93 offset:16384
	ds_read_b128 v[194:197], v90 offset:49152
	ds_read_b128 v[198:201], v93 offset:20480
	ds_read_b128 v[202:205], v90 offset:53248
	s_waitcnt lgkmcnt(6)
	v_mfma_f32_32x32x16_bf16 v[50:65], v[162:165], v[166:169], v[50:65]
	s_waitcnt lgkmcnt(4)
	v_mfma_f32_32x32x16_bf16 v[34:49], v[162:165], v[186:189], v[34:49]
	v_mfma_f32_32x32x16_bf16 v[18:33], v[182:185], v[166:169], v[18:33]
	v_mfma_f32_32x32x16_bf16 v[2:17], v[182:185], v[186:189], v[2:17]
	ds_read_b128 v[162:165], v89 offset:16384
	ds_read_b128 v[166:169], v89 offset:20480
	ds_read_b128 v[182:185], v88 offset:49152
	ds_read_b128 v[186:189], v88 offset:53248
	s_waitcnt lgkmcnt(6)
	v_mfma_f32_32x32x16_bf16 v[50:65], v[190:193], v[194:197], v[50:65]
	s_waitcnt lgkmcnt(4)
	v_mfma_f32_32x32x16_bf16 v[34:49], v[190:193], v[202:205], v[34:49]
	v_mfma_f32_32x32x16_bf16 v[18:33], v[198:201], v[194:197], v[18:33]
	v_mfma_f32_32x32x16_bf16 v[2:17], v[198:201], v[202:205], v[2:17]
	ds_read_b128 v[190:193], v87 offset:16384
	ds_read_b128 v[194:197], v87 offset:20480
	ds_read_b128 v[198:201], v86 offset:49152
	ds_read_b128 v[202:205], v86 offset:53248
	v_lshl_add_u64 v[66:67], v[66:67], 0, s[98:99]
	v_lshl_add_u64 v[70:71], v[70:71], 0, s[98:99]
	v_lshl_add_u64 v[74:75], v[74:75], 0, s[98:99]
	v_lshl_add_u64 v[78:79], v[78:79], 0, s[98:99]
	v_lshl_add_u64 v[68:69], v[68:69], 0, s[98:99]
	v_lshl_add_u64 v[72:73], v[72:73], 0, s[98:99]
	v_lshl_add_u64 v[76:77], v[76:77], 0, s[98:99]
	v_lshl_add_u64 v[80:81], v[80:81], 0, s[98:99]
	s_waitcnt lgkmcnt(0)
	s_barrier
	s_add_u32 m0, s32, 0x4000
	v_mfma_f32_32x32x16_bf16 v[50:65], v[162:165], v[182:185], v[50:65]
	global_load_lds_dwordx4 v[66:67], off sc1
	s_add_u32 m0, s32, 0x5000
	v_mfma_f32_32x32x16_bf16 v[34:49], v[162:165], v[186:189], v[34:49]
	global_load_lds_dwordx4 v[70:71], off sc1
	s_add_u32 m0, s32, 0x6000
	v_mfma_f32_32x32x16_bf16 v[18:33], v[166:169], v[182:185], v[18:33]
	global_load_lds_dwordx4 v[74:75], off sc1
	s_add_u32 m0, s32, 0x7000
	v_mfma_f32_32x32x16_bf16 v[2:17], v[166:169], v[186:189], v[2:17]
	global_load_lds_dwordx4 v[78:79], off sc1
	s_add_u32 m0, s32, 0xc000
	v_mfma_f32_32x32x16_bf16 v[50:65], v[190:193], v[198:201], v[50:65]
	global_load_lds_dwordx4 v[68:69], off
	s_add_u32 m0, s32, 0xd000
	v_mfma_f32_32x32x16_bf16 v[34:49], v[190:193], v[202:205], v[34:49]
	global_load_lds_dwordx4 v[72:73], off
	s_add_u32 m0, s32, 0xe000
	v_mfma_f32_32x32x16_bf16 v[18:33], v[194:197], v[198:201], v[18:33]
	global_load_lds_dwordx4 v[76:77], off
	s_add_u32 m0, s32, 0xf000
	v_mfma_f32_32x32x16_bf16 v[2:17], v[194:197], v[202:205], v[2:17]
	global_load_lds_dwordx4 v[80:81], off
	s_waitcnt vmcnt(8)
	s_barrier
	ds_read_b128 v[162:165], v91
	ds_read_b128 v[166:169], v92 offset:32768
	ds_read_b128 v[182:185], v91 offset:4096
	ds_read_b128 v[186:189], v92 offset:36864
	ds_read_b128 v[190:193], v93
	ds_read_b128 v[194:197], v90 offset:32768
	ds_read_b128 v[198:201], v93 offset:4096
	ds_read_b128 v[202:205], v90 offset:36864
	s_waitcnt lgkmcnt(6)
	v_mfma_f32_32x32x16_bf16 v[50:65], v[162:165], v[166:169], v[50:65]
	s_waitcnt lgkmcnt(4)
	v_mfma_f32_32x32x16_bf16 v[34:49], v[162:165], v[186:189], v[34:49]
	v_mfma_f32_32x32x16_bf16 v[18:33], v[182:185], v[166:169], v[18:33]
	v_mfma_f32_32x32x16_bf16 v[2:17], v[182:185], v[186:189], v[2:17]
	ds_read_b128 v[162:165], v89
	ds_read_b128 v[166:169], v89 offset:4096
	ds_read_b128 v[182:185], v88 offset:32768
	ds_read_b128 v[186:189], v88 offset:36864
	s_waitcnt lgkmcnt(6)
	v_mfma_f32_32x32x16_bf16 v[50:65], v[190:193], v[194:197], v[50:65]
	s_waitcnt lgkmcnt(4)
	v_mfma_f32_32x32x16_bf16 v[34:49], v[190:193], v[202:205], v[34:49]
	v_mfma_f32_32x32x16_bf16 v[18:33], v[198:201], v[194:197], v[18:33]
	v_mfma_f32_32x32x16_bf16 v[2:17], v[198:201], v[202:205], v[2:17]
	ds_read_b128 v[190:193], v87
	ds_read_b128 v[194:197], v87 offset:4096
	ds_read_b128 v[198:201], v86 offset:32768
	ds_read_b128 v[202:205], v86 offset:36864
	v_lshl_add_u64 v[66:67], v[66:67], 0, s[98:99]
	v_lshl_add_u64 v[70:71], v[70:71], 0, s[98:99]
	v_lshl_add_u64 v[74:75], v[74:75], 0, s[98:99]
	v_lshl_add_u64 v[78:79], v[78:79], 0, s[98:99]
	v_lshl_add_u64 v[68:69], v[68:69], 0, s[98:99]
	v_lshl_add_u64 v[72:73], v[72:73], 0, s[98:99]
	v_lshl_add_u64 v[76:77], v[76:77], 0, s[98:99]
	v_lshl_add_u64 v[80:81], v[80:81], 0, s[98:99]
	s_waitcnt lgkmcnt(0)
	s_barrier
	s_add_u32 m0, s32, 0x0
	s_nop 0
	global_load_lds_dwordx4 v[66:67], off sc1
	s_add_u32 m0, s32, 0x1000
	s_nop 0
	global_load_lds_dwordx4 v[70:71], off sc1
	s_add_u32 m0, s32, 0x2000
	s_nop 0
	global_load_lds_dwordx4 v[74:75], off sc1
	s_add_u32 m0, s32, 0x3000
	s_nop 0
	global_load_lds_dwordx4 v[78:79], off sc1
	s_add_u32 m0, s32, 0x8000
	s_nop 0
	global_load_lds_dwordx4 v[68:69], off
	s_add_u32 m0, s32, 0x9000
	s_nop 0
	global_load_lds_dwordx4 v[72:73], off
	s_add_u32 m0, s32, 0xa000
	s_nop 0
	global_load_lds_dwordx4 v[76:77], off
	s_add_u32 m0, s32, 0xb000
	s_nop 0
	global_load_lds_dwordx4 v[80:81], off
	s_waitcnt vmcnt(8)
	s_barrier
	s_nop 0
	s_nop 0
	s_nop 0
	s_nop 0
	s_nop 0
	s_nop 0
	s_nop 0
	v_mfma_f32_32x32x16_bf16 v[50:65], v[162:165], v[182:185], v[50:65]
	v_mfma_f32_32x32x16_bf16 v[34:49], v[162:165], v[186:189], v[34:49]
	v_mfma_f32_32x32x16_bf16 v[18:33], v[166:169], v[182:185], v[18:33]
	v_mfma_f32_32x32x16_bf16 v[2:17], v[166:169], v[186:189], v[2:17]
	ds_read_b128 v[110:113], v91 offset:16384
	ds_read_b128 v[114:117], v91 offset:20480
	ds_read_b128 v[118:121], v92 offset:49152
	ds_read_b128 v[122:125], v92 offset:53248
	ds_read_b128 v[162:165], v93 offset:16384
	ds_read_b128 v[166:169], v93 offset:20480
	ds_read_b128 v[182:185], v90 offset:49152
	ds_read_b128 v[186:189], v90 offset:53248
	v_mfma_f32_32x32x16_bf16 v[50:65], v[190:193], v[198:201], v[50:65]
	v_mfma_f32_32x32x16_bf16 v[34:49], v[190:193], v[202:205], v[34:49]
	v_mfma_f32_32x32x16_bf16 v[18:33], v[194:197], v[198:201], v[18:33]
	v_mfma_f32_32x32x16_bf16 v[2:17], v[194:197], v[202:205], v[2:17]
	s_waitcnt lgkmcnt(5)
	v_mfma_f32_32x32x16_bf16 v[50:65], v[110:113], v[118:121], v[50:65]
	s_waitcnt lgkmcnt(4)
	v_mfma_f32_32x32x16_bf16 v[34:49], v[110:113], v[122:125], v[34:49]
	v_mfma_f32_32x32x16_bf16 v[18:33], v[114:117], v[118:121], v[18:33]
	v_mfma_f32_32x32x16_bf16 v[2:17], v[114:117], v[122:125], v[2:17]
	ds_read_b128 v[110:113], v89 offset:16384
	ds_read_b128 v[114:117], v89 offset:20480
	ds_read_b128 v[118:121], v88 offset:49152
	ds_read_b128 v[122:125], v88 offset:53248
	s_waitcnt lgkmcnt(5)
	v_mfma_f32_32x32x16_bf16 v[50:65], v[162:165], v[182:185], v[50:65]
	s_waitcnt lgkmcnt(4)
	v_mfma_f32_32x32x16_bf16 v[34:49], v[162:165], v[186:189], v[34:49]
	v_mfma_f32_32x32x16_bf16 v[18:33], v[166:169], v[182:185], v[18:33]
	v_mfma_f32_32x32x16_bf16 v[2:17], v[166:169], v[186:189], v[2:17]
	ds_read_b128 v[162:165], v87 offset:16384
	ds_read_b128 v[166:169], v87 offset:20480
	ds_read_b128 v[182:185], v86 offset:49152
	ds_read_b128 v[186:189], v86 offset:53248
	s_waitcnt lgkmcnt(5)
	v_mfma_f32_32x32x16_bf16 v[50:65], v[110:113], v[118:121], v[50:65]
	v_lshl_add_u64 v[66:67], v[66:67], 0, s[98:99]
	v_lshl_add_u64 v[70:71], v[70:71], 0, s[98:99]
	v_lshl_add_u64 v[74:75], v[74:75], 0, s[98:99]
	v_lshl_add_u64 v[78:79], v[78:79], 0, s[98:99]
	v_lshl_add_u64 v[68:69], v[68:69], 0, s[98:99]
	v_lshl_add_u64 v[72:73], v[72:73], 0, s[98:99]
	v_lshl_add_u64 v[76:77], v[76:77], 0, s[98:99]
	v_lshl_add_u64 v[80:81], v[80:81], 0, s[98:99]
	s_waitcnt lgkmcnt(0)
	s_barrier
	s_add_u32 m0, s32, 0x4000
	s_nop 0
	global_load_lds_dwordx4 v[66:67], off sc1
	s_add_u32 m0, s32, 0x5000
	s_nop 0
	global_load_lds_dwordx4 v[70:71], off sc1
	s_add_u32 m0, s32, 0x6000
	s_nop 0
	global_load_lds_dwordx4 v[74:75], off sc1
	s_add_u32 m0, s32, 0x7000
	s_nop 0
	global_load_lds_dwordx4 v[78:79], off sc1
	s_add_u32 m0, s32, 0xc000
	s_nop 0
	global_load_lds_dwordx4 v[68:69], off
	s_add_u32 m0, s32, 0xd000
	s_nop 0
	global_load_lds_dwordx4 v[72:73], off
	s_add_u32 m0, s32, 0xe000
	s_nop 0
	global_load_lds_dwordx4 v[76:77], off
	s_add_u32 m0, s32, 0xf000
	s_nop 0
	global_load_lds_dwordx4 v[80:81], off
	s_waitcnt vmcnt(8)
	s_barrier
	v_mfma_f32_32x32x16_bf16 v[34:49], v[110:113], v[122:125], v[34:49]
	v_mfma_f32_32x32x16_bf16 v[18:33], v[114:117], v[118:121], v[18:33]
	v_mfma_f32_32x32x16_bf16 v[2:17], v[114:117], v[122:125], v[2:17]
	ds_read_b128 v[110:113], v91
	ds_read_b128 v[114:117], v91 offset:4096
	ds_read_b128 v[118:121], v92 offset:32768
	ds_read_b128 v[122:125], v92 offset:36864
	ds_read_b128 v[126:129], v93
	ds_read_b128 v[134:137], v93 offset:4096
	ds_read_b128 v[138:141], v90 offset:32768
	ds_read_b128 v[142:145], v90 offset:36864
	v_mfma_f32_32x32x16_bf16 v[50:65], v[162:165], v[182:185], v[50:65]
	v_mfma_f32_32x32x16_bf16 v[34:49], v[162:165], v[186:189], v[34:49]
	v_mfma_f32_32x32x16_bf16 v[18:33], v[166:169], v[182:185], v[18:33]
	v_mfma_f32_32x32x16_bf16 v[2:17], v[166:169], v[186:189], v[2:17]
	s_waitcnt lgkmcnt(5)
	v_mfma_f32_32x32x16_bf16 v[50:65], v[110:113], v[118:121], v[50:65]
	s_waitcnt lgkmcnt(4)
	v_mfma_f32_32x32x16_bf16 v[34:49], v[110:113], v[122:125], v[34:49]
	v_mfma_f32_32x32x16_bf16 v[18:33], v[114:117], v[118:121], v[18:33]
	v_mfma_f32_32x32x16_bf16 v[2:17], v[114:117], v[122:125], v[2:17]
	ds_read_b128 v[110:113], v89
	ds_read_b128 v[114:117], v89 offset:4096
	ds_read_b128 v[118:121], v88 offset:32768
	ds_read_b128 v[122:125], v88 offset:36864
	s_waitcnt lgkmcnt(5)
	v_mfma_f32_32x32x16_bf16 v[50:65], v[126:129], v[138:141], v[50:65]
	s_waitcnt lgkmcnt(4)
	v_mfma_f32_32x32x16_bf16 v[34:49], v[126:129], v[142:145], v[34:49]
	v_mfma_f32_32x32x16_bf16 v[18:33], v[134:137], v[138:141], v[18:33]
	v_mfma_f32_32x32x16_bf16 v[2:17], v[134:137], v[142:145], v[2:17]
	ds_read_b128 v[126:129], v87
	ds_read_b128 v[134:137], v87 offset:4096
	ds_read_b128 v[138:141], v86 offset:32768
	ds_read_b128 v[142:145], v86 offset:36864
	s_waitcnt lgkmcnt(5)
	v_mfma_f32_32x32x16_bf16 v[50:65], v[110:113], v[118:121], v[50:65]
	s_waitcnt vmcnt(0)
	s_waitcnt lgkmcnt(0)
	s_barrier
	ds_read_b128 v[66:69], v91 offset:16384
	ds_read_b128 v[70:73], v91 offset:20480
	ds_read_b128 v[74:77], v92 offset:49152
	ds_read_b128 v[78:81], v92 offset:53248
	ds_read_b128 v[94:97], v93 offset:16384
	ds_read_b128 v[98:101], v93 offset:20480
	ds_read_b128 v[102:105], v90 offset:49152
	ds_read_b128 v[90:93], v90 offset:53248
	v_mfma_f32_32x32x16_bf16 v[34:49], v[110:113], v[122:125], v[34:49]
	v_mfma_f32_32x32x16_bf16 v[18:33], v[114:117], v[118:121], v[18:33]
	v_mfma_f32_32x32x16_bf16 v[2:17], v[114:117], v[122:125], v[2:17]
	v_mfma_f32_32x32x16_bf16 v[50:65], v[126:129], v[138:141], v[50:65]
	v_mfma_f32_32x32x16_bf16 v[34:49], v[126:129], v[142:145], v[34:49]
	v_mfma_f32_32x32x16_bf16 v[18:33], v[134:137], v[138:141], v[18:33]
	v_mfma_f32_32x32x16_bf16 v[2:17], v[134:137], v[142:145], v[2:17]
	s_waitcnt lgkmcnt(5)
	v_mfma_f32_32x32x16_bf16 v[50:65], v[66:69], v[74:77], v[50:65]
	s_waitcnt lgkmcnt(4)
	v_mfma_f32_32x32x16_bf16 v[34:49], v[66:69], v[78:81], v[34:49]
	v_mfma_f32_32x32x16_bf16 v[18:33], v[70:73], v[74:77], v[18:33]
	v_mfma_f32_32x32x16_bf16 v[2:17], v[70:73], v[78:81], v[2:17]
	ds_read_b128 v[66:69], v89 offset:16384
	ds_read_b128 v[70:73], v89 offset:20480
	ds_read_b128 v[74:77], v88 offset:49152
	ds_read_b128 v[78:81], v88 offset:53248
	s_waitcnt lgkmcnt(5)
	v_mfma_f32_32x32x16_bf16 v[50:65], v[94:97], v[102:105], v[50:65]
	s_waitcnt lgkmcnt(4)
	v_mfma_f32_32x32x16_bf16 v[34:49], v[94:97], v[90:93], v[34:49]
	v_mfma_f32_32x32x16_bf16 v[18:33], v[98:101], v[102:105], v[18:33]
	v_mfma_f32_32x32x16_bf16 v[2:17], v[98:101], v[90:93], v[2:17]
	ds_read_b128 v[88:91], v87 offset:16384
	ds_read_b128 v[92:95], v87 offset:20480
	ds_read_b128 v[96:99], v86 offset:49152
	ds_read_b128 v[100:103], v86 offset:53248
	s_waitcnt lgkmcnt(5)
	v_mfma_f32_32x32x16_bf16 v[50:65], v[66:69], v[74:77], v[50:65]
	v_lshlrev_b32_e32 v0, 6, v85
	v_subrev_u32_e32 v0, s2, v0
	s_lshl_b32 s3, s34, 7
	s_movk_i32 s2, 0x9c0
	s_waitcnt lgkmcnt(0)
	s_barrier
	v_mfma_f32_32x32x16_bf16 v[34:49], v[66:69], v[78:81], v[34:49]
	v_add_u32_e32 v66, s7, v0
	v_lshl_add_u32 v68, v83, 6, s3
	v_add_u32_e32 v0, v66, v84
	v_cmp_lt_i32_e64 s[40:41], s63, v0
	v_cmp_gt_u32_e32 vcc, s2, v66
	v_lshl_add_u64 v[66:67], v[0:1], 1, s[48:49]
	v_mfma_f32_32x32x16_bf16 v[18:33], v[70:73], v[74:77], v[18:33]
	v_mfma_f32_32x32x16_bf16 v[2:17], v[70:73], v[78:81], v[2:17]
	v_lshl_or_b32 v70, v82, 2, v68
	v_mfma_f32_32x32x16_bf16 v[50:65], v[88:91], v[96:99], v[50:65]
	v_mfma_f32_32x32x16_bf16 v[34:49], v[88:91], v[100:103], v[34:49]
	v_mfma_f32_32x32x16_bf16 v[18:33], v[92:95], v[96:99], v[18:33]
	v_mfma_f32_32x32x16_bf16 v[2:17], v[92:95], v[100:103], v[2:17]
	s_and_saveexec_b64 s[2:3], s[40:41]
	s_xor_b64 s[2:3], exec, s[2:3]
	s_cbranch_execz .LBB0_236
	s_and_saveexec_b64 s[4:5], vcc
	s_cbranch_execz .LBB0_235
	s_nop 3
	v_cvt_pk_bf16_f32 v71, v50, s0
	v_mad_i64_i32 v[68:69], s[34:35], v70, s68, v[66:67]
	global_store_short v[68:69], v71, off offset:-1920

.LBB0_1186:
	s_ashr_i32 s5, s4, 31
	s_lshr_b32 s5, s5, 29
	s_add_i32 s5, s4, s5
	s_ashr_i32 s34, s5, 3
	s_ashr_i32 s35, s34, 31
	v_readlane_b32 s36, v210, 50
	v_mov_b32_e32 v36, v133
	s_lshl_b64 s[6:7], s[34:35], 18
	v_readlane_b32 s38, v210, 52
	v_readlane_b32 s39, v210, 53
	v_ashrrev_i32_e32 v34, 3, v36
	s_add_u32 s6, s38, s6
	v_ashrrev_i32_e32 v35, 31, v34
	s_addc_u32 s7, s39, s7
	v_lshlrev_b64 v[2:3], 11, v[34:35]
	v_lshlrev_b32_e32 v0, 4, v36
	v_lshl_add_u64 v[2:3], s[6:7], 0, v[2:3]
	v_and_b32_e32 v0, 0x70, v0
	s_lshl_b32 s5, s34, 10
	v_lshl_add_u64 v[66:67], v[2:3], 0, v[0:1]
	v_subrev_u32_e32 v2, s5, v34
	v_add_u32_e32 v2, s3, v2
	v_ashrrev_i32_e32 v3, 31, v2
	v_lshlrev_b64 v[2:3], 11, v[2:3]
	v_lshl_add_u64 v[2:3], s[0:1], 0, v[2:3]
	v_add_co_u32_e32 v70, vcc, s10, v66
	v_lshl_add_u64 v[68:69], v[2:3], 0, v[0:1]
	s_nop 0
	v_addc_co_u32_e32 v71, vcc, 0, v67, vcc
	v_add_co_u32_e32 v72, vcc, s10, v68
	v_addc_co_u32_e32 v73, vcc, 0, v69, vcc
	v_add_co_u32_e32 v74, vcc, s63, v66
	s_nop 0
	v_addc_co_u32_e32 v75, vcc, 0, v67, vcc
	v_add_co_u32_e32 v76, vcc, s63, v68
	s_nop 0
	v_addc_co_u32_e32 v77, vcc, 0, v69, vcc
	v_add_co_u32_e32 v78, vcc, s61, v66
	s_nop 0
	v_addc_co_u32_e32 v79, vcc, 0, v67, vcc
	v_add_co_u32_e32 v80, vcc, s61, v68
	v_lshlrev_b32_e32 v0, 7, v34
	s_nop 0
	v_addc_co_u32_e32 v81, vcc, 0, v69, vcc
	v_lshrrev_b32_e32 v216, 4, v133
	v_xor_b32_e32 v216, v216, v133
	v_and_b32_e32 v216, 7, v216
	v_lshlrev_b32_e32 v216, 4, v216
	v_mov_b32_e32 v217, 0x70
	v_lshrrev_b32_e32 v218, 6, v133
	v_lshlrev_b32_e32 v218, 10, v218
	s_nop 0
	v_readfirstlane_b32 s32, v218
	v_bfi_b32 v66, v217, v216, v66
	v_bfi_b32 v70, v217, v216, v70
	v_bfi_b32 v74, v217, v216, v74
	v_bfi_b32 v78, v217, v216, v78
	v_bfi_b32 v68, v217, v216, v68
	v_bfi_b32 v72, v217, v216, v72
	v_bfi_b32 v76, v217, v216, v76
	v_bfi_b32 v80, v217, v216, v80
	s_mov_b64 s[98:99], 0x80
	s_add_u32 m0, s32, 0x0
	s_nop 0
	global_load_lds_dwordx4 v[66:67], off sc1
	s_add_u32 m0, s32, 0x1000
	s_nop 0
	global_load_lds_dwordx4 v[70:71], off sc1
	s_add_u32 m0, s32, 0x2000
	s_nop 0
	global_load_lds_dwordx4 v[74:75], off sc1
	s_add_u32 m0, s32, 0x3000
	s_nop 0
	global_load_lds_dwordx4 v[78:79], off sc1
	s_add_u32 m0, s32, 0x8000
	s_nop 0
	global_load_lds_dwordx4 v[68:69], off
	s_add_u32 m0, s32, 0x9000
	s_nop 0
	global_load_lds_dwordx4 v[72:73], off
	s_add_u32 m0, s32, 0xa000
	s_nop 0
	global_load_lds_dwordx4 v[76:77], off
	s_add_u32 m0, s32, 0xb000
	s_nop 0
	global_load_lds_dwordx4 v[80:81], off
	v_lshl_add_u64 v[66:67], v[66:67], 0, s[98:99]
	v_lshl_add_u64 v[70:71], v[70:71], 0, s[98:99]
	v_lshl_add_u64 v[74:75], v[74:75], 0, s[98:99]
	v_lshl_add_u64 v[78:79], v[78:79], 0, s[98:99]
	v_lshl_add_u64 v[68:69], v[68:69], 0, s[98:99]
	v_lshl_add_u64 v[72:73], v[72:73], 0, s[98:99]
	v_lshl_add_u64 v[76:77], v[76:77], 0, s[98:99]
	v_lshl_add_u64 v[80:81], v[80:81], 0, s[98:99]
	s_add_u32 m0, s32, 0x4000
	s_nop 0
	global_load_lds_dwordx4 v[66:67], off sc1
	s_add_u32 m0, s32, 0x5000
	s_nop 0
	global_load_lds_dwordx4 v[70:71], off sc1
	s_add_u32 m0, s32, 0x6000
	s_nop 0
	global_load_lds_dwordx4 v[74:75], off sc1
	s_add_u32 m0, s32, 0x7000
	s_nop 0
	global_load_lds_dwordx4 v[78:79], off sc1
	s_add_u32 m0, s32, 0xc000
	s_nop 0
	global_load_lds_dwordx4 v[68:69], off
	s_add_u32 m0, s32, 0xd000
	s_nop 0
	global_load_lds_dwordx4 v[72:73], off
	s_add_u32 m0, s32, 0xe000
	s_nop 0
	global_load_lds_dwordx4 v[76:77], off
	s_add_u32 m0, s32, 0xf000
	s_nop 0
	global_load_lds_dwordx4 v[80:81], off
	v_lshrrev_b32_e32 v34, 1, v34
	v_xor_b32_e32 v34, v34, v36
	v_lshlrev_b32_e32 v34, 4, v34
	s_movk_i32 s6, 0x70
	v_and_or_b32 v0, v34, s6, v0
	s_waitcnt vmcnt(26)
	v_and_b32_e32 v82, 31, v36
	v_bfe_u32 v85, v36, 5, 1
	v_ashrrev_i32_e32 v84, 7, v36
	v_bfe_u32 v83, v36, 6, 1
	v_readlane_b32 s37, v210, 51
	v_readlane_b32 s40, v210, 54
	v_readlane_b32 s41, v210, 55
	v_readlane_b32 s42, v210, 56
	v_readlane_b32 s43, v210, 57
	v_readlane_b32 s44, v210, 58
	v_readlane_b32 s45, v210, 59
	v_readlane_b32 s46, v210, 60
	v_readlane_b32 s47, v210, 61
	v_readlane_b32 s48, v210, 62
	v_readlane_b32 s49, v210, 63
	v_readlane_b32 s50, v209, 0
	v_readlane_b32 s51, v209, 1
	v_lshl_add_u64 v[66:67], v[66:67], 0, s[98:99]
	v_lshl_add_u64 v[70:71], v[70:71], 0, s[98:99]
	v_lshl_add_u64 v[74:75], v[74:75], 0, s[98:99]
	v_lshl_add_u64 v[78:79], v[78:79], 0, s[98:99]
	v_lshl_add_u64 v[68:69], v[68:69], 0, s[98:99]
	v_lshl_add_u64 v[72:73], v[72:73], 0, s[98:99]
	v_lshl_add_u64 v[76:77], v[76:77], 0, s[98:99]
	v_lshl_add_u64 v[80:81], v[80:81], 0, s[98:99]
	s_waitcnt vmcnt(8)
	s_waitcnt lgkmcnt(0)
	s_barrier
	v_lshrrev_b32_e32 v4, 1, v36
	v_lshlrev_b32_e32 v2, 7, v82
	v_bitop3_b32 v4, v4, v85, 7 bitop3:0x6c
	v_lshl_or_b32 v3, v84, 13, v2
	v_bfe_u32 v5, v36, 1, 3
	v_lshlrev_b32_e32 v4, 4, v4
	v_lshl_or_b32 v2, v83, 13, v2
	v_or_b32_e32 v91, v3, v4
	v_or_b32_e32 v92, v2, v4
	v_bitop3_b32 v4, v85, v5, 2 bitop3:0x36
	v_lshlrev_b32_e32 v4, 4, v4
	v_or_b32_e32 v93, v3, v4
	v_or_b32_e32 v90, v2, v4
	v_bitop3_b32 v4, v85, v5, 4 bitop3:0x36
	v_lshlrev_b32_e32 v4, 4, v4
	v_or_b32_e32 v89, v3, v4
	v_or_b32_e32 v88, v2, v4
	v_bitop3_b32 v4, v85, v5, 6 bitop3:0x36
	v_lshlrev_b32_e32 v4, 4, v4
	v_or_b32_e32 v87, v3, v4
	v_or_b32_e32 v86, v2, v4
	ds_read_b128 v[2:5], v91
	ds_read_b128 v[6:9], v92 offset:32768
	ds_read_b128 v[10:13], v91 offset:4096
	ds_read_b128 v[14:17], v92 offset:36864
	ds_read_b128 v[162:165], v93
	ds_read_b128 v[166:169], v90 offset:32768
	ds_read_b128 v[182:185], v93 offset:4096
	ds_read_b128 v[186:189], v90 offset:36864
	s_waitcnt lgkmcnt(6)
	v_mfma_f32_32x32x16_bf16 v[50:65], v[2:5], v[6:9], 0
	s_waitcnt lgkmcnt(4)
	v_mfma_f32_32x32x16_bf16 v[18:33], v[2:5], v[14:17], 0
	v_mfma_f32_32x32x16_bf16 v[34:49], v[10:13], v[6:9], 0
	v_mfma_f32_32x32x16_bf16 v[2:17], v[10:13], v[14:17], 0
	ds_read_b128 v[190:193], v89
	ds_read_b128 v[194:197], v89 offset:4096
	ds_read_b128 v[198:201], v88 offset:32768
	ds_read_b128 v[202:205], v88 offset:36864
	s_waitcnt lgkmcnt(6)
	v_mfma_f32_32x32x16_bf16 v[50:65], v[162:165], v[166:169], v[50:65]
	s_waitcnt lgkmcnt(4)
	v_mfma_f32_32x32x16_bf16 v[18:33], v[162:165], v[186:189], v[18:33]
	v_mfma_f32_32x32x16_bf16 v[34:49], v[182:185], v[166:169], v[34:49]
	v_mfma_f32_32x32x16_bf16 v[2:17], v[182:185], v[186:189], v[2:17]
	ds_read_b128 v[162:165], v87
	ds_read_b128 v[166:169], v87 offset:4096
	ds_read_b128 v[182:185], v86 offset:32768
	ds_read_b128 v[186:189], v86 offset:36864
	s_waitcnt lgkmcnt(0)
	s_barrier
	s_add_u32 m0, s32, 0x0
	v_mfma_f32_32x32x16_bf16 v[50:65], v[190:193], v[198:201], v[50:65]
	global_load_lds_dwordx4 v[66:67], off sc1
	s_add_u32 m0, s32, 0x1000
	v_mfma_f32_32x32x16_bf16 v[18:33], v[190:193], v[202:205], v[18:33]
	global_load_lds_dwordx4 v[70:71], off sc1
	s_add_u32 m0, s32, 0x2000
	v_mfma_f32_32x32x16_bf16 v[34:49], v[194:197], v[198:201], v[34:49]
	global_load_lds_dwordx4 v[74:75], off sc1
	s_add_u32 m0, s32, 0x3000
	v_mfma_f32_32x32x16_bf16 v[2:17], v[194:197], v[202:205], v[2:17]
	global_load_lds_dwordx4 v[78:79], off sc1
	s_add_u32 m0, s32, 0x8000
	v_mfma_f32_32x32x16_bf16 v[50:65], v[162:165], v[182:185], v[50:65]
	global_load_lds_dwordx4 v[68:69], off
	s_add_u32 m0, s32, 0x9000
	v_mfma_f32_32x32x16_bf16 v[18:33], v[162:165], v[186:189], v[18:33]
	global_load_lds_dwordx4 v[72:73], off
	s_add_u32 m0, s32, 0xa000
	v_mfma_f32_32x32x16_bf16 v[34:49], v[166:169], v[182:185], v[34:49]
	global_load_lds_dwordx4 v[76:77], off
	s_add_u32 m0, s32, 0xb000
	v_mfma_f32_32x32x16_bf16 v[2:17], v[166:169], v[186:189], v[2:17]
	global_load_lds_dwordx4 v[80:81], off
	s_waitcnt vmcnt(8)
	s_barrier
	ds_read_b128 v[162:165], v91 offset:16384
	ds_read_b128 v[166:169], v92 offset:49152
	ds_read_b128 v[182:185], v91 offset:20480
	ds_read_b128 v[186:189], v92 offset:53248
	ds_read_b128 v[190:193], v93 offset:16384
	ds_read_b128 v[194:197], v90 offset:49152
	ds_read_b128 v[198:201], v93 offset:20480
	ds_read_b128 v[202:205], v90 offset:53248
	s_waitcnt lgkmcnt(6)
	v_mfma_f32_32x32x16_bf16 v[50:65], v[162:165], v[166:169], v[50:65]
	s_waitcnt lgkmcnt(4)
	v_mfma_f32_32x32x16_bf16 v[18:33], v[162:165], v[186:189], v[18:33]
	v_mfma_f32_32x32x16_bf16 v[34:49], v[182:185], v[166:169], v[34:49]
	v_mfma_f32_32x32x16_bf16 v[2:17], v[182:185], v[186:189], v[2:17]
	ds_read_b128 v[162:165], v89 offset:16384
	ds_read_b128 v[166:169], v89 offset:20480
	ds_read_b128 v[182:185], v88 offset:49152
	ds_read_b128 v[186:189], v88 offset:53248
	s_waitcnt lgkmcnt(6)
	v_mfma_f32_32x32x16_bf16 v[50:65], v[190:193], v[194:197], v[50:65]
	s_waitcnt lgkmcnt(4)
	v_mfma_f32_32x32x16_bf16 v[18:33], v[190:193], v[202:205], v[18:33]
	v_mfma_f32_32x32x16_bf16 v[34:49], v[198:201], v[194:197], v[34:49]
	v_mfma_f32_32x32x16_bf16 v[2:17], v[198:201], v[202:205], v[2:17]
	ds_read_b128 v[190:193], v87 offset:16384
	ds_read_b128 v[194:197], v87 offset:20480
	ds_read_b128 v[198:201], v86 offset:49152
	ds_read_b128 v[202:205], v86 offset:53248
	v_lshl_add_u64 v[66:67], v[66:67], 0, s[98:99]
	v_lshl_add_u64 v[70:71], v[70:71], 0, s[98:99]
	v_lshl_add_u64 v[74:75], v[74:75], 0, s[98:99]
	v_lshl_add_u64 v[78:79], v[78:79], 0, s[98:99]
	v_lshl_add_u64 v[68:69], v[68:69], 0, s[98:99]
	v_lshl_add_u64 v[72:73], v[72:73], 0, s[98:99]
	v_lshl_add_u64 v[76:77], v[76:77], 0, s[98:99]
	v_lshl_add_u64 v[80:81], v[80:81], 0, s[98:99]
	s_waitcnt lgkmcnt(0)
	s_barrier
	s_add_u32 m0, s32, 0x4000
	v_mfma_f32_32x32x16_bf16 v[50:65], v[162:165], v[182:185], v[50:65]
	global_load_lds_dwordx4 v[66:67], off sc1
	s_add_u32 m0, s32, 0x5000
	v_mfma_f32_32x32x16_bf16 v[18:33], v[162:165], v[186:189], v[18:33]
	global_load_lds_dwordx4 v[70:71], off sc1
	s_add_u32 m0, s32, 0x6000
	v_mfma_f32_32x32x16_bf16 v[34:49], v[166:169], v[182:185], v[34:49]
	global_load_lds_dwordx4 v[74:75], off sc1
	s_add_u32 m0, s32, 0x7000
	v_mfma_f32_32x32x16_bf16 v[2:17], v[166:169], v[186:189], v[2:17]
	global_load_lds_dwordx4 v[78:79], off sc1
	s_add_u32 m0, s32, 0xc000
	v_mfma_f32_32x32x16_bf16 v[50:65], v[190:193], v[198:201], v[50:65]
	global_load_lds_dwordx4 v[68:69], off
	s_add_u32 m0, s32, 0xd000
	v_mfma_f32_32x32x16_bf16 v[18:33], v[190:193], v[202:205], v[18:33]
	global_load_lds_dwordx4 v[72:73], off
	s_add_u32 m0, s32, 0xe000
	v_mfma_f32_32x32x16_bf16 v[34:49], v[194:197], v[198:201], v[34:49]
	global_load_lds_dwordx4 v[76:77], off
	s_add_u32 m0, s32, 0xf000
	v_mfma_f32_32x32x16_bf16 v[2:17], v[194:197], v[202:205], v[2:17]
	global_load_lds_dwordx4 v[80:81], off
	s_waitcnt vmcnt(8)
	s_barrier
	ds_read_b128 v[162:165], v91
	ds_read_b128 v[166:169], v92 offset:32768
	ds_read_b128 v[182:185], v91 offset:4096
	ds_read_b128 v[186:189], v92 offset:36864
	ds_read_b128 v[190:193], v93
	ds_read_b128 v[194:197], v90 offset:32768
	ds_read_b128 v[198:201], v93 offset:4096
	ds_read_b128 v[202:205], v90 offset:36864
	s_waitcnt lgkmcnt(6)
	v_mfma_f32_32x32x16_bf16 v[50:65], v[162:165], v[166:169], v[50:65]
	s_waitcnt lgkmcnt(4)
	v_mfma_f32_32x32x16_bf16 v[18:33], v[162:165], v[186:189], v[18:33]
	v_mfma_f32_32x32x16_bf16 v[34:49], v[182:185], v[166:169], v[34:49]
	v_mfma_f32_32x32x16_bf16 v[2:17], v[182:185], v[186:189], v[2:17]
	ds_read_b128 v[162:165], v89
	ds_read_b128 v[166:169], v89 offset:4096
	ds_read_b128 v[182:185], v88 offset:32768
	ds_read_b128 v[186:189], v88 offset:36864
	s_waitcnt lgkmcnt(6)
	v_mfma_f32_32x32x16_bf16 v[50:65], v[190:193], v[194:197], v[50:65]
	s_waitcnt lgkmcnt(4)
	v_mfma_f32_32x32x16_bf16 v[18:33], v[190:193], v[202:205], v[18:33]
	v_mfma_f32_32x32x16_bf16 v[34:49], v[198:201], v[194:197], v[34:49]
	v_mfma_f32_32x32x16_bf16 v[2:17], v[198:201], v[202:205], v[2:17]
	ds_read_b128 v[190:193], v87
	ds_read_b128 v[194:197], v87 offset:4096
	ds_read_b128 v[198:201], v86 offset:32768
	ds_read_b128 v[202:205], v86 offset:36864
	v_lshl_add_u64 v[66:67], v[66:67], 0, s[98:99]
	v_lshl_add_u64 v[70:71], v[70:71], 0, s[98:99]
	v_lshl_add_u64 v[74:75], v[74:75], 0, s[98:99]
	v_lshl_add_u64 v[78:79], v[78:79], 0, s[98:99]
	v_lshl_add_u64 v[68:69], v[68:69], 0, s[98:99]
	v_lshl_add_u64 v[72:73], v[72:73], 0, s[98:99]
	v_lshl_add_u64 v[76:77], v[76:77], 0, s[98:99]
	v_lshl_add_u64 v[80:81], v[80:81], 0, s[98:99]
	s_waitcnt lgkmcnt(0)
	s_barrier
	s_add_u32 m0, s32, 0x0
	v_mfma_f32_32x32x16_bf16 v[50:65], v[162:165], v[182:185], v[50:65]
	global_load_lds_dwordx4 v[66:67], off sc1
	s_add_u32 m0, s32, 0x1000
	v_mfma_f32_32x32x16_bf16 v[18:33], v[162:165], v[186:189], v[18:33]
	global_load_lds_dwordx4 v[70:71], off sc1
	s_add_u32 m0, s32, 0x2000
	v_mfma_f32_32x32x16_bf16 v[34:49], v[166:169], v[182:185], v[34:49]
	global_load_lds_dwordx4 v[74:75], off sc1
	s_add_u32 m0, s32, 0x3000
	v_mfma_f32_32x32x16_bf16 v[2:17], v[166:169], v[186:189], v[2:17]
	global_load_lds_dwordx4 v[78:79], off sc1
	s_add_u32 m0, s32, 0x8000
	v_mfma_f32_32x32x16_bf16 v[50:65], v[190:193], v[198:201], v[50:65]
	global_load_lds_dwordx4 v[68:69], off
	s_add_u32 m0, s32, 0x9000
	v_mfma_f32_32x32x16_bf16 v[18:33], v[190:193], v[202:205], v[18:33]
	global_load_lds_dwordx4 v[72:73], off
	s_add_u32 m0, s32, 0xa000
	v_mfma_f32_32x32x16_bf16 v[34:49], v[194:197], v[198:201], v[34:49]
	global_load_lds_dwordx4 v[76:77], off
	s_add_u32 m0, s32, 0xb000
	v_mfma_f32_32x32x16_bf16 v[2:17], v[194:197], v[202:205], v[2:17]
	global_load_lds_dwordx4 v[80:81], off
	s_waitcnt vmcnt(8)
	s_barrier
	ds_read_b128 v[162:165], v91 offset:16384
	ds_read_b128 v[166:169], v92 offset:49152
	ds_read_b128 v[182:185], v91 offset:20480
	ds_read_b128 v[186:189], v92 offset:53248
	ds_read_b128 v[190:193], v93 offset:16384
	ds_read_b128 v[194:197], v90 offset:49152
	ds_read_b128 v[198:201], v93 offset:20480
	ds_read_b128 v[202:205], v90 offset:53248
	s_waitcnt lgkmcnt(6)
	v_mfma_f32_32x32x16_bf16 v[50:65], v[162:165], v[166:169], v[50:65]
	s_waitcnt lgkmcnt(4)
	v_mfma_f32_32x32x16_bf16 v[18:33], v[162:165], v[186:189], v[18:33]
	v_mfma_f32_32x32x16_bf16 v[34:49], v[182:185], v[166:169], v[34:49]
	v_mfma_f32_32x32x16_bf16 v[2:17], v[182:185], v[186:189], v[2:17]
	ds_read_b128 v[162:165], v89 offset:16384
	ds_read_b128 v[166:169], v89 offset:20480
	ds_read_b128 v[182:185], v88 offset:49152
	ds_read_b128 v[186:189], v88 offset:53248
	s_waitcnt lgkmcnt(6)
	v_mfma_f32_32x32x16_bf16 v[50:65], v[190:193], v[194:197], v[50:65]
	s_waitcnt lgkmcnt(4)
	v_mfma_f32_32x32x16_bf16 v[18:33], v[190:193], v[202:205], v[18:33]
	v_mfma_f32_32x32x16_bf16 v[34:49], v[198:201], v[194:197], v[34:49]
	v_mfma_f32_32x32x16_bf16 v[2:17], v[198:201], v[202:205], v[2:17]
	ds_read_b128 v[190:193], v87 offset:16384
	ds_read_b128 v[194:197], v87 offset:20480
	ds_read_b128 v[198:201], v86 offset:49152
	ds_read_b128 v[202:205], v86 offset:53248
	v_lshl_add_u64 v[66:67], v[66:67], 0, s[98:99]
	v_lshl_add_u64 v[70:71], v[70:71], 0, s[98:99]
	v_lshl_add_u64 v[74:75], v[74:75], 0, s[98:99]
	v_lshl_add_u64 v[78:79], v[78:79], 0, s[98:99]
	v_lshl_add_u64 v[68:69], v[68:69], 0, s[98:99]
	v_lshl_add_u64 v[72:73], v[72:73], 0, s[98:99]
	v_lshl_add_u64 v[76:77], v[76:77], 0, s[98:99]
	v_lshl_add_u64 v[80:81], v[80:81], 0, s[98:99]
	s_waitcnt lgkmcnt(0)
	s_barrier
	s_add_u32 m0, s32, 0x4000
	v_mfma_f32_32x32x16_bf16 v[50:65], v[162:165], v[182:185], v[50:65]
	global_load_lds_dwordx4 v[66:67], off sc1
	s_add_u32 m0, s32, 0x5000
	v_mfma_f32_32x32x16_bf16 v[18:33], v[162:165], v[186:189], v[18:33]
	global_load_lds_dwordx4 v[70:71], off sc1
	s_add_u32 m0, s32, 0x6000
	v_mfma_f32_32x32x16_bf16 v[34:49], v[166:169], v[182:185], v[34:49]
	global_load_lds_dwordx4 v[74:75], off sc1
	s_add_u32 m0, s32, 0x7000
	v_mfma_f32_32x32x16_bf16 v[2:17], v[166:169], v[186:189], v[2:17]
	global_load_lds_dwordx4 v[78:79], off sc1
	s_add_u32 m0, s32, 0xc000
	v_mfma_f32_32x32x16_bf16 v[50:65], v[190:193], v[198:201], v[50:65]
	global_load_lds_dwordx4 v[68:69], off
	s_add_u32 m0, s32, 0xd000
	v_mfma_f32_32x32x16_bf16 v[18:33], v[190:193], v[202:205], v[18:33]
	global_load_lds_dwordx4 v[72:73], off
	s_add_u32 m0, s32, 0xe000
	v_mfma_f32_32x32x16_bf16 v[34:49], v[194:197], v[198:201], v[34:49]
	global_load_lds_dwordx4 v[76:77], off
	s_add_u32 m0, s32, 0xf000
	v_mfma_f32_32x32x16_bf16 v[2:17], v[194:197], v[202:205], v[2:17]
	global_load_lds_dwordx4 v[80:81], off
	s_waitcnt vmcnt(8)
	s_barrier
	ds_read_b128 v[162:165], v91
	ds_read_b128 v[166:169], v92 offset:32768
	ds_read_b128 v[182:185], v91 offset:4096
	ds_read_b128 v[186:189], v92 offset:36864
	ds_read_b128 v[190:193], v93
	ds_read_b128 v[194:197], v90 offset:32768
	ds_read_b128 v[198:201], v93 offset:4096
	ds_read_b128 v[202:205], v90 offset:36864
	s_waitcnt lgkmcnt(6)
	v_mfma_f32_32x32x16_bf16 v[50:65], v[162:165], v[166:169], v[50:65]
	s_waitcnt lgkmcnt(4)
	v_mfma_f32_32x32x16_bf16 v[18:33], v[162:165], v[186:189], v[18:33]
	v_mfma_f32_32x32x16_bf16 v[34:49], v[182:185], v[166:169], v[34:49]
	v_mfma_f32_32x32x16_bf16 v[2:17], v[182:185], v[186:189], v[2:17]
	ds_read_b128 v[162:165], v89
	ds_read_b128 v[166:169], v89 offset:4096
	ds_read_b128 v[182:185], v88 offset:32768
	ds_read_b128 v[186:189], v88 offset:36864
	s_waitcnt lgkmcnt(6)
	v_mfma_f32_32x32x16_bf16 v[50:65], v[190:193], v[194:197], v[50:65]
	s_waitcnt lgkmcnt(4)
	v_mfma_f32_32x32x16_bf16 v[18:33], v[190:193], v[202:205], v[18:33]
	v_mfma_f32_32x32x16_bf16 v[34:49], v[198:201], v[194:197], v[34:49]
	v_mfma_f32_32x32x16_bf16 v[2:17], v[198:201], v[202:205], v[2:17]
	ds_read_b128 v[190:193], v87
	ds_read_b128 v[194:197], v87 offset:4096
	ds_read_b128 v[198:201], v86 offset:32768
	ds_read_b128 v[202:205], v86 offset:36864
	v_lshl_add_u64 v[66:67], v[66:67], 0, s[98:99]
	v_lshl_add_u64 v[70:71], v[70:71], 0, s[98:99]
	v_lshl_add_u64 v[74:75], v[74:75], 0, s[98:99]
	v_lshl_add_u64 v[78:79], v[78:79], 0, s[98:99]
	v_lshl_add_u64 v[68:69], v[68:69], 0, s[98:99]
	v_lshl_add_u64 v[72:73], v[72:73], 0, s[98:99]
	v_lshl_add_u64 v[76:77], v[76:77], 0, s[98:99]
	v_lshl_add_u64 v[80:81], v[80:81], 0, s[98:99]
	s_waitcnt lgkmcnt(0)
	s_barrier
	s_add_u32 m0, s32, 0x0
	v_mfma_f32_32x32x16_bf16 v[50:65], v[162:165], v[182:185], v[50:65]
	global_load_lds_dwordx4 v[66:67], off sc1
	s_add_u32 m0, s32, 0x1000
	v_mfma_f32_32x32x16_bf16 v[18:33], v[162:165], v[186:189], v[18:33]
	global_load_lds_dwordx4 v[70:71], off sc1
	s_add_u32 m0, s32, 0x2000
	v_mfma_f32_32x32x16_bf16 v[34:49], v[166:169], v[182:185], v[34:49]
	global_load_lds_dwordx4 v[74:75], off sc1
	s_add_u32 m0, s32, 0x3000
	v_mfma_f32_32x32x16_bf16 v[2:17], v[166:169], v[186:189], v[2:17]
	global_load_lds_dwordx4 v[78:79], off sc1
	s_add_u32 m0, s32, 0x8000
	v_mfma_f32_32x32x16_bf16 v[50:65], v[190:193], v[198:201], v[50:65]
	global_load_lds_dwordx4 v[68:69], off
	s_add_u32 m0, s32, 0x9000
	v_mfma_f32_32x32x16_bf16 v[18:33], v[190:193], v[202:205], v[18:33]
	global_load_lds_dwordx4 v[72:73], off
	s_add_u32 m0, s32, 0xa000
	v_mfma_f32_32x32x16_bf16 v[34:49], v[194:197], v[198:201], v[34:49]
	global_load_lds_dwordx4 v[76:77], off
	s_add_u32 m0, s32, 0xb000
	v_mfma_f32_32x32x16_bf16 v[2:17], v[194:197], v[202:205], v[2:17]
	global_load_lds_dwordx4 v[80:81], off
	s_waitcnt vmcnt(8)
	s_barrier
	ds_read_b128 v[162:165], v91 offset:16384
	ds_read_b128 v[166:169], v92 offset:49152
	ds_read_b128 v[182:185], v91 offset:20480
	ds_read_b128 v[186:189], v92 offset:53248
	ds_read_b128 v[190:193], v93 offset:16384
	ds_read_b128 v[194:197], v90 offset:49152
	ds_read_b128 v[198:201], v93 offset:20480
	ds_read_b128 v[202:205], v90 offset:53248
	s_waitcnt lgkmcnt(6)
	v_mfma_f32_32x32x16_bf16 v[50:65], v[162:165], v[166:169], v[50:65]
	s_waitcnt lgkmcnt(4)
	v_mfma_f32_32x32x16_bf16 v[18:33], v[162:165], v[186:189], v[18:33]
	v_mfma_f32_32x32x16_bf16 v[34:49], v[182:185], v[166:169], v[34:49]
	v_mfma_f32_32x32x16_bf16 v[2:17], v[182:185], v[186:189], v[2:17]
	ds_read_b128 v[162:165], v89 offset:16384
	ds_read_b128 v[166:169], v89 offset:20480
	ds_read_b128 v[182:185], v88 offset:49152
	ds_read_b128 v[186:189], v88 offset:53248
	s_waitcnt lgkmcnt(6)
	v_mfma_f32_32x32x16_bf16 v[50:65], v[190:193], v[194:197], v[50:65]
	s_waitcnt lgkmcnt(4)
	v_mfma_f32_32x32x16_bf16 v[18:33], v[190:193], v[202:205], v[18:33]
	v_mfma_f32_32x32x16_bf16 v[34:49], v[198:201], v[194:197], v[34:49]
	v_mfma_f32_32x32x16_bf16 v[2:17], v[198:201], v[202:205], v[2:17]
	ds_read_b128 v[190:193], v87 offset:16384
	ds_read_b128 v[194:197], v87 offset:20480
	ds_read_b128 v[198:201], v86 offset:49152
	ds_read_b128 v[202:205], v86 offset:53248
	v_lshl_add_u64 v[66:67], v[66:67], 0, s[98:99]
	v_lshl_add_u64 v[70:71], v[70:71], 0, s[98:99]
	v_lshl_add_u64 v[74:75], v[74:75], 0, s[98:99]
	v_lshl_add_u64 v[78:79], v[78:79], 0, s[98:99]
	v_lshl_add_u64 v[68:69], v[68:69], 0, s[98:99]
	v_lshl_add_u64 v[72:73], v[72:73], 0, s[98:99]
	v_lshl_add_u64 v[76:77], v[76:77], 0, s[98:99]
	v_lshl_add_u64 v[80:81], v[80:81], 0, s[98:99]
	s_waitcnt lgkmcnt(0)
	s_barrier
	s_add_u32 m0, s32, 0x4000
	v_mfma_f32_32x32x16_bf16 v[50:65], v[162:165], v[182:185], v[50:65]
	global_load_lds_dwordx4 v[66:67], off sc1
	s_add_u32 m0, s32, 0x5000
	v_mfma_f32_32x32x16_bf16 v[18:33], v[162:165], v[186:189], v[18:33]
	global_load_lds_dwordx4 v[70:71], off sc1
	s_add_u32 m0, s32, 0x6000
	v_mfma_f32_32x32x16_bf16 v[34:49], v[166:169], v[182:185], v[34:49]
	global_load_lds_dwordx4 v[74:75], off sc1
	s_add_u32 m0, s32, 0x7000
	v_mfma_f32_32x32x16_bf16 v[2:17], v[166:169], v[186:189], v[2:17]
	global_load_lds_dwordx4 v[78:79], off sc1
	s_add_u32 m0, s32, 0xc000
	v_mfma_f32_32x32x16_bf16 v[50:65], v[190:193], v[198:201], v[50:65]
	global_load_lds_dwordx4 v[68:69], off
	s_add_u32 m0, s32, 0xd000
	v_mfma_f32_32x32x16_bf16 v[18:33], v[190:193], v[202:205], v[18:33]
	global_load_lds_dwordx4 v[72:73], off
	s_add_u32 m0, s32, 0xe000
	v_mfma_f32_32x32x16_bf16 v[34:49], v[194:197], v[198:201], v[34:49]
	global_load_lds_dwordx4 v[76:77], off
	s_add_u32 m0, s32, 0xf000
	v_mfma_f32_32x32x16_bf16 v[2:17], v[194:197], v[202:205], v[2:17]
	global_load_lds_dwordx4 v[80:81], off
	s_waitcnt vmcnt(8)
	s_barrier
	ds_read_b128 v[162:165], v91
	ds_read_b128 v[166:169], v92 offset:32768
	ds_read_b128 v[182:185], v91 offset:4096
	ds_read_b128 v[186:189], v92 offset:36864
	ds_read_b128 v[190:193], v93
	ds_read_b128 v[194:197], v90 offset:32768
	ds_read_b128 v[198:201], v93 offset:4096
	ds_read_b128 v[202:205], v90 offset:36864
	s_waitcnt lgkmcnt(6)
	v_mfma_f32_32x32x16_bf16 v[50:65], v[162:165], v[166:169], v[50:65]
	s_waitcnt lgkmcnt(4)
	v_mfma_f32_32x32x16_bf16 v[18:33], v[162:165], v[186:189], v[18:33]
	v_mfma_f32_32x32x16_bf16 v[34:49], v[182:185], v[166:169], v[34:49]
	v_mfma_f32_32x32x16_bf16 v[2:17], v[182:185], v[186:189], v[2:17]
	ds_read_b128 v[162:165], v89
	ds_read_b128 v[166:169], v89 offset:4096
	ds_read_b128 v[182:185], v88 offset:32768
	ds_read_b128 v[186:189], v88 offset:36864
	s_waitcnt lgkmcnt(6)
	v_mfma_f32_32x32x16_bf16 v[50:65], v[190:193], v[194:197], v[50:65]
	s_waitcnt lgkmcnt(4)
	v_mfma_f32_32x32x16_bf16 v[18:33], v[190:193], v[202:205], v[18:33]
	v_mfma_f32_32x32x16_bf16 v[34:49], v[198:201], v[194:197], v[34:49]
	v_mfma_f32_32x32x16_bf16 v[2:17], v[198:201], v[202:205], v[2:17]
	ds_read_b128 v[190:193], v87
	ds_read_b128 v[194:197], v87 offset:4096
	ds_read_b128 v[198:201], v86 offset:32768
	ds_read_b128 v[202:205], v86 offset:36864
	v_lshl_add_u64 v[66:67], v[66:67], 0, s[98:99]
	v_lshl_add_u64 v[70:71], v[70:71], 0, s[98:99]
	v_lshl_add_u64 v[74:75], v[74:75], 0, s[98:99]
	v_lshl_add_u64 v[78:79], v[78:79], 0, s[98:99]
	v_lshl_add_u64 v[68:69], v[68:69], 0, s[98:99]
	v_lshl_add_u64 v[72:73], v[72:73], 0, s[98:99]
	v_lshl_add_u64 v[76:77], v[76:77], 0, s[98:99]
	v_lshl_add_u64 v[80:81], v[80:81], 0, s[98:99]
	s_waitcnt lgkmcnt(0)
	s_barrier
	s_add_u32 m0, s32, 0x0
	v_mfma_f32_32x32x16_bf16 v[50:65], v[162:165], v[182:185], v[50:65]
	global_load_lds_dwordx4 v[66:67], off sc1
	s_add_u32 m0, s32, 0x1000
	v_mfma_f32_32x32x16_bf16 v[18:33], v[162:165], v[186:189], v[18:33]
	global_load_lds_dwordx4 v[70:71], off sc1
	s_add_u32 m0, s32, 0x2000
	v_mfma_f32_32x32x16_bf16 v[34:49], v[166:169], v[182:185], v[34:49]
	global_load_lds_dwordx4 v[74:75], off sc1
	s_add_u32 m0, s32, 0x3000
	v_mfma_f32_32x32x16_bf16 v[2:17], v[166:169], v[186:189], v[2:17]
	global_load_lds_dwordx4 v[78:79], off sc1
	s_add_u32 m0, s32, 0x8000
	v_mfma_f32_32x32x16_bf16 v[50:65], v[190:193], v[198:201], v[50:65]
	global_load_lds_dwordx4 v[68:69], off
	s_add_u32 m0, s32, 0x9000
	v_mfma_f32_32x32x16_bf16 v[18:33], v[190:193], v[202:205], v[18:33]
	global_load_lds_dwordx4 v[72:73], off
	s_add_u32 m0, s32, 0xa000
	v_mfma_f32_32x32x16_bf16 v[34:49], v[194:197], v[198:201], v[34:49]
	global_load_lds_dwordx4 v[76:77], off
	s_add_u32 m0, s32, 0xb000
	v_mfma_f32_32x32x16_bf16 v[2:17], v[194:197], v[202:205], v[2:17]
	global_load_lds_dwordx4 v[80:81], off
	s_waitcnt vmcnt(8)
	s_barrier
	ds_read_b128 v[162:165], v91 offset:16384
	ds_read_b128 v[166:169], v92 offset:49152
	ds_read_b128 v[182:185], v91 offset:20480
	ds_read_b128 v[186:189], v92 offset:53248
	ds_read_b128 v[190:193], v93 offset:16384
	ds_read_b128 v[194:197], v90 offset:49152
	ds_read_b128 v[198:201], v93 offset:20480
	ds_read_b128 v[202:205], v90 offset:53248
	s_waitcnt lgkmcnt(6)
	v_mfma_f32_32x32x16_bf16 v[50:65], v[162:165], v[166:169], v[50:65]
	s_waitcnt lgkmcnt(4)
	v_mfma_f32_32x32x16_bf16 v[18:33], v[162:165], v[186:189], v[18:33]
	v_mfma_f32_32x32x16_bf16 v[34:49], v[182:185], v[166:169], v[34:49]
	v_mfma_f32_32x32x16_bf16 v[2:17], v[182:185], v[186:189], v[2:17]
	ds_read_b128 v[162:165], v89 offset:16384
	ds_read_b128 v[166:169], v89 offset:20480
	ds_read_b128 v[182:185], v88 offset:49152
	ds_read_b128 v[186:189], v88 offset:53248
	s_waitcnt lgkmcnt(6)
	v_mfma_f32_32x32x16_bf16 v[50:65], v[190:193], v[194:197], v[50:65]
	s_waitcnt lgkmcnt(4)
	v_mfma_f32_32x32x16_bf16 v[18:33], v[190:193], v[202:205], v[18:33]
	v_mfma_f32_32x32x16_bf16 v[34:49], v[198:201], v[194:197], v[34:49]
	v_mfma_f32_32x32x16_bf16 v[2:17], v[198:201], v[202:205], v[2:17]
	ds_read_b128 v[190:193], v87 offset:16384
	ds_read_b128 v[194:197], v87 offset:20480
	ds_read_b128 v[198:201], v86 offset:49152
	ds_read_b128 v[202:205], v86 offset:53248
	v_lshl_add_u64 v[66:67], v[66:67], 0, s[98:99]
	v_lshl_add_u64 v[70:71], v[70:71], 0, s[98:99]
	v_lshl_add_u64 v[74:75], v[74:75], 0, s[98:99]
	v_lshl_add_u64 v[78:79], v[78:79], 0, s[98:99]
	v_lshl_add_u64 v[68:69], v[68:69], 0, s[98:99]
	v_lshl_add_u64 v[72:73], v[72:73], 0, s[98:99]
	v_lshl_add_u64 v[76:77], v[76:77], 0, s[98:99]
	v_lshl_add_u64 v[80:81], v[80:81], 0, s[98:99]
	s_waitcnt lgkmcnt(0)
	s_barrier
	s_add_u32 m0, s32, 0x4000
	v_mfma_f32_32x32x16_bf16 v[50:65], v[162:165], v[182:185], v[50:65]
	global_load_lds_dwordx4 v[66:67], off sc1
	s_add_u32 m0, s32, 0x5000
	v_mfma_f32_32x32x16_bf16 v[18:33], v[162:165], v[186:189], v[18:33]
	global_load_lds_dwordx4 v[70:71], off sc1
	s_add_u32 m0, s32, 0x6000
	v_mfma_f32_32x32x16_bf16 v[34:49], v[166:169], v[182:185], v[34:49]
	global_load_lds_dwordx4 v[74:75], off sc1
	s_add_u32 m0, s32, 0x7000
	v_mfma_f32_32x32x16_bf16 v[2:17], v[166:169], v[186:189], v[2:17]
	global_load_lds_dwordx4 v[78:79], off sc1
	s_add_u32 m0, s32, 0xc000
	v_mfma_f32_32x32x16_bf16 v[50:65], v[190:193], v[198:201], v[50:65]
	global_load_lds_dwordx4 v[68:69], off
	s_add_u32 m0, s32, 0xd000
	v_mfma_f32_32x32x16_bf16 v[18:33], v[190:193], v[202:205], v[18:33]
	global_load_lds_dwordx4 v[72:73], off
	s_add_u32 m0, s32, 0xe000
	v_mfma_f32_32x32x16_bf16 v[34:49], v[194:197], v[198:201], v[34:49]
	global_load_lds_dwordx4 v[76:77], off
	s_add_u32 m0, s32, 0xf000
	v_mfma_f32_32x32x16_bf16 v[2:17], v[194:197], v[202:205], v[2:17]
	global_load_lds_dwordx4 v[80:81], off
	s_waitcnt vmcnt(8)
	s_barrier
	ds_read_b128 v[162:165], v91
	ds_read_b128 v[166:169], v92 offset:32768
	ds_read_b128 v[182:185], v91 offset:4096
	ds_read_b128 v[186:189], v92 offset:36864
	ds_read_b128 v[190:193], v93
	ds_read_b128 v[194:197], v90 offset:32768
	ds_read_b128 v[198:201], v93 offset:4096
	ds_read_b128 v[202:205], v90 offset:36864
	s_waitcnt lgkmcnt(6)
	v_mfma_f32_32x32x16_bf16 v[50:65], v[162:165], v[166:169], v[50:65]
	s_waitcnt lgkmcnt(4)
	v_mfma_f32_32x32x16_bf16 v[18:33], v[162:165], v[186:189], v[18:33]
	v_mfma_f32_32x32x16_bf16 v[34:49], v[182:185], v[166:169], v[34:49]
	v_mfma_f32_32x32x16_bf16 v[2:17], v[182:185], v[186:189], v[2:17]
	ds_read_b128 v[162:165], v89
	ds_read_b128 v[166:169], v89 offset:4096
	ds_read_b128 v[182:185], v88 offset:32768
	ds_read_b128 v[186:189], v88 offset:36864
	s_waitcnt lgkmcnt(6)
	v_mfma_f32_32x32x16_bf16 v[50:65], v[190:193], v[194:197], v[50:65]
	s_waitcnt lgkmcnt(4)
	v_mfma_f32_32x32x16_bf16 v[18:33], v[190:193], v[202:205], v[18:33]
	v_mfma_f32_32x32x16_bf16 v[34:49], v[198:201], v[194:197], v[34:49]
	v_mfma_f32_32x32x16_bf16 v[2:17], v[198:201], v[202:205], v[2:17]
	ds_read_b128 v[190:193], v87
	ds_read_b128 v[194:197], v87 offset:4096
	ds_read_b128 v[198:201], v86 offset:32768
	ds_read_b128 v[202:205], v86 offset:36864
	v_lshl_add_u64 v[66:67], v[66:67], 0, s[98:99]
	v_lshl_add_u64 v[70:71], v[70:71], 0, s[98:99]
	v_lshl_add_u64 v[74:75], v[74:75], 0, s[98:99]
	v_lshl_add_u64 v[78:79], v[78:79], 0, s[98:99]
	v_lshl_add_u64 v[68:69], v[68:69], 0, s[98:99]
	v_lshl_add_u64 v[72:73], v[72:73], 0, s[98:99]
	v_lshl_add_u64 v[76:77], v[76:77], 0, s[98:99]
	v_lshl_add_u64 v[80:81], v[80:81], 0, s[98:99]
	s_waitcnt lgkmcnt(0)
	s_barrier
	s_add_u32 m0, s32, 0x0
	v_mfma_f32_32x32x16_bf16 v[50:65], v[162:165], v[182:185], v[50:65]
	global_load_lds_dwordx4 v[66:67], off sc1
	s_add_u32 m0, s32, 0x1000
	v_mfma_f32_32x32x16_bf16 v[18:33], v[162:165], v[186:189], v[18:33]
	global_load_lds_dwordx4 v[70:71], off sc1
	s_add_u32 m0, s32, 0x2000
	v_mfma_f32_32x32x16_bf16 v[34:49], v[166:169], v[182:185], v[34:49]
	global_load_lds_dwordx4 v[74:75], off sc1
	s_add_u32 m0, s32, 0x3000
	v_mfma_f32_32x32x16_bf16 v[2:17], v[166:169], v[186:189], v[2:17]
	global_load_lds_dwordx4 v[78:79], off sc1
	s_add_u32 m0, s32, 0x8000
	v_mfma_f32_32x32x16_bf16 v[50:65], v[190:193], v[198:201], v[50:65]
	global_load_lds_dwordx4 v[68:69], off
	s_add_u32 m0, s32, 0x9000
	v_mfma_f32_32x32x16_bf16 v[18:33], v[190:193], v[202:205], v[18:33]
	global_load_lds_dwordx4 v[72:73], off
	s_add_u32 m0, s32, 0xa000
	v_mfma_f32_32x32x16_bf16 v[34:49], v[194:197], v[198:201], v[34:49]
	global_load_lds_dwordx4 v[76:77], off
	s_add_u32 m0, s32, 0xb000
	v_mfma_f32_32x32x16_bf16 v[2:17], v[194:197], v[202:205], v[2:17]
	global_load_lds_dwordx4 v[80:81], off
	s_waitcnt vmcnt(8)
	s_barrier
	ds_read_b128 v[162:165], v91 offset:16384
	ds_read_b128 v[166:169], v92 offset:49152
	ds_read_b128 v[182:185], v91 offset:20480
	ds_read_b128 v[186:189], v92 offset:53248
	ds_read_b128 v[190:193], v93 offset:16384
	ds_read_b128 v[194:197], v90 offset:49152
	ds_read_b128 v[198:201], v93 offset:20480
	ds_read_b128 v[202:205], v90 offset:53248
	s_waitcnt lgkmcnt(6)
	v_mfma_f32_32x32x16_bf16 v[50:65], v[162:165], v[166:169], v[50:65]
	s_waitcnt lgkmcnt(4)
	v_mfma_f32_32x32x16_bf16 v[18:33], v[162:165], v[186:189], v[18:33]
	v_mfma_f32_32x32x16_bf16 v[34:49], v[182:185], v[166:169], v[34:49]
	v_mfma_f32_32x32x16_bf16 v[2:17], v[182:185], v[186:189], v[2:17]
	ds_read_b128 v[162:165], v89 offset:16384
	ds_read_b128 v[166:169], v89 offset:20480
	ds_read_b128 v[182:185], v88 offset:49152
	ds_read_b128 v[186:189], v88 offset:53248
	s_waitcnt lgkmcnt(6)
	v_mfma_f32_32x32x16_bf16 v[50:65], v[190:193], v[194:197], v[50:65]
	s_waitcnt lgkmcnt(4)
	v_mfma_f32_32x32x16_bf16 v[18:33], v[190:193], v[202:205], v[18:33]
	v_mfma_f32_32x32x16_bf16 v[34:49], v[198:201], v[194:197], v[34:49]
	v_mfma_f32_32x32x16_bf16 v[2:17], v[198:201], v[202:205], v[2:17]
	ds_read_b128 v[190:193], v87 offset:16384
	ds_read_b128 v[194:197], v87 offset:20480
	ds_read_b128 v[198:201], v86 offset:49152
	ds_read_b128 v[202:205], v86 offset:53248
	v_lshl_add_u64 v[66:67], v[66:67], 0, s[98:99]
	v_lshl_add_u64 v[70:71], v[70:71], 0, s[98:99]
	v_lshl_add_u64 v[74:75], v[74:75], 0, s[98:99]
	v_lshl_add_u64 v[78:79], v[78:79], 0, s[98:99]
	v_lshl_add_u64 v[68:69], v[68:69], 0, s[98:99]
	v_lshl_add_u64 v[72:73], v[72:73], 0, s[98:99]
	v_lshl_add_u64 v[76:77], v[76:77], 0, s[98:99]
	v_lshl_add_u64 v[80:81], v[80:81], 0, s[98:99]
	s_waitcnt lgkmcnt(0)
	s_barrier
	s_add_u32 m0, s32, 0x4000
	v_mfma_f32_32x32x16_bf16 v[50:65], v[162:165], v[182:185], v[50:65]
	global_load_lds_dwordx4 v[66:67], off sc1
	s_add_u32 m0, s32, 0x5000
	v_mfma_f32_32x32x16_bf16 v[18:33], v[162:165], v[186:189], v[18:33]
	global_load_lds_dwordx4 v[70:71], off sc1
	s_add_u32 m0, s32, 0x6000
	v_mfma_f32_32x32x16_bf16 v[34:49], v[166:169], v[182:185], v[34:49]
	global_load_lds_dwordx4 v[74:75], off sc1
	s_add_u32 m0, s32, 0x7000
	v_mfma_f32_32x32x16_bf16 v[2:17], v[166:169], v[186:189], v[2:17]
	global_load_lds_dwordx4 v[78:79], off sc1
	s_add_u32 m0, s32, 0xc000
	v_mfma_f32_32x32x16_bf16 v[50:65], v[190:193], v[198:201], v[50:65]
	global_load_lds_dwordx4 v[68:69], off
	s_add_u32 m0, s32, 0xd000
	v_mfma_f32_32x32x16_bf16 v[18:33], v[190:193], v[202:205], v[18:33]
	global_load_lds_dwordx4 v[72:73], off
	s_add_u32 m0, s32, 0xe000
	v_mfma_f32_32x32x16_bf16 v[34:49], v[194:197], v[198:201], v[34:49]
	global_load_lds_dwordx4 v[76:77], off
	s_add_u32 m0, s32, 0xf000
	v_mfma_f32_32x32x16_bf16 v[2:17], v[194:197], v[202:205], v[2:17]
	global_load_lds_dwordx4 v[80:81], off
	s_waitcnt vmcnt(8)
	s_barrier
	ds_read_b128 v[162:165], v91
	ds_read_b128 v[166:169], v92 offset:32768
	ds_read_b128 v[182:185], v91 offset:4096
	ds_read_b128 v[186:189], v92 offset:36864
	ds_read_b128 v[190:193], v93
	ds_read_b128 v[194:197], v90 offset:32768
	ds_read_b128 v[198:201], v93 offset:4096
	ds_read_b128 v[202:205], v90 offset:36864
	s_waitcnt lgkmcnt(6)
	v_mfma_f32_32x32x16_bf16 v[50:65], v[162:165], v[166:169], v[50:65]
	s_waitcnt lgkmcnt(4)
	v_mfma_f32_32x32x16_bf16 v[18:33], v[162:165], v[186:189], v[18:33]
	v_mfma_f32_32x32x16_bf16 v[34:49], v[182:185], v[166:169], v[34:49]
	v_mfma_f32_32x32x16_bf16 v[2:17], v[182:185], v[186:189], v[2:17]
	ds_read_b128 v[162:165], v89
	ds_read_b128 v[166:169], v89 offset:4096
	ds_read_b128 v[182:185], v88 offset:32768
	ds_read_b128 v[186:189], v88 offset:36864
	s_waitcnt lgkmcnt(6)
	v_mfma_f32_32x32x16_bf16 v[50:65], v[190:193], v[194:197], v[50:65]
	s_waitcnt lgkmcnt(4)
	v_mfma_f32_32x32x16_bf16 v[18:33], v[190:193], v[202:205], v[18:33]
	v_mfma_f32_32x32x16_bf16 v[34:49], v[198:201], v[194:197], v[34:49]
	v_mfma_f32_32x32x16_bf16 v[2:17], v[198:201], v[202:205], v[2:17]
	ds_read_b128 v[190:193], v87
	ds_read_b128 v[194:197], v87 offset:4096
	ds_read_b128 v[198:201], v86 offset:32768
	ds_read_b128 v[202:205], v86 offset:36864
	v_lshl_add_u64 v[66:67], v[66:67], 0, s[98:99]
	v_lshl_add_u64 v[70:71], v[70:71], 0, s[98:99]
	v_lshl_add_u64 v[74:75], v[74:75], 0, s[98:99]
	v_lshl_add_u64 v[78:79], v[78:79], 0, s[98:99]
	v_lshl_add_u64 v[68:69], v[68:69], 0, s[98:99]
	v_lshl_add_u64 v[72:73], v[72:73], 0, s[98:99]
	v_lshl_add_u64 v[76:77], v[76:77], 0, s[98:99]
	v_lshl_add_u64 v[80:81], v[80:81], 0, s[98:99]
	s_waitcnt lgkmcnt(0)
	s_barrier
	s_add_u32 m0, s32, 0x0
	v_mfma_f32_32x32x16_bf16 v[50:65], v[162:165], v[182:185], v[50:65]
	global_load_lds_dwordx4 v[66:67], off sc1
	s_add_u32 m0, s32, 0x1000
	v_mfma_f32_32x32x16_bf16 v[18:33], v[162:165], v[186:189], v[18:33]
	global_load_lds_dwordx4 v[70:71], off sc1
	s_add_u32 m0, s32, 0x2000
	v_mfma_f32_32x32x16_bf16 v[34:49], v[166:169], v[182:185], v[34:49]
	global_load_lds_dwordx4 v[74:75], off sc1
	s_add_u32 m0, s32, 0x3000
	v_mfma_f32_32x32x16_bf16 v[2:17], v[166:169], v[186:189], v[2:17]
	global_load_lds_dwordx4 v[78:79], off sc1
	s_add_u32 m0, s32, 0x8000
	v_mfma_f32_32x32x16_bf16 v[50:65], v[190:193], v[198:201], v[50:65]
	global_load_lds_dwordx4 v[68:69], off
	s_add_u32 m0, s32, 0x9000
	v_mfma_f32_32x32x16_bf16 v[18:33], v[190:193], v[202:205], v[18:33]
	global_load_lds_dwordx4 v[72:73], off
	s_add_u32 m0, s32, 0xa000
	v_mfma_f32_32x32x16_bf16 v[34:49], v[194:197], v[198:201], v[34:49]
	global_load_lds_dwordx4 v[76:77], off
	s_add_u32 m0, s32, 0xb000
	v_mfma_f32_32x32x16_bf16 v[2:17], v[194:197], v[202:205], v[2:17]
	global_load_lds_dwordx4 v[80:81], off
	s_waitcnt vmcnt(8)
	s_barrier
	ds_read_b128 v[162:165], v91 offset:16384
	ds_read_b128 v[166:169], v92 offset:49152
	ds_read_b128 v[182:185], v91 offset:20480
	ds_read_b128 v[186:189], v92 offset:53248
	ds_read_b128 v[190:193], v93 offset:16384
	ds_read_b128 v[194:197], v90 offset:49152
	ds_read_b128 v[198:201], v93 offset:20480
	ds_read_b128 v[202:205], v90 offset:53248
	s_waitcnt lgkmcnt(6)
	v_mfma_f32_32x32x16_bf16 v[50:65], v[162:165], v[166:169], v[50:65]
	s_waitcnt lgkmcnt(4)
	v_mfma_f32_32x32x16_bf16 v[18:33], v[162:165], v[186:189], v[18:33]
	v_mfma_f32_32x32x16_bf16 v[34:49], v[182:185], v[166:169], v[34:49]
	v_mfma_f32_32x32x16_bf16 v[2:17], v[182:185], v[186:189], v[2:17]
	ds_read_b128 v[162:165], v89 offset:16384
	ds_read_b128 v[166:169], v89 offset:20480
	ds_read_b128 v[182:185], v88 offset:49152
	ds_read_b128 v[186:189], v88 offset:53248
	s_waitcnt lgkmcnt(6)
	v_mfma_f32_32x32x16_bf16 v[50:65], v[190:193], v[194:197], v[50:65]
	s_waitcnt lgkmcnt(4)
	v_mfma_f32_32x32x16_bf16 v[18:33], v[190:193], v[202:205], v[18:33]
	v_mfma_f32_32x32x16_bf16 v[34:49], v[198:201], v[194:197], v[34:49]
	v_mfma_f32_32x32x16_bf16 v[2:17], v[198:201], v[202:205], v[2:17]
	ds_read_b128 v[190:193], v87 offset:16384
	ds_read_b128 v[194:197], v87 offset:20480
	ds_read_b128 v[198:201], v86 offset:49152
	ds_read_b128 v[202:205], v86 offset:53248
	v_lshl_add_u64 v[66:67], v[66:67], 0, s[98:99]
	v_lshl_add_u64 v[70:71], v[70:71], 0, s[98:99]
	v_lshl_add_u64 v[74:75], v[74:75], 0, s[98:99]
	v_lshl_add_u64 v[78:79], v[78:79], 0, s[98:99]
	v_lshl_add_u64 v[68:69], v[68:69], 0, s[98:99]
	v_lshl_add_u64 v[72:73], v[72:73], 0, s[98:99]
	v_lshl_add_u64 v[76:77], v[76:77], 0, s[98:99]
	v_lshl_add_u64 v[80:81], v[80:81], 0, s[98:99]
	s_waitcnt lgkmcnt(0)
	s_barrier
	s_add_u32 m0, s32, 0x4000
	v_mfma_f32_32x32x16_bf16 v[50:65], v[162:165], v[182:185], v[50:65]
	global_load_lds_dwordx4 v[66:67], off sc1
	s_add_u32 m0, s32, 0x5000
	v_mfma_f32_32x32x16_bf16 v[18:33], v[162:165], v[186:189], v[18:33]
	global_load_lds_dwordx4 v[70:71], off sc1
	s_add_u32 m0, s32, 0x6000
	v_mfma_f32_32x32x16_bf16 v[34:49], v[166:169], v[182:185], v[34:49]
	global_load_lds_dwordx4 v[74:75], off sc1
	s_add_u32 m0, s32, 0x7000
	v_mfma_f32_32x32x16_bf16 v[2:17], v[166:169], v[186:189], v[2:17]
	global_load_lds_dwordx4 v[78:79], off sc1
	s_add_u32 m0, s32, 0xc000
	v_mfma_f32_32x32x16_bf16 v[50:65], v[190:193], v[198:201], v[50:65]
	global_load_lds_dwordx4 v[68:69], off
	s_add_u32 m0, s32, 0xd000
	v_mfma_f32_32x32x16_bf16 v[18:33], v[190:193], v[202:205], v[18:33]
	global_load_lds_dwordx4 v[72:73], off
	s_add_u32 m0, s32, 0xe000
	v_mfma_f32_32x32x16_bf16 v[34:49], v[194:197], v[198:201], v[34:49]
	global_load_lds_dwordx4 v[76:77], off
	s_add_u32 m0, s32, 0xf000
	v_mfma_f32_32x32x16_bf16 v[2:17], v[194:197], v[202:205], v[2:17]
	global_load_lds_dwordx4 v[80:81], off
	s_waitcnt vmcnt(8)
	s_barrier
	ds_read_b128 v[162:165], v91
	ds_read_b128 v[166:169], v92 offset:32768
	ds_read_b128 v[182:185], v91 offset:4096
	ds_read_b128 v[186:189], v92 offset:36864
	ds_read_b128 v[190:193], v93
	ds_read_b128 v[194:197], v90 offset:32768
	ds_read_b128 v[198:201], v93 offset:4096
	ds_read_b128 v[202:205], v90 offset:36864
	s_waitcnt lgkmcnt(6)
	v_mfma_f32_32x32x16_bf16 v[50:65], v[162:165], v[166:169], v[50:65]
	s_waitcnt lgkmcnt(4)
	v_mfma_f32_32x32x16_bf16 v[18:33], v[162:165], v[186:189], v[18:33]
	v_mfma_f32_32x32x16_bf16 v[34:49], v[182:185], v[166:169], v[34:49]
	v_mfma_f32_32x32x16_bf16 v[2:17], v[182:185], v[186:189], v[2:17]
	ds_read_b128 v[162:165], v89
	ds_read_b128 v[166:169], v89 offset:4096
	ds_read_b128 v[182:185], v88 offset:32768
	ds_read_b128 v[186:189], v88 offset:36864
	s_waitcnt lgkmcnt(6)
	v_mfma_f32_32x32x16_bf16 v[50:65], v[190:193], v[194:197], v[50:65]
	s_waitcnt lgkmcnt(4)
	v_mfma_f32_32x32x16_bf16 v[18:33], v[190:193], v[202:205], v[18:33]
	v_mfma_f32_32x32x16_bf16 v[34:49], v[198:201], v[194:197], v[34:49]
	v_mfma_f32_32x32x16_bf16 v[2:17], v[198:201], v[202:205], v[2:17]
	ds_read_b128 v[190:193], v87
	ds_read_b128 v[194:197], v87 offset:4096
	ds_read_b128 v[198:201], v86 offset:32768
	ds_read_b128 v[202:205], v86 offset:36864
	v_lshl_add_u64 v[66:67], v[66:67], 0, s[98:99]
	v_lshl_add_u64 v[70:71], v[70:71], 0, s[98:99]
	v_lshl_add_u64 v[74:75], v[74:75], 0, s[98:99]
	v_lshl_add_u64 v[78:79], v[78:79], 0, s[98:99]
	v_lshl_add_u64 v[68:69], v[68:69], 0, s[98:99]
	v_lshl_add_u64 v[72:73], v[72:73], 0, s[98:99]
	v_lshl_add_u64 v[76:77], v[76:77], 0, s[98:99]
	v_lshl_add_u64 v[80:81], v[80:81], 0, s[98:99]
	s_waitcnt lgkmcnt(0)
	s_barrier
	s_add_u32 m0, s32, 0x0
	s_nop 0
	global_load_lds_dwordx4 v[66:67], off sc1
	s_add_u32 m0, s32, 0x1000
	s_nop 0
	global_load_lds_dwordx4 v[70:71], off sc1
	s_add_u32 m0, s32, 0x2000
	s_nop 0
	global_load_lds_dwordx4 v[74:75], off sc1
	s_add_u32 m0, s32, 0x3000
	s_nop 0
	global_load_lds_dwordx4 v[78:79], off sc1
	s_add_u32 m0, s32, 0x8000
	s_nop 0
	global_load_lds_dwordx4 v[68:69], off
	s_add_u32 m0, s32, 0x9000
	s_nop 0
	global_load_lds_dwordx4 v[72:73], off
	s_add_u32 m0, s32, 0xa000
	s_nop 0
	global_load_lds_dwordx4 v[76:77], off
	s_add_u32 m0, s32, 0xb000
	s_nop 0
	global_load_lds_dwordx4 v[80:81], off
	s_waitcnt vmcnt(8)
	s_barrier
	s_nop 0
	s_nop 0
	s_nop 0
	s_nop 0
	s_nop 0
	s_nop 0
	s_nop 0
	v_mfma_f32_32x32x16_bf16 v[50:65], v[162:165], v[182:185], v[50:65]
	v_mfma_f32_32x32x16_bf16 v[18:33], v[162:165], v[186:189], v[18:33]
	v_mfma_f32_32x32x16_bf16 v[34:49], v[166:169], v[182:185], v[34:49]
	v_mfma_f32_32x32x16_bf16 v[2:17], v[166:169], v[186:189], v[2:17]
	ds_read_b128 v[110:113], v91 offset:16384
	ds_read_b128 v[114:117], v91 offset:20480
	ds_read_b128 v[118:121], v92 offset:49152
	ds_read_b128 v[122:125], v92 offset:53248
	ds_read_b128 v[162:165], v93 offset:16384
	ds_read_b128 v[166:169], v93 offset:20480
	ds_read_b128 v[182:185], v90 offset:49152
	ds_read_b128 v[186:189], v90 offset:53248
	v_mfma_f32_32x32x16_bf16 v[50:65], v[190:193], v[198:201], v[50:65]
	v_mfma_f32_32x32x16_bf16 v[18:33], v[190:193], v[202:205], v[18:33]
	v_mfma_f32_32x32x16_bf16 v[34:49], v[194:197], v[198:201], v[34:49]
	v_mfma_f32_32x32x16_bf16 v[2:17], v[194:197], v[202:205], v[2:17]
	s_waitcnt lgkmcnt(5)
	v_mfma_f32_32x32x16_bf16 v[50:65], v[110:113], v[118:121], v[50:65]
	s_waitcnt lgkmcnt(4)
	v_mfma_f32_32x32x16_bf16 v[18:33], v[110:113], v[122:125], v[18:33]
	v_mfma_f32_32x32x16_bf16 v[34:49], v[114:117], v[118:121], v[34:49]
	v_mfma_f32_32x32x16_bf16 v[2:17], v[114:117], v[122:125], v[2:17]
	ds_read_b128 v[110:113], v89 offset:16384
	ds_read_b128 v[114:117], v89 offset:20480
	ds_read_b128 v[118:121], v88 offset:49152
	ds_read_b128 v[122:125], v88 offset:53248
	s_waitcnt lgkmcnt(5)
	v_mfma_f32_32x32x16_bf16 v[50:65], v[162:165], v[182:185], v[50:65]
	s_waitcnt lgkmcnt(4)
	v_mfma_f32_32x32x16_bf16 v[18:33], v[162:165], v[186:189], v[18:33]
	v_mfma_f32_32x32x16_bf16 v[34:49], v[166:169], v[182:185], v[34:49]
	v_mfma_f32_32x32x16_bf16 v[2:17], v[166:169], v[186:189], v[2:17]
	ds_read_b128 v[162:165], v87 offset:16384
	ds_read_b128 v[166:169], v87 offset:20480
	ds_read_b128 v[182:185], v86 offset:49152
	ds_read_b128 v[186:189], v86 offset:53248
	s_waitcnt lgkmcnt(5)
	v_mfma_f32_32x32x16_bf16 v[50:65], v[110:113], v[118:121], v[50:65]
	v_lshl_add_u64 v[66:67], v[66:67], 0, s[98:99]
	v_lshl_add_u64 v[70:71], v[70:71], 0, s[98:99]
	v_lshl_add_u64 v[74:75], v[74:75], 0, s[98:99]
	v_lshl_add_u64 v[78:79], v[78:79], 0, s[98:99]
	v_lshl_add_u64 v[68:69], v[68:69], 0, s[98:99]
	v_lshl_add_u64 v[72:73], v[72:73], 0, s[98:99]
	v_lshl_add_u64 v[76:77], v[76:77], 0, s[98:99]
	v_lshl_add_u64 v[80:81], v[80:81], 0, s[98:99]
	s_waitcnt lgkmcnt(0)
	s_barrier
	s_add_u32 m0, s32, 0x4000
	s_nop 0
	global_load_lds_dwordx4 v[66:67], off sc1
	s_add_u32 m0, s32, 0x5000
	s_nop 0
	global_load_lds_dwordx4 v[70:71], off sc1
	s_add_u32 m0, s32, 0x6000
	s_nop 0
	global_load_lds_dwordx4 v[74:75], off sc1
	s_add_u32 m0, s32, 0x7000
	s_nop 0
	global_load_lds_dwordx4 v[78:79], off sc1
	s_add_u32 m0, s32, 0xc000
	s_nop 0
	global_load_lds_dwordx4 v[68:69], off
	s_add_u32 m0, s32, 0xd000
	s_nop 0
	global_load_lds_dwordx4 v[72:73], off
	s_add_u32 m0, s32, 0xe000
	s_nop 0
	global_load_lds_dwordx4 v[76:77], off
	s_add_u32 m0, s32, 0xf000
	s_nop 0
	global_load_lds_dwordx4 v[80:81], off
	s_waitcnt vmcnt(8)
	s_barrier
	v_mfma_f32_32x32x16_bf16 v[18:33], v[110:113], v[122:125], v[18:33]
	v_mfma_f32_32x32x16_bf16 v[34:49], v[114:117], v[118:121], v[34:49]
	v_mfma_f32_32x32x16_bf16 v[2:17], v[114:117], v[122:125], v[2:17]
	ds_read_b128 v[110:113], v91
	ds_read_b128 v[114:117], v91 offset:4096
	ds_read_b128 v[118:121], v92 offset:32768
	ds_read_b128 v[122:125], v92 offset:36864
	ds_read_b128 v[126:129], v93
	ds_read_b128 v[134:137], v93 offset:4096
	ds_read_b128 v[138:141], v90 offset:32768
	ds_read_b128 v[142:145], v90 offset:36864
	v_mfma_f32_32x32x16_bf16 v[50:65], v[162:165], v[182:185], v[50:65]
	v_mfma_f32_32x32x16_bf16 v[18:33], v[162:165], v[186:189], v[18:33]
	v_mfma_f32_32x32x16_bf16 v[34:49], v[166:169], v[182:185], v[34:49]
	v_mfma_f32_32x32x16_bf16 v[2:17], v[166:169], v[186:189], v[2:17]
	s_waitcnt lgkmcnt(5)
	v_mfma_f32_32x32x16_bf16 v[50:65], v[110:113], v[118:121], v[50:65]
	s_waitcnt lgkmcnt(4)
	v_mfma_f32_32x32x16_bf16 v[18:33], v[110:113], v[122:125], v[18:33]
	v_mfma_f32_32x32x16_bf16 v[34:49], v[114:117], v[118:121], v[34:49]
	v_mfma_f32_32x32x16_bf16 v[2:17], v[114:117], v[122:125], v[2:17]
	ds_read_b128 v[110:113], v89
	ds_read_b128 v[114:117], v89 offset:4096
	ds_read_b128 v[118:121], v88 offset:32768
	ds_read_b128 v[122:125], v88 offset:36864
	s_waitcnt lgkmcnt(5)
	v_mfma_f32_32x32x16_bf16 v[50:65], v[126:129], v[138:141], v[50:65]
	s_waitcnt lgkmcnt(4)
	v_mfma_f32_32x32x16_bf16 v[18:33], v[126:129], v[142:145], v[18:33]
	v_mfma_f32_32x32x16_bf16 v[34:49], v[134:137], v[138:141], v[34:49]
	v_mfma_f32_32x32x16_bf16 v[2:17], v[134:137], v[142:145], v[2:17]
	ds_read_b128 v[126:129], v87
	ds_read_b128 v[134:137], v87 offset:4096
	ds_read_b128 v[138:141], v86 offset:32768
	ds_read_b128 v[142:145], v86 offset:36864
	s_waitcnt vmcnt(0)
	s_waitcnt lgkmcnt(0)
	s_barrier
	ds_read_b128 v[66:69], v91 offset:16384
	ds_read_b128 v[70:73], v91 offset:20480
	ds_read_b128 v[74:77], v92 offset:49152
	ds_read_b128 v[78:81], v92 offset:53248
	ds_read_b128 v[94:97], v93 offset:16384
	ds_read_b128 v[98:101], v93 offset:20480
	ds_read_b128 v[102:105], v90 offset:49152
	ds_read_b128 v[90:93], v90 offset:53248
	v_mfma_f32_32x32x16_bf16 v[50:65], v[110:113], v[118:121], v[50:65]
	v_mfma_f32_32x32x16_bf16 v[18:33], v[110:113], v[122:125], v[18:33]
	v_mfma_f32_32x32x16_bf16 v[34:49], v[114:117], v[118:121], v[34:49]
	v_mfma_f32_32x32x16_bf16 v[2:17], v[114:117], v[122:125], v[2:17]
	v_mfma_f32_32x32x16_bf16 v[50:65], v[126:129], v[138:141], v[50:65]
	v_mfma_f32_32x32x16_bf16 v[18:33], v[126:129], v[142:145], v[18:33]
	v_mfma_f32_32x32x16_bf16 v[34:49], v[134:137], v[138:141], v[34:49]
	v_mfma_f32_32x32x16_bf16 v[2:17], v[134:137], v[142:145], v[2:17]
	s_waitcnt lgkmcnt(5)
	v_mfma_f32_32x32x16_bf16 v[50:65], v[66:69], v[74:77], v[50:65]
	s_waitcnt lgkmcnt(4)
	v_mfma_f32_32x32x16_bf16 v[18:33], v[66:69], v[78:81], v[18:33]
	v_mfma_f32_32x32x16_bf16 v[34:49], v[70:73], v[74:77], v[34:49]
	v_mfma_f32_32x32x16_bf16 v[2:17], v[70:73], v[78:81], v[2:17]
	ds_read_b128 v[66:69], v89 offset:16384
	ds_read_b128 v[70:73], v89 offset:20480
	ds_read_b128 v[74:77], v88 offset:49152
	ds_read_b128 v[78:81], v88 offset:53248
	s_waitcnt lgkmcnt(5)
	v_mfma_f32_32x32x16_bf16 v[50:65], v[94:97], v[102:105], v[50:65]
	s_waitcnt lgkmcnt(4)
	v_mfma_f32_32x32x16_bf16 v[18:33], v[94:97], v[90:93], v[18:33]
	v_mfma_f32_32x32x16_bf16 v[34:49], v[98:101], v[102:105], v[34:49]
	v_mfma_f32_32x32x16_bf16 v[2:17], v[98:101], v[90:93], v[2:17]
	ds_read_b128 v[88:91], v87 offset:16384
	ds_read_b128 v[92:95], v87 offset:20480
	ds_read_b128 v[96:99], v86 offset:49152
	ds_read_b128 v[100:103], v86 offset:53248
	s_lshl_b32 s6, s34, 7
	v_lshl_add_u32 v0, v84, 6, s6
	s_min_i32 s7, s6, 0x4000
	v_lshl_or_b32 v0, v85, 2, v0
	s_movk_i32 s6, 0x4000
	s_waitcnt lgkmcnt(5)
	v_mfma_f32_32x32x16_bf16 v[50:65], v[66:69], v[74:77], v[50:65]
	v_cmp_gt_i32_e32 vcc, s6, v0
	v_readlane_b32 s36, v210, 2
	v_readlane_b32 s40, v210, 6
	s_ashr_i32 s7, s7, 12
	s_add_i32 s7, s7, s70
	s_mul_hi_i32 s8, s7, 0x6000
	s_mulk_i32 s7, 0x6000
	s_waitcnt lgkmcnt(4)
	v_mfma_f32_32x32x16_bf16 v[18:33], v[66:69], v[78:81], v[18:33]
	v_add_u32_e32 v66, 0xffffc000, v0
	v_ashrrev_i32_e32 v67, 31, v0
	v_cndmask_b32_e32 v66, v66, v0, vcc
	v_mov_b32_e32 v0, s95
	v_mov_b32_e32 v68, s89
	v_cndmask_b32_e32 v69, v0, v68, vcc
	v_mov_b32_e32 v0, s94
	v_mov_b32_e32 v68, s88
	v_mfma_f32_32x32x16_bf16 v[34:49], v[70:73], v[74:77], v[34:49]
	v_cndmask_b32_e32 v67, 0, v67, vcc
	v_cndmask_b32_e32 v68, v0, v68, vcc
	v_mov_b32_e32 v0, s40
	v_lshlrev_b64 v[66:67], 12, v[66:67]
	v_lshl_add_u64 v[134:135], v[68:69], 0, v[66:67]
	v_readlane_b32 s37, v210, 3
	v_readlane_b32 s41, v210, 7
	v_mfma_f32_32x32x16_bf16 v[2:17], v[70:73], v[78:81], v[2:17]
	v_mov_b32_e32 v70, s36
	v_cndmask_b32_e32 v0, v0, v70, vcc
	v_cndmask_b32_e64 v68, v68, v0, s[52:53]
	v_lshl_or_b32 v0, v83, 6, v82
	s_add_u32 s7, s90, s7
	v_mov_b32_e32 v70, s41
	v_mov_b32_e32 v71, s37
	v_subrev_u32_e32 v0, s5, v0
	s_addc_u32 s8, s91, s8
	v_cndmask_b32_e32 v70, v70, v71, vcc
	v_add_u32_e32 v168, s3, v0
	s_add_u32 s34, s7, 0x2000
	v_cndmask_b32_e64 v69, v69, v70, s[52:53]
	v_ashrrev_i32_e32 v169, 31, v168
	s_addc_u32 s35, s8, 0
	v_lshl_add_u64 v[66:67], v[68:69], 0, v[66:67]
	v_lshlrev_b64 v[136:137], 2, v[168:169]
	v_lshl_add_u64 v[68:69], s[34:35], 0, v[136:137]
	v_lshl_add_u64 v[66:67], v[66:67], 0, v[136:137]
	s_movk_i32 s8, 0x1000
	s_waitcnt lgkmcnt(0)
	s_barrier
	global_load_dword v0, v[68:69], off
	v_add_co_u32_e32 v68, vcc, s8, v66
	s_movk_i32 s6, 0x2000
	s_nop 0
	v_addc_co_u32_e32 v69, vcc, 0, v67, vcc
	global_load_dword v138, v[66:67], off
	v_add_co_u32_e32 v70, vcc, s6, v66
	v_readlane_b32 s38, v210, 4
	s_nop 0
	v_addc_co_u32_e32 v71, vcc, 0, v67, vcc
	global_load_dword v139, v[70:71], off offset:-4096
	global_load_dword v140, v[70:71], off
	s_movk_i32 s38, 0x3000
	v_add_co_u32_e32 v72, vcc, s38, v66
	s_mov_b32 s7, 0x8000
	s_nop 0
	v_addc_co_u32_e32 v73, vcc, 0, v67, vcc
	global_load_dword v141, v[72:73], off
	v_add_co_u32_e32 v74, vcc, s7, v66
	s_mov_b32 s36, 0x9000
	s_nop 0
	v_addc_co_u32_e32 v75, vcc, 0, v67, vcc
	v_add_co_u32_e32 v76, vcc, s36, v66
	s_mov_b32 s37, 0xa000
	s_nop 0
	v_addc_co_u32_e32 v77, vcc, 0, v67, vcc
	v_add_co_u32_e32 v78, vcc, s37, v66
	s_mov_b32 s5, 0xb000
	s_nop 0
	v_addc_co_u32_e32 v79, vcc, 0, v67, vcc
	global_load_dword v142, v[76:77], off offset:-4096
	global_load_dword v143, v[76:77], off
	v_add_co_u32_e32 v80, vcc, s5, v66
	v_readlane_b32 s39, v210, 5
	s_nop 0
	v_addc_co_u32_e32 v81, vcc, 0, v67, vcc
	v_add_co_u32_e32 v82, vcc, s10, v66
	s_mov_b32 s39, 0x11000
	s_nop 0
	v_addc_co_u32_e32 v83, vcc, 0, v67, vcc
	global_load_dword v144, v[80:81], off offset:-4096
	global_load_dword v145, v[80:81], off
	v_add_co_u32_e32 v84, vcc, s39, v66
	v_mfma_f32_32x32x16_bf16 v[50:65], v[88:91], v[96:99], v[50:65]
	s_nop 0
	v_addc_co_u32_e32 v85, vcc, 0, v67, vcc
	v_add_co_u32_e32 v86, vcc, s62, v66
	global_load_dword v146, v[84:85], off offset:-4096
	global_load_dword v147, v[84:85], off
	v_addc_co_u32_e32 v87, vcc, 0, v67, vcc
	v_mfma_f32_32x32x16_bf16 v[18:33], v[88:91], v[100:103], v[18:33]
	v_add_co_u32_e32 v88, vcc, s57, v66
	v_lshl_add_u64 v[134:135], v[134:135], 0, v[136:137]
	s_nop 0
	v_addc_co_u32_e32 v89, vcc, 0, v67, vcc
	v_add_co_u32_e32 v90, vcc, s54, v66
	v_mfma_f32_32x32x16_bf16 v[34:49], v[92:95], v[96:99], v[34:49]
	s_nop 0
	v_addc_co_u32_e32 v91, vcc, 0, v67, vcc
	global_load_dword v148, v[88:89], off offset:-4096
	global_load_dword v149, v[88:89], off
	s_add_i32 s4, s4, s66
	s_add_i32 s3, s3, s2
	s_cmp_lt_i32 s4, s59
	v_readlane_b32 s42, v210, 8
	v_mfma_f32_32x32x16_bf16 v[2:17], v[92:95], v[100:103], v[2:17]
	v_add_co_u32_e32 v92, vcc, s55, v66
	v_readlane_b32 s43, v210, 9
	s_nop 0
	v_addc_co_u32_e32 v93, vcc, 0, v67, vcc
	v_add_co_u32_e32 v94, vcc, s72, v66
	global_load_dword v150, v[92:93], off offset:-4096
	global_load_dword v151, v[92:93], off
	v_addc_co_u32_e32 v95, vcc, 0, v67, vcc
	v_add_co_u32_e32 v96, vcc, s73, v66
	s_waitcnt vmcnt(13)
	v_fmac_f32_e32 v138, v50, v0
	v_addc_co_u32_e32 v97, vcc, 0, v67, vcc
	v_add_co_u32_e32 v98, vcc, s63, v66
	global_load_dword v152, v[96:97], off offset:-4096
	global_load_dword v153, v[96:97], off
	v_addc_co_u32_e32 v99, vcc, 0, v67, vcc
	v_add_co_u32_e32 v100, vcc, s74, v66
	s_waitcnt vmcnt(14)
	v_fmac_f32_e32 v139, v51, v0
	v_addc_co_u32_e32 v101, vcc, 0, v67, vcc
	v_add_co_u32_e32 v102, vcc, s75, v66
	global_load_dword v154, v[100:101], off offset:-4096
	global_load_dword v155, v[100:101], off
	v_addc_co_u32_e32 v103, vcc, 0, v67, vcc
	v_add_co_u32_e32 v104, vcc, s76, v66
	s_waitcnt vmcnt(15)
	v_fmac_f32_e32 v140, v52, v0
	v_addc_co_u32_e32 v105, vcc, 0, v67, vcc
	v_add_co_u32_e32 v106, vcc, s77, v66
	global_load_dword v156, v[104:105], off offset:-4096
	global_load_dword v157, v[104:105], off
	v_addc_co_u32_e32 v107, vcc, 0, v67, vcc
	v_add_co_u32_e32 v108, vcc, s78, v66
	s_waitcnt vmcnt(16)
	v_fmac_f32_e32 v141, v53, v0
	v_addc_co_u32_e32 v109, vcc, 0, v67, vcc
	v_add_co_u32_e32 v110, vcc, s79, v66
	global_load_dword v158, v[108:109], off offset:-4096
	global_load_dword v159, v[108:109], off
	v_addc_co_u32_e32 v111, vcc, 0, v67, vcc
	v_add_co_u32_e32 v112, vcc, s58, v66
	s_waitcnt vmcnt(17)
	v_fmac_f32_e32 v142, v54, v0
	v_addc_co_u32_e32 v113, vcc, 0, v67, vcc
	v_add_co_u32_e32 v114, vcc, s61, v66
	global_load_dword v160, v[112:113], off offset:-4096
	global_load_dword v161, v[112:113], off
	v_addc_co_u32_e32 v115, vcc, 0, v67, vcc
	v_add_co_u32_e32 v116, vcc, s56, v66
	s_waitcnt vmcnt(18)
	v_fmac_f32_e32 v143, v55, v0
	v_addc_co_u32_e32 v117, vcc, 0, v67, vcc
	v_add_co_u32_e32 v118, vcc, s97, v66
	global_load_dword v162, v[116:117], off offset:-4096
	global_load_dword v163, v[116:117], off
	v_addc_co_u32_e32 v119, vcc, 0, v67, vcc
	v_add_co_u32_e32 v120, vcc, s9, v66
	s_waitcnt vmcnt(19)
	v_fmac_f32_e32 v144, v56, v0
	v_addc_co_u32_e32 v121, vcc, 0, v67, vcc
	v_add_co_u32_e32 v122, vcc, s69, v66
	global_load_dword v164, v[120:121], off offset:-4096
	global_load_dword v165, v[120:121], off
	v_addc_co_u32_e32 v123, vcc, 0, v67, vcc
	v_add_co_u32_e32 v124, vcc, s67, v66
	s_waitcnt vmcnt(20)
	v_fmac_f32_e32 v145, v57, v0
	v_addc_co_u32_e32 v125, vcc, 0, v67, vcc
	v_add_co_u32_e32 v126, vcc, s60, v66
	global_load_dword v166, v[124:125], off offset:-4096
	global_load_dword v167, v[124:125], off
	v_addc_co_u32_e32 v127, vcc, 0, v67, vcc
	v_add_co_u32_e32 v128, vcc, s33, v66
	s_waitcnt vmcnt(21)
	v_fmac_f32_e32 v146, v58, v0
	v_addc_co_u32_e32 v129, vcc, 0, v67, vcc
	global_load_dword v169, v[128:129], off offset:-4096
	global_load_dword v181, v[128:129], off
	v_add_co_u32_e32 v50, vcc, s8, v134
	global_store_dword v[134:135], v138, off
	s_nop 0
	v_addc_co_u32_e32 v51, vcc, 0, v135, vcc
	v_add_co_u32_e32 v136, vcc, s6, v134
	s_waitcnt vmcnt(23)
	v_fmac_f32_e32 v147, v59, v0
	v_addc_co_u32_e32 v137, vcc, 0, v135, vcc
	v_add_co_u32_e32 v52, vcc, s38, v134
	global_store_dword v[136:137], v139, off offset:-4096
	s_nop 0
	v_addc_co_u32_e32 v53, vcc, 0, v135, vcc
	v_add_co_u32_e32 v138, vcc, s7, v134
	global_store_dword v[136:137], v140, off
	s_nop 0
	v_addc_co_u32_e32 v139, vcc, 0, v135, vcc
	v_add_co_u32_e32 v140, vcc, s36, v134
	global_store_dword v[52:53], v141, off
	s_nop 0
	v_addc_co_u32_e32 v141, vcc, 0, v135, vcc
	v_add_co_u32_e32 v54, vcc, s37, v134
	global_store_dword v[140:141], v142, off offset:-4096
	s_nop 0
	v_addc_co_u32_e32 v55, vcc, 0, v135, vcc
	v_add_co_u32_e32 v142, vcc, s5, v134
	global_store_dword v[140:141], v143, off
	s_nop 0
	v_addc_co_u32_e32 v143, vcc, 0, v135, vcc
	v_add_co_u32_e32 v56, vcc, s10, v134
	global_store_dword v[142:143], v144, off offset:-4096
	s_nop 0
	v_addc_co_u32_e32 v57, vcc, 0, v135, vcc
	v_add_co_u32_e32 v144, vcc, s39, v134
	global_store_dword v[142:143], v145, off
	s_nop 0
	v_addc_co_u32_e32 v145, vcc, 0, v135, vcc
	v_add_co_u32_e32 v58, vcc, s62, v134
	global_store_dword v[144:145], v146, off offset:-4096
	s_nop 0
	v_addc_co_u32_e32 v59, vcc, 0, v135, vcc
	v_add_co_u32_e32 v146, vcc, s57, v134
	global_store_dword v[144:145], v147, off
	s_nop 0
	v_addc_co_u32_e32 v147, vcc, 0, v135, vcc
	s_waitcnt vmcnt(31)
	v_fmac_f32_e32 v148, v60, v0
	v_add_co_u32_e32 v60, vcc, s54, v134
	s_waitcnt vmcnt(30)
	v_fmac_f32_e32 v149, v61, v0
	v_addc_co_u32_e32 v61, vcc, 0, v135, vcc
	global_store_dword v[146:147], v148, off offset:-4096
	v_add_co_u32_e32 v148, vcc, s55, v134
	global_store_dword v[146:147], v149, off
	s_nop 0
	v_addc_co_u32_e32 v149, vcc, 0, v135, vcc
	s_waitcnt vmcnt(31)
	v_fmac_f32_e32 v150, v62, v0
	v_add_co_u32_e32 v62, vcc, s72, v134
	s_waitcnt vmcnt(30)
	v_fmac_f32_e32 v151, v63, v0
	v_addc_co_u32_e32 v63, vcc, 0, v135, vcc
	global_store_dword v[148:149], v150, off offset:-4096
	v_add_co_u32_e32 v150, vcc, s73, v134
	global_store_dword v[148:149], v151, off
	s_nop 0
	v_addc_co_u32_e32 v151, vcc, 0, v135, vcc
	s_waitcnt vmcnt(31)
	v_fmac_f32_e32 v152, v64, v0
	v_add_co_u32_e32 v64, vcc, s63, v134
	s_waitcnt vmcnt(30)
	v_fmac_f32_e32 v153, v65, v0
	v_addc_co_u32_e32 v65, vcc, 0, v135, vcc
	global_store_dword v[150:151], v152, off offset:-4096
	v_add_co_u32_e32 v152, vcc, s74, v134
	global_store_dword v[150:151], v153, off
	s_nop 0
	v_addc_co_u32_e32 v153, vcc, 0, v135, vcc
	s_waitcnt vmcnt(31)
	v_fmac_f32_e32 v154, v34, v0
	v_add_co_u32_e32 v34, vcc, s75, v134
	s_waitcnt vmcnt(30)
	v_fmac_f32_e32 v155, v35, v0
	v_addc_co_u32_e32 v35, vcc, 0, v135, vcc
	global_store_dword v[152:153], v154, off offset:-4096
	v_add_co_u32_e32 v154, vcc, s76, v134
	global_store_dword v[152:153], v155, off
	s_nop 0
	v_addc_co_u32_e32 v155, vcc, 0, v135, vcc
	s_waitcnt vmcnt(31)
	v_fmac_f32_e32 v156, v36, v0
	v_add_co_u32_e32 v36, vcc, s77, v134
	s_waitcnt vmcnt(30)
	v_fmac_f32_e32 v157, v37, v0
	v_addc_co_u32_e32 v37, vcc, 0, v135, vcc
	global_store_dword v[154:155], v156, off offset:-4096
	v_add_co_u32_e32 v156, vcc, s78, v134
	global_store_dword v[154:155], v157, off
	s_nop 0
	v_addc_co_u32_e32 v157, vcc, 0, v135, vcc
	s_waitcnt vmcnt(31)
	v_fmac_f32_e32 v158, v38, v0
	v_add_co_u32_e32 v38, vcc, s79, v134
	s_waitcnt vmcnt(30)
	v_fmac_f32_e32 v159, v39, v0
	v_addc_co_u32_e32 v39, vcc, 0, v135, vcc
	global_store_dword v[156:157], v158, off offset:-4096
	v_add_co_u32_e32 v158, vcc, s58, v134
	global_store_dword v[156:157], v159, off
	s_nop 0
	v_addc_co_u32_e32 v159, vcc, 0, v135, vcc
	s_waitcnt vmcnt(31)
	v_fmac_f32_e32 v160, v40, v0
	v_add_co_u32_e32 v40, vcc, s61, v134
	s_waitcnt vmcnt(30)
	v_fmac_f32_e32 v161, v41, v0
	v_addc_co_u32_e32 v41, vcc, 0, v135, vcc
	global_store_dword v[158:159], v160, off offset:-4096
	v_add_co_u32_e32 v160, vcc, s56, v134
	global_store_dword v[158:159], v161, off
	s_nop 0
	v_addc_co_u32_e32 v161, vcc, 0, v135, vcc
	s_waitcnt vmcnt(31)
	v_fmac_f32_e32 v162, v42, v0
	v_add_co_u32_e32 v42, vcc, s97, v134
	s_waitcnt vmcnt(30)
	v_fmac_f32_e32 v163, v43, v0
	v_addc_co_u32_e32 v43, vcc, 0, v135, vcc
	global_store_dword v[160:161], v162, off offset:-4096
	v_add_co_u32_e32 v162, vcc, s9, v134
	global_store_dword v[160:161], v163, off
	s_nop 0
	v_addc_co_u32_e32 v163, vcc, 0, v135, vcc
	s_waitcnt vmcnt(31)
	v_fmac_f32_e32 v164, v44, v0
	v_add_co_u32_e32 v44, vcc, s69, v134
	s_waitcnt vmcnt(30)
	v_fmac_f32_e32 v165, v45, v0
	v_addc_co_u32_e32 v45, vcc, 0, v135, vcc
	global_store_dword v[162:163], v164, off offset:-4096
	v_add_co_u32_e32 v164, vcc, s67, v134
	global_store_dword v[162:163], v165, off
	s_nop 0
	v_addc_co_u32_e32 v165, vcc, 0, v135, vcc
	s_waitcnt vmcnt(31)
	v_fmac_f32_e32 v166, v46, v0
	v_add_co_u32_e32 v46, vcc, s60, v134
	s_waitcnt vmcnt(30)
	v_fmac_f32_e32 v167, v47, v0
	v_addc_co_u32_e32 v47, vcc, 0, v135, vcc
	global_store_dword v[164:165], v166, off offset:-4096
	s_waitcnt vmcnt(30)
	v_fmac_f32_e32 v169, v48, v0
	v_add_co_u32_e32 v166, vcc, s33, v134
	v_add_u32_e32 v48, 32, v168
	global_store_dword v[164:165], v167, off
	v_addc_co_u32_e32 v167, vcc, 0, v135, vcc
	s_waitcnt vmcnt(30)
	v_fmac_f32_e32 v181, v49, v0
	v_ashrrev_i32_e32 v49, 31, v48
	global_store_dword v[166:167], v169, off offset:-4096
	global_store_dword v[166:167], v181, off
	v_lshl_add_u64 v[48:49], v[48:49], 2, s[34:35]
	global_load_dword v0, v[48:49], off
	s_nop 0
	global_load_dword v48, v[66:67], off offset:128
	global_load_dword v49, v[68:69], off offset:128
	s_nop 0
	global_load_dword v66, v[70:71], off offset:128
	global_load_dword v67, v[72:73], off offset:128
	global_load_dword v68, v[74:75], off offset:128
	global_load_dword v69, v[76:77], off offset:128
	s_nop 0
	global_load_dword v70, v[78:79], off offset:128
	global_load_dword v71, v[80:81], off offset:128
	global_load_dword v72, v[82:83], off offset:128
	global_load_dword v73, v[84:85], off offset:128
	global_load_dword v74, v[86:87], off offset:128
	global_load_dword v75, v[88:89], off offset:128
	global_load_dword v76, v[90:91], off offset:128
	global_load_dword v77, v[92:93], off offset:128
	global_load_dword v78, v[94:95], off offset:128
	global_load_dword v79, v[96:97], off offset:128
	global_load_dword v80, v[98:99], off offset:128
	global_load_dword v81, v[100:101], off offset:128
	global_load_dword v82, v[102:103], off offset:128
	global_load_dword v83, v[104:105], off offset:128
	global_load_dword v84, v[106:107], off offset:128
	global_load_dword v85, v[108:109], off offset:128
	global_load_dword v86, v[110:111], off offset:128
	global_load_dword v87, v[112:113], off offset:128
	global_load_dword v88, v[114:115], off offset:128
	global_load_dword v89, v[116:117], off offset:128
	global_load_dword v90, v[118:119], off offset:128
	global_load_dword v91, v[120:121], off offset:128
	global_load_dword v92, v[122:123], off offset:128
	global_load_dword v93, v[124:125], off offset:128
	global_load_dword v94, v[126:127], off offset:128
	global_load_dword v95, v[128:129], off offset:128
	v_readlane_b32 s44, v210, 10
	v_readlane_b32 s45, v210, 11
	v_readlane_b32 s46, v210, 12
	v_readlane_b32 s47, v210, 13
	v_readlane_b32 s48, v210, 14
	v_readlane_b32 s49, v210, 15
	v_readlane_b32 s50, v210, 16
	v_readlane_b32 s51, v210, 17
	s_waitcnt vmcnt(31)
	v_fmac_f32_e32 v48, v18, v0
	s_waitcnt vmcnt(30)
	v_fmac_f32_e32 v49, v19, v0
	s_waitcnt vmcnt(29)
	v_fmac_f32_e32 v66, v20, v0
	s_waitcnt vmcnt(28)
	v_fmac_f32_e32 v67, v21, v0
	s_waitcnt vmcnt(27)
	v_fmac_f32_e32 v68, v22, v0
	s_waitcnt vmcnt(26)
	v_fmac_f32_e32 v69, v23, v0
	s_waitcnt vmcnt(25)
	v_fmac_f32_e32 v70, v24, v0
	s_waitcnt vmcnt(24)
	v_fmac_f32_e32 v71, v25, v0
	s_waitcnt vmcnt(23)
	v_fmac_f32_e32 v72, v26, v0
	s_waitcnt vmcnt(22)
	v_fmac_f32_e32 v73, v27, v0
	s_waitcnt vmcnt(21)
	v_fmac_f32_e32 v74, v28, v0
	s_waitcnt vmcnt(20)
	v_fmac_f32_e32 v75, v29, v0
	s_waitcnt vmcnt(19)
	v_fmac_f32_e32 v76, v30, v0
	s_waitcnt vmcnt(18)
	v_fmac_f32_e32 v77, v31, v0
	s_waitcnt vmcnt(17)
	v_fmac_f32_e32 v78, v32, v0
	s_waitcnt vmcnt(16)
	v_fmac_f32_e32 v79, v33, v0
	s_waitcnt vmcnt(15)
	v_fmac_f32_e32 v80, v2, v0
	s_waitcnt vmcnt(14)
	v_fmac_f32_e32 v81, v3, v0
	s_waitcnt vmcnt(13)
	v_fmac_f32_e32 v82, v4, v0
	s_waitcnt vmcnt(12)
	v_fmac_f32_e32 v83, v5, v0
	s_waitcnt vmcnt(11)
	v_fmac_f32_e32 v84, v6, v0
	s_waitcnt vmcnt(10)
	v_fmac_f32_e32 v85, v7, v0
	s_waitcnt vmcnt(9)
	v_fmac_f32_e32 v86, v8, v0
	s_waitcnt vmcnt(8)
	v_fmac_f32_e32 v87, v9, v0
	s_waitcnt vmcnt(7)
	v_fmac_f32_e32 v88, v10, v0
	s_waitcnt vmcnt(6)
	v_fmac_f32_e32 v89, v11, v0
	s_waitcnt vmcnt(5)
	v_fmac_f32_e32 v90, v12, v0
	s_waitcnt vmcnt(4)
	v_fmac_f32_e32 v91, v13, v0
	s_waitcnt vmcnt(3)
	v_fmac_f32_e32 v92, v14, v0
	s_waitcnt vmcnt(2)
	v_fmac_f32_e32 v93, v15, v0
	s_waitcnt vmcnt(1)
	v_fmac_f32_e32 v94, v16, v0
	s_waitcnt vmcnt(0)
	v_fmac_f32_e32 v95, v17, v0
	global_store_dword v[134:135], v48, off offset:128
	global_store_dword v[50:51], v49, off offset:128
	global_store_dword v[136:137], v66, off offset:128
	global_store_dword v[52:53], v67, off offset:128
	global_store_dword v[138:139], v68, off offset:128
	global_store_dword v[140:141], v69, off offset:128
	global_store_dword v[54:55], v70, off offset:128
	global_store_dword v[142:143], v71, off offset:128
	global_store_dword v[56:57], v72, off offset:128
	global_store_dword v[144:145], v73, off offset:128
	global_store_dword v[58:59], v74, off offset:128
	global_store_dword v[146:147], v75, off offset:128
	global_store_dword v[60:61], v76, off offset:128
	global_store_dword v[148:149], v77, off offset:128
	global_store_dword v[62:63], v78, off offset:128
	global_store_dword v[150:151], v79, off offset:128
	global_store_dword v[64:65], v80, off offset:128
	global_store_dword v[152:153], v81, off offset:128
	global_store_dword v[34:35], v82, off offset:128
	global_store_dword v[154:155], v83, off offset:128
	global_store_dword v[36:37], v84, off offset:128
	global_store_dword v[156:157], v85, off offset:128
	global_store_dword v[38:39], v86, off offset:128
	global_store_dword v[158:159], v87, off offset:128
	global_store_dword v[40:41], v88, off offset:128
	global_store_dword v[160:161], v89, off offset:128
	global_store_dword v[42:43], v90, off offset:128
	global_store_dword v[162:163], v91, off offset:128
	global_store_dword v[44:45], v92, off offset:128
	global_store_dword v[164:165], v93, off offset:128
	global_store_dword v[46:47], v94, off offset:128
	global_store_dword v[166:167], v95, off offset:128
	s_cmpk_lt_i32 s4, 0x400
	s_cbranch_scc1 .LBB0_1186
	s_cmpk_ge_i32 s4, 0x600
	s_cbranch_scc1 .Lph6_done
	s_cmpk_le_i32 s59, 0x400
	s_cbranch_scc1 .Lph6_done
	v_readlane_b32 s5, v209, 2
	s_cmpk_ge_u32 s5, 0x40
	s_cbranch_scc1 .Lph6_done
	s_add_i32 s4, s5, 0x400
	s_lshl_b32 s3, s4, 7
	s_branch .LBB0_1186

.LBB0_1298:
	s_ashr_i32 s6, s5, 31
	s_lshr_b32 s6, s6, 27
	s_add_i32 s6, s5, s6
	s_ashr_i32 s34, s6, 5
	s_ashr_i32 s35, s34, 31
	v_mov_b32_e32 v36, v133
	s_lshl_b64 s[6:7], s[34:35], 18
	s_add_u32 s6, s38, s6
	v_ashrrev_i32_e32 v34, 3, v36
	v_ashrrev_i32_e32 v35, 31, v34
	s_addc_u32 s7, s39, s7
	v_lshlrev_b64 v[2:3], 11, v[34:35]
	v_lshlrev_b32_e32 v0, 4, v36
	v_lshl_add_u64 v[2:3], s[6:7], 0, v[2:3]
	v_and_b32_e32 v0, 0x70, v0
	s_lshl_b32 s6, s34, 12
	v_lshl_add_u64 v[66:67], v[2:3], 0, v[0:1]
	v_subrev_u32_e32 v2, s6, v34
	v_add_u32_e32 v2, s4, v2
	v_ashrrev_i32_e32 v3, 31, v2
	v_lshlrev_b64 v[2:3], 11, v[2:3]
	v_lshl_add_u64 v[2:3], s[0:1], 0, v[2:3]
	v_add_co_u32_e32 v70, vcc, s56, v66
	v_lshl_add_u64 v[68:69], v[2:3], 0, v[0:1]
	s_nop 0
	v_addc_co_u32_e32 v71, vcc, 0, v67, vcc
	v_add_co_u32_e32 v72, vcc, s56, v68
	v_addc_co_u32_e32 v73, vcc, 0, v69, vcc
	v_add_co_u32_e32 v74, vcc, s57, v66
	s_nop 0
	v_addc_co_u32_e32 v75, vcc, 0, v67, vcc
	v_add_co_u32_e32 v76, vcc, s57, v68
	s_nop 0
	v_addc_co_u32_e32 v77, vcc, 0, v69, vcc
	v_add_co_u32_e32 v78, vcc, s58, v66
	s_nop 0
	v_addc_co_u32_e32 v79, vcc, 0, v67, vcc
	v_add_co_u32_e32 v80, vcc, s58, v68
	v_lshlrev_b32_e32 v0, 7, v34
	s_nop 0
	v_addc_co_u32_e32 v81, vcc, 0, v69, vcc
	v_lshrrev_b32_e32 v216, 4, v133
	v_xor_b32_e32 v216, v216, v133
	v_and_b32_e32 v216, 7, v216
	v_lshlrev_b32_e32 v216, 4, v216
	v_mov_b32_e32 v217, 0x70
	v_lshrrev_b32_e32 v218, 6, v133
	v_lshlrev_b32_e32 v218, 10, v218
	s_nop 0
	v_readfirstlane_b32 s32, v218
	v_bfi_b32 v66, v217, v216, v66
	v_bfi_b32 v70, v217, v216, v70
	v_bfi_b32 v74, v217, v216, v74
	v_bfi_b32 v78, v217, v216, v78
	v_bfi_b32 v68, v217, v216, v68
	v_bfi_b32 v72, v217, v216, v72
	v_bfi_b32 v76, v217, v216, v76
	v_bfi_b32 v80, v217, v216, v80
	s_mov_b64 s[98:99], 0x80
	s_add_u32 m0, s32, 0x0
	s_nop 0
	global_load_lds_dwordx4 v[66:67], off sc1
	s_add_u32 m0, s32, 0x1000
	s_nop 0
	global_load_lds_dwordx4 v[70:71], off sc1
	s_add_u32 m0, s32, 0x2000
	s_nop 0
	global_load_lds_dwordx4 v[74:75], off sc1
	s_add_u32 m0, s32, 0x3000
	s_nop 0
	global_load_lds_dwordx4 v[78:79], off sc1
	s_add_u32 m0, s32, 0x8000
	s_nop 0
	global_load_lds_dwordx4 v[68:69], off
	s_add_u32 m0, s32, 0x9000
	s_nop 0
	global_load_lds_dwordx4 v[72:73], off
	s_add_u32 m0, s32, 0xa000
	s_nop 0
	global_load_lds_dwordx4 v[76:77], off
	s_add_u32 m0, s32, 0xb000
	s_nop 0
	global_load_lds_dwordx4 v[80:81], off
	v_lshl_add_u64 v[66:67], v[66:67], 0, s[98:99]
	v_lshl_add_u64 v[70:71], v[70:71], 0, s[98:99]
	v_lshl_add_u64 v[74:75], v[74:75], 0, s[98:99]
	v_lshl_add_u64 v[78:79], v[78:79], 0, s[98:99]
	v_lshl_add_u64 v[68:69], v[68:69], 0, s[98:99]
	v_lshl_add_u64 v[72:73], v[72:73], 0, s[98:99]
	v_lshl_add_u64 v[76:77], v[76:77], 0, s[98:99]
	v_lshl_add_u64 v[80:81], v[80:81], 0, s[98:99]
	s_add_u32 m0, s32, 0x4000
	s_nop 0
	global_load_lds_dwordx4 v[66:67], off sc1
	s_add_u32 m0, s32, 0x5000
	s_nop 0
	global_load_lds_dwordx4 v[70:71], off sc1
	s_add_u32 m0, s32, 0x6000
	s_nop 0
	global_load_lds_dwordx4 v[74:75], off sc1
	s_add_u32 m0, s32, 0x7000
	s_nop 0
	global_load_lds_dwordx4 v[78:79], off sc1
	s_add_u32 m0, s32, 0xc000
	s_nop 0
	global_load_lds_dwordx4 v[68:69], off
	s_add_u32 m0, s32, 0xd000
	s_nop 0
	global_load_lds_dwordx4 v[72:73], off
	s_add_u32 m0, s32, 0xe000
	s_nop 0
	global_load_lds_dwordx4 v[76:77], off
	s_add_u32 m0, s32, 0xf000
	s_nop 0
	global_load_lds_dwordx4 v[80:81], off
	v_lshrrev_b32_e32 v34, 1, v34
	v_xor_b32_e32 v34, v34, v36
	v_lshlrev_b32_e32 v34, 4, v34
	v_and_or_b32 v0, v34, s59, v0
	s_waitcnt vmcnt(26)
	v_and_b32_e32 v82, 31, v36
	v_bfe_u32 v83, v36, 5, 1
	v_ashrrev_i32_e32 v84, 7, v36
	v_bfe_u32 v85, v36, 6, 1
	v_lshl_add_u64 v[66:67], v[66:67], 0, s[98:99]
	v_lshl_add_u64 v[70:71], v[70:71], 0, s[98:99]
	v_lshl_add_u64 v[74:75], v[74:75], 0, s[98:99]
	v_lshl_add_u64 v[78:79], v[78:79], 0, s[98:99]
	v_lshl_add_u64 v[68:69], v[68:69], 0, s[98:99]
	v_lshl_add_u64 v[72:73], v[72:73], 0, s[98:99]
	v_lshl_add_u64 v[76:77], v[76:77], 0, s[98:99]
	v_lshl_add_u64 v[80:81], v[80:81], 0, s[98:99]
	s_waitcnt vmcnt(8)
	s_waitcnt lgkmcnt(0)
	s_barrier
	v_lshrrev_b32_e32 v4, 1, v36
	v_lshlrev_b32_e32 v2, 7, v82
	v_bitop3_b32 v4, v4, v83, 7 bitop3:0x6c
	v_lshl_or_b32 v3, v84, 13, v2
	v_bfe_u32 v5, v36, 1, 3
	v_lshlrev_b32_e32 v4, 4, v4
	v_lshl_or_b32 v2, v85, 13, v2
	v_or_b32_e32 v91, v3, v4
	v_or_b32_e32 v92, v2, v4
	v_bitop3_b32 v4, v83, v5, 2 bitop3:0x36
	v_lshlrev_b32_e32 v4, 4, v4
	v_or_b32_e32 v93, v3, v4
	v_or_b32_e32 v90, v2, v4
	v_bitop3_b32 v4, v83, v5, 4 bitop3:0x36
	v_lshlrev_b32_e32 v4, 4, v4
	v_or_b32_e32 v89, v3, v4
	v_or_b32_e32 v88, v2, v4
	v_bitop3_b32 v4, v83, v5, 6 bitop3:0x36
	v_lshlrev_b32_e32 v4, 4, v4
	v_or_b32_e32 v87, v3, v4
	v_or_b32_e32 v86, v2, v4
	ds_read_b128 v[2:5], v91
	ds_read_b128 v[6:9], v92 offset:32768
	ds_read_b128 v[10:13], v91 offset:4096
	ds_read_b128 v[14:17], v92 offset:36864
	ds_read_b128 v[162:165], v93
	ds_read_b128 v[166:169], v90 offset:32768
	ds_read_b128 v[182:185], v93 offset:4096
	ds_read_b128 v[186:189], v90 offset:36864
	s_waitcnt lgkmcnt(6)
	v_mfma_f32_32x32x16_bf16 v[50:65], v[2:5], v[6:9], 0
	s_waitcnt lgkmcnt(4)
	v_mfma_f32_32x32x16_bf16 v[34:49], v[2:5], v[14:17], 0
	v_mfma_f32_32x32x16_bf16 v[18:33], v[10:13], v[6:9], 0
	v_mfma_f32_32x32x16_bf16 v[2:17], v[10:13], v[14:17], 0
	ds_read_b128 v[190:193], v89
	ds_read_b128 v[194:197], v89 offset:4096
	ds_read_b128 v[198:201], v88 offset:32768
	ds_read_b128 v[202:205], v88 offset:36864
	s_waitcnt lgkmcnt(6)
	v_mfma_f32_32x32x16_bf16 v[50:65], v[162:165], v[166:169], v[50:65]
	s_waitcnt lgkmcnt(4)
	v_mfma_f32_32x32x16_bf16 v[34:49], v[162:165], v[186:189], v[34:49]
	v_mfma_f32_32x32x16_bf16 v[18:33], v[182:185], v[166:169], v[18:33]
	v_mfma_f32_32x32x16_bf16 v[2:17], v[182:185], v[186:189], v[2:17]
	ds_read_b128 v[162:165], v87
	ds_read_b128 v[166:169], v87 offset:4096
	ds_read_b128 v[182:185], v86 offset:32768
	ds_read_b128 v[186:189], v86 offset:36864
	s_waitcnt lgkmcnt(0)
	s_barrier
	s_add_u32 m0, s32, 0x0
	v_mfma_f32_32x32x16_bf16 v[50:65], v[190:193], v[198:201], v[50:65]
	global_load_lds_dwordx4 v[66:67], off sc1
	s_add_u32 m0, s32, 0x1000
	v_mfma_f32_32x32x16_bf16 v[34:49], v[190:193], v[202:205], v[34:49]
	global_load_lds_dwordx4 v[70:71], off sc1
	s_add_u32 m0, s32, 0x2000
	v_mfma_f32_32x32x16_bf16 v[18:33], v[194:197], v[198:201], v[18:33]
	global_load_lds_dwordx4 v[74:75], off sc1
	s_add_u32 m0, s32, 0x3000
	v_mfma_f32_32x32x16_bf16 v[2:17], v[194:197], v[202:205], v[2:17]
	global_load_lds_dwordx4 v[78:79], off sc1
	s_add_u32 m0, s32, 0x8000
	v_mfma_f32_32x32x16_bf16 v[50:65], v[162:165], v[182:185], v[50:65]
	global_load_lds_dwordx4 v[68:69], off
	s_add_u32 m0, s32, 0x9000
	v_mfma_f32_32x32x16_bf16 v[34:49], v[162:165], v[186:189], v[34:49]
	global_load_lds_dwordx4 v[72:73], off
	s_add_u32 m0, s32, 0xa000
	v_mfma_f32_32x32x16_bf16 v[18:33], v[166:169], v[182:185], v[18:33]
	global_load_lds_dwordx4 v[76:77], off
	s_add_u32 m0, s32, 0xb000
	v_mfma_f32_32x32x16_bf16 v[2:17], v[166:169], v[186:189], v[2:17]
	global_load_lds_dwordx4 v[80:81], off
	s_waitcnt vmcnt(8)
	s_barrier
	ds_read_b128 v[162:165], v91 offset:16384
	ds_read_b128 v[166:169], v92 offset:49152
	ds_read_b128 v[182:185], v91 offset:20480
	ds_read_b128 v[186:189], v92 offset:53248
	ds_read_b128 v[190:193], v93 offset:16384
	ds_read_b128 v[194:197], v90 offset:49152
	ds_read_b128 v[198:201], v93 offset:20480
	ds_read_b128 v[202:205], v90 offset:53248
	s_waitcnt lgkmcnt(6)
	v_mfma_f32_32x32x16_bf16 v[50:65], v[162:165], v[166:169], v[50:65]
	s_waitcnt lgkmcnt(4)
	v_mfma_f32_32x32x16_bf16 v[34:49], v[162:165], v[186:189], v[34:49]
	v_mfma_f32_32x32x16_bf16 v[18:33], v[182:185], v[166:169], v[18:33]
	v_mfma_f32_32x32x16_bf16 v[2:17], v[182:185], v[186:189], v[2:17]
	ds_read_b128 v[162:165], v89 offset:16384
	ds_read_b128 v[166:169], v89 offset:20480
	ds_read_b128 v[182:185], v88 offset:49152
	ds_read_b128 v[186:189], v88 offset:53248
	s_waitcnt lgkmcnt(6)
	v_mfma_f32_32x32x16_bf16 v[50:65], v[190:193], v[194:197], v[50:65]
	s_waitcnt lgkmcnt(4)
	v_mfma_f32_32x32x16_bf16 v[34:49], v[190:193], v[202:205], v[34:49]
	v_mfma_f32_32x32x16_bf16 v[18:33], v[198:201], v[194:197], v[18:33]
	v_mfma_f32_32x32x16_bf16 v[2:17], v[198:201], v[202:205], v[2:17]
	ds_read_b128 v[190:193], v87 offset:16384
	ds_read_b128 v[194:197], v87 offset:20480
	ds_read_b128 v[198:201], v86 offset:49152
	ds_read_b128 v[202:205], v86 offset:53248
	v_lshl_add_u64 v[66:67], v[66:67], 0, s[98:99]
	v_lshl_add_u64 v[70:71], v[70:71], 0, s[98:99]
	v_lshl_add_u64 v[74:75], v[74:75], 0, s[98:99]
	v_lshl_add_u64 v[78:79], v[78:79], 0, s[98:99]
	v_lshl_add_u64 v[68:69], v[68:69], 0, s[98:99]
	v_lshl_add_u64 v[72:73], v[72:73], 0, s[98:99]
	v_lshl_add_u64 v[76:77], v[76:77], 0, s[98:99]
	v_lshl_add_u64 v[80:81], v[80:81], 0, s[98:99]
	s_waitcnt lgkmcnt(0)
	s_barrier
	s_add_u32 m0, s32, 0x4000
	v_mfma_f32_32x32x16_bf16 v[50:65], v[162:165], v[182:185], v[50:65]
	global_load_lds_dwordx4 v[66:67], off sc1
	s_add_u32 m0, s32, 0x5000
	v_mfma_f32_32x32x16_bf16 v[34:49], v[162:165], v[186:189], v[34:49]
	global_load_lds_dwordx4 v[70:71], off sc1
	s_add_u32 m0, s32, 0x6000
	v_mfma_f32_32x32x16_bf16 v[18:33], v[166:169], v[182:185], v[18:33]
	global_load_lds_dwordx4 v[74:75], off sc1
	s_add_u32 m0, s32, 0x7000
	v_mfma_f32_32x32x16_bf16 v[2:17], v[166:169], v[186:189], v[2:17]
	global_load_lds_dwordx4 v[78:79], off sc1
	s_add_u32 m0, s32, 0xc000
	v_mfma_f32_32x32x16_bf16 v[50:65], v[190:193], v[198:201], v[50:65]
	global_load_lds_dwordx4 v[68:69], off
	s_add_u32 m0, s32, 0xd000
	v_mfma_f32_32x32x16_bf16 v[34:49], v[190:193], v[202:205], v[34:49]
	global_load_lds_dwordx4 v[72:73], off
	s_add_u32 m0, s32, 0xe000
	v_mfma_f32_32x32x16_bf16 v[18:33], v[194:197], v[198:201], v[18:33]
	global_load_lds_dwordx4 v[76:77], off
	s_add_u32 m0, s32, 0xf000
	v_mfma_f32_32x32x16_bf16 v[2:17], v[194:197], v[202:205], v[2:17]
	global_load_lds_dwordx4 v[80:81], off
	s_waitcnt vmcnt(8)
	s_barrier
	ds_read_b128 v[162:165], v91
	ds_read_b128 v[166:169], v92 offset:32768
	ds_read_b128 v[182:185], v91 offset:4096
	ds_read_b128 v[186:189], v92 offset:36864
	ds_read_b128 v[190:193], v93
	ds_read_b128 v[194:197], v90 offset:32768
	ds_read_b128 v[198:201], v93 offset:4096
	ds_read_b128 v[202:205], v90 offset:36864
	s_waitcnt lgkmcnt(6)
	v_mfma_f32_32x32x16_bf16 v[50:65], v[162:165], v[166:169], v[50:65]
	s_waitcnt lgkmcnt(4)
	v_mfma_f32_32x32x16_bf16 v[34:49], v[162:165], v[186:189], v[34:49]
	v_mfma_f32_32x32x16_bf16 v[18:33], v[182:185], v[166:169], v[18:33]
	v_mfma_f32_32x32x16_bf16 v[2:17], v[182:185], v[186:189], v[2:17]
	ds_read_b128 v[162:165], v89
	ds_read_b128 v[166:169], v89 offset:4096
	ds_read_b128 v[182:185], v88 offset:32768
	ds_read_b128 v[186:189], v88 offset:36864
	s_waitcnt lgkmcnt(6)
	v_mfma_f32_32x32x16_bf16 v[50:65], v[190:193], v[194:197], v[50:65]
	s_waitcnt lgkmcnt(4)
	v_mfma_f32_32x32x16_bf16 v[34:49], v[190:193], v[202:205], v[34:49]
	v_mfma_f32_32x32x16_bf16 v[18:33], v[198:201], v[194:197], v[18:33]
	v_mfma_f32_32x32x16_bf16 v[2:17], v[198:201], v[202:205], v[2:17]
	ds_read_b128 v[190:193], v87
	ds_read_b128 v[194:197], v87 offset:4096
	ds_read_b128 v[198:201], v86 offset:32768
	ds_read_b128 v[202:205], v86 offset:36864
	v_lshl_add_u64 v[66:67], v[66:67], 0, s[98:99]
	v_lshl_add_u64 v[70:71], v[70:71], 0, s[98:99]
	v_lshl_add_u64 v[74:75], v[74:75], 0, s[98:99]
	v_lshl_add_u64 v[78:79], v[78:79], 0, s[98:99]
	v_lshl_add_u64 v[68:69], v[68:69], 0, s[98:99]
	v_lshl_add_u64 v[72:73], v[72:73], 0, s[98:99]
	v_lshl_add_u64 v[76:77], v[76:77], 0, s[98:99]
	v_lshl_add_u64 v[80:81], v[80:81], 0, s[98:99]
	s_waitcnt lgkmcnt(0)
	s_barrier
	s_add_u32 m0, s32, 0x0
	v_mfma_f32_32x32x16_bf16 v[50:65], v[162:165], v[182:185], v[50:65]
	global_load_lds_dwordx4 v[66:67], off sc1
	s_add_u32 m0, s32, 0x1000
	v_mfma_f32_32x32x16_bf16 v[34:49], v[162:165], v[186:189], v[34:49]
	global_load_lds_dwordx4 v[70:71], off sc1
	s_add_u32 m0, s32, 0x2000
	v_mfma_f32_32x32x16_bf16 v[18:33], v[166:169], v[182:185], v[18:33]
	global_load_lds_dwordx4 v[74:75], off sc1
	s_add_u32 m0, s32, 0x3000
	v_mfma_f32_32x32x16_bf16 v[2:17], v[166:169], v[186:189], v[2:17]
	global_load_lds_dwordx4 v[78:79], off sc1
	s_add_u32 m0, s32, 0x8000
	v_mfma_f32_32x32x16_bf16 v[50:65], v[190:193], v[198:201], v[50:65]
	global_load_lds_dwordx4 v[68:69], off
	s_add_u32 m0, s32, 0x9000
	v_mfma_f32_32x32x16_bf16 v[34:49], v[190:193], v[202:205], v[34:49]
	global_load_lds_dwordx4 v[72:73], off
	s_add_u32 m0, s32, 0xa000
	v_mfma_f32_32x32x16_bf16 v[18:33], v[194:197], v[198:201], v[18:33]
	global_load_lds_dwordx4 v[76:77], off
	s_add_u32 m0, s32, 0xb000
	v_mfma_f32_32x32x16_bf16 v[2:17], v[194:197], v[202:205], v[2:17]
	global_load_lds_dwordx4 v[80:81], off
	s_waitcnt vmcnt(8)
	s_barrier
	ds_read_b128 v[162:165], v91 offset:16384
	ds_read_b128 v[166:169], v92 offset:49152
	ds_read_b128 v[182:185], v91 offset:20480
	ds_read_b128 v[186:189], v92 offset:53248
	ds_read_b128 v[190:193], v93 offset:16384
	ds_read_b128 v[194:197], v90 offset:49152
	ds_read_b128 v[198:201], v93 offset:20480
	ds_read_b128 v[202:205], v90 offset:53248
	s_waitcnt lgkmcnt(6)
	v_mfma_f32_32x32x16_bf16 v[50:65], v[162:165], v[166:169], v[50:65]
	s_waitcnt lgkmcnt(4)
	v_mfma_f32_32x32x16_bf16 v[34:49], v[162:165], v[186:189], v[34:49]
	v_mfma_f32_32x32x16_bf16 v[18:33], v[182:185], v[166:169], v[18:33]
	v_mfma_f32_32x32x16_bf16 v[2:17], v[182:185], v[186:189], v[2:17]
	ds_read_b128 v[162:165], v89 offset:16384
	ds_read_b128 v[166:169], v89 offset:20480
	ds_read_b128 v[182:185], v88 offset:49152
	ds_read_b128 v[186:189], v88 offset:53248
	s_waitcnt lgkmcnt(6)
	v_mfma_f32_32x32x16_bf16 v[50:65], v[190:193], v[194:197], v[50:65]
	s_waitcnt lgkmcnt(4)
	v_mfma_f32_32x32x16_bf16 v[34:49], v[190:193], v[202:205], v[34:49]
	v_mfma_f32_32x32x16_bf16 v[18:33], v[198:201], v[194:197], v[18:33]
	v_mfma_f32_32x32x16_bf16 v[2:17], v[198:201], v[202:205], v[2:17]
	ds_read_b128 v[190:193], v87 offset:16384
	ds_read_b128 v[194:197], v87 offset:20480
	ds_read_b128 v[198:201], v86 offset:49152
	ds_read_b128 v[202:205], v86 offset:53248
	v_lshl_add_u64 v[66:67], v[66:67], 0, s[98:99]
	v_lshl_add_u64 v[70:71], v[70:71], 0, s[98:99]
	v_lshl_add_u64 v[74:75], v[74:75], 0, s[98:99]
	v_lshl_add_u64 v[78:79], v[78:79], 0, s[98:99]
	v_lshl_add_u64 v[68:69], v[68:69], 0, s[98:99]
	v_lshl_add_u64 v[72:73], v[72:73], 0, s[98:99]
	v_lshl_add_u64 v[76:77], v[76:77], 0, s[98:99]
	v_lshl_add_u64 v[80:81], v[80:81], 0, s[98:99]
	s_waitcnt lgkmcnt(0)
	s_barrier
	s_add_u32 m0, s32, 0x4000
	v_mfma_f32_32x32x16_bf16 v[50:65], v[162:165], v[182:185], v[50:65]
	global_load_lds_dwordx4 v[66:67], off sc1
	s_add_u32 m0, s32, 0x5000
	v_mfma_f32_32x32x16_bf16 v[34:49], v[162:165], v[186:189], v[34:49]
	global_load_lds_dwordx4 v[70:71], off sc1
	s_add_u32 m0, s32, 0x6000
	v_mfma_f32_32x32x16_bf16 v[18:33], v[166:169], v[182:185], v[18:33]
	global_load_lds_dwordx4 v[74:75], off sc1
	s_add_u32 m0, s32, 0x7000
	v_mfma_f32_32x32x16_bf16 v[2:17], v[166:169], v[186:189], v[2:17]
	global_load_lds_dwordx4 v[78:79], off sc1
	s_add_u32 m0, s32, 0xc000
	v_mfma_f32_32x32x16_bf16 v[50:65], v[190:193], v[198:201], v[50:65]
	global_load_lds_dwordx4 v[68:69], off
	s_add_u32 m0, s32, 0xd000
	v_mfma_f32_32x32x16_bf16 v[34:49], v[190:193], v[202:205], v[34:49]
	global_load_lds_dwordx4 v[72:73], off
	s_add_u32 m0, s32, 0xe000
	v_mfma_f32_32x32x16_bf16 v[18:33], v[194:197], v[198:201], v[18:33]
	global_load_lds_dwordx4 v[76:77], off
	s_add_u32 m0, s32, 0xf000
	v_mfma_f32_32x32x16_bf16 v[2:17], v[194:197], v[202:205], v[2:17]
	global_load_lds_dwordx4 v[80:81], off
	s_waitcnt vmcnt(8)
	s_barrier
	ds_read_b128 v[162:165], v91
	ds_read_b128 v[166:169], v92 offset:32768
	ds_read_b128 v[182:185], v91 offset:4096
	ds_read_b128 v[186:189], v92 offset:36864
	ds_read_b128 v[190:193], v93
	ds_read_b128 v[194:197], v90 offset:32768
	ds_read_b128 v[198:201], v93 offset:4096
	ds_read_b128 v[202:205], v90 offset:36864
	s_waitcnt lgkmcnt(6)
	v_mfma_f32_32x32x16_bf16 v[50:65], v[162:165], v[166:169], v[50:65]
	s_waitcnt lgkmcnt(4)
	v_mfma_f32_32x32x16_bf16 v[34:49], v[162:165], v[186:189], v[34:49]
	v_mfma_f32_32x32x16_bf16 v[18:33], v[182:185], v[166:169], v[18:33]
	v_mfma_f32_32x32x16_bf16 v[2:17], v[182:185], v[186:189], v[2:17]
	ds_read_b128 v[162:165], v89
	ds_read_b128 v[166:169], v89 offset:4096
	ds_read_b128 v[182:185], v88 offset:32768
	ds_read_b128 v[186:189], v88 offset:36864
	s_waitcnt lgkmcnt(6)
	v_mfma_f32_32x32x16_bf16 v[50:65], v[190:193], v[194:197], v[50:65]
	s_waitcnt lgkmcnt(4)
	v_mfma_f32_32x32x16_bf16 v[34:49], v[190:193], v[202:205], v[34:49]
	v_mfma_f32_32x32x16_bf16 v[18:33], v[198:201], v[194:197], v[18:33]
	v_mfma_f32_32x32x16_bf16 v[2:17], v[198:201], v[202:205], v[2:17]
	ds_read_b128 v[190:193], v87
	ds_read_b128 v[194:197], v87 offset:4096
	ds_read_b128 v[198:201], v86 offset:32768
	ds_read_b128 v[202:205], v86 offset:36864
	v_lshl_add_u64 v[66:67], v[66:67], 0, s[98:99]
	v_lshl_add_u64 v[70:71], v[70:71], 0, s[98:99]
	v_lshl_add_u64 v[74:75], v[74:75], 0, s[98:99]
	v_lshl_add_u64 v[78:79], v[78:79], 0, s[98:99]
	v_lshl_add_u64 v[68:69], v[68:69], 0, s[98:99]
	v_lshl_add_u64 v[72:73], v[72:73], 0, s[98:99]
	v_lshl_add_u64 v[76:77], v[76:77], 0, s[98:99]
	v_lshl_add_u64 v[80:81], v[80:81], 0, s[98:99]
	s_waitcnt lgkmcnt(0)
	s_barrier
	s_add_u32 m0, s32, 0x0
	v_mfma_f32_32x32x16_bf16 v[50:65], v[162:165], v[182:185], v[50:65]
	global_load_lds_dwordx4 v[66:67], off sc1
	s_add_u32 m0, s32, 0x1000
	v_mfma_f32_32x32x16_bf16 v[34:49], v[162:165], v[186:189], v[34:49]
	global_load_lds_dwordx4 v[70:71], off sc1
	s_add_u32 m0, s32, 0x2000
	v_mfma_f32_32x32x16_bf16 v[18:33], v[166:169], v[182:185], v[18:33]
	global_load_lds_dwordx4 v[74:75], off sc1
	s_add_u32 m0, s32, 0x3000
	v_mfma_f32_32x32x16_bf16 v[2:17], v[166:169], v[186:189], v[2:17]
	global_load_lds_dwordx4 v[78:79], off sc1
	s_add_u32 m0, s32, 0x8000
	v_mfma_f32_32x32x16_bf16 v[50:65], v[190:193], v[198:201], v[50:65]
	global_load_lds_dwordx4 v[68:69], off
	s_add_u32 m0, s32, 0x9000
	v_mfma_f32_32x32x16_bf16 v[34:49], v[190:193], v[202:205], v[34:49]
	global_load_lds_dwordx4 v[72:73], off
	s_add_u32 m0, s32, 0xa000
	v_mfma_f32_32x32x16_bf16 v[18:33], v[194:197], v[198:201], v[18:33]
	global_load_lds_dwordx4 v[76:77], off
	s_add_u32 m0, s32, 0xb000
	v_mfma_f32_32x32x16_bf16 v[2:17], v[194:197], v[202:205], v[2:17]
	global_load_lds_dwordx4 v[80:81], off
	s_waitcnt vmcnt(8)
	s_barrier
	ds_read_b128 v[162:165], v91 offset:16384
	ds_read_b128 v[166:169], v92 offset:49152
	ds_read_b128 v[182:185], v91 offset:20480
	ds_read_b128 v[186:189], v92 offset:53248
	ds_read_b128 v[190:193], v93 offset:16384
	ds_read_b128 v[194:197], v90 offset:49152
	ds_read_b128 v[198:201], v93 offset:20480
	ds_read_b128 v[202:205], v90 offset:53248
	s_waitcnt lgkmcnt(6)
	v_mfma_f32_32x32x16_bf16 v[50:65], v[162:165], v[166:169], v[50:65]
	s_waitcnt lgkmcnt(4)
	v_mfma_f32_32x32x16_bf16 v[34:49], v[162:165], v[186:189], v[34:49]
	v_mfma_f32_32x32x16_bf16 v[18:33], v[182:185], v[166:169], v[18:33]
	v_mfma_f32_32x32x16_bf16 v[2:17], v[182:185], v[186:189], v[2:17]
	ds_read_b128 v[162:165], v89 offset:16384
	ds_read_b128 v[166:169], v89 offset:20480
	ds_read_b128 v[182:185], v88 offset:49152
	ds_read_b128 v[186:189], v88 offset:53248
	s_waitcnt lgkmcnt(6)
	v_mfma_f32_32x32x16_bf16 v[50:65], v[190:193], v[194:197], v[50:65]
	s_waitcnt lgkmcnt(4)
	v_mfma_f32_32x32x16_bf16 v[34:49], v[190:193], v[202:205], v[34:49]
	v_mfma_f32_32x32x16_bf16 v[18:33], v[198:201], v[194:197], v[18:33]
	v_mfma_f32_32x32x16_bf16 v[2:17], v[198:201], v[202:205], v[2:17]
	ds_read_b128 v[190:193], v87 offset:16384
	ds_read_b128 v[194:197], v87 offset:20480
	ds_read_b128 v[198:201], v86 offset:49152
	ds_read_b128 v[202:205], v86 offset:53248
	v_lshl_add_u64 v[66:67], v[66:67], 0, s[98:99]
	v_lshl_add_u64 v[70:71], v[70:71], 0, s[98:99]
	v_lshl_add_u64 v[74:75], v[74:75], 0, s[98:99]
	v_lshl_add_u64 v[78:79], v[78:79], 0, s[98:99]
	v_lshl_add_u64 v[68:69], v[68:69], 0, s[98:99]
	v_lshl_add_u64 v[72:73], v[72:73], 0, s[98:99]
	v_lshl_add_u64 v[76:77], v[76:77], 0, s[98:99]
	v_lshl_add_u64 v[80:81], v[80:81], 0, s[98:99]
	s_waitcnt lgkmcnt(0)
	s_barrier
	s_add_u32 m0, s32, 0x4000
	v_mfma_f32_32x32x16_bf16 v[50:65], v[162:165], v[182:185], v[50:65]
	global_load_lds_dwordx4 v[66:67], off sc1
	s_add_u32 m0, s32, 0x5000
	v_mfma_f32_32x32x16_bf16 v[34:49], v[162:165], v[186:189], v[34:49]
	global_load_lds_dwordx4 v[70:71], off sc1
	s_add_u32 m0, s32, 0x6000
	v_mfma_f32_32x32x16_bf16 v[18:33], v[166:169], v[182:185], v[18:33]
	global_load_lds_dwordx4 v[74:75], off sc1
	s_add_u32 m0, s32, 0x7000
	v_mfma_f32_32x32x16_bf16 v[2:17], v[166:169], v[186:189], v[2:17]
	global_load_lds_dwordx4 v[78:79], off sc1
	s_add_u32 m0, s32, 0xc000
	v_mfma_f32_32x32x16_bf16 v[50:65], v[190:193], v[198:201], v[50:65]
	global_load_lds_dwordx4 v[68:69], off
	s_add_u32 m0, s32, 0xd000
	v_mfma_f32_32x32x16_bf16 v[34:49], v[190:193], v[202:205], v[34:49]
	global_load_lds_dwordx4 v[72:73], off
	s_add_u32 m0, s32, 0xe000
	v_mfma_f32_32x32x16_bf16 v[18:33], v[194:197], v[198:201], v[18:33]
	global_load_lds_dwordx4 v[76:77], off
	s_add_u32 m0, s32, 0xf000
	v_mfma_f32_32x32x16_bf16 v[2:17], v[194:197], v[202:205], v[2:17]
	global_load_lds_dwordx4 v[80:81], off
	s_waitcnt vmcnt(8)
	s_barrier
	ds_read_b128 v[162:165], v91
	ds_read_b128 v[166:169], v92 offset:32768
	ds_read_b128 v[182:185], v91 offset:4096
	ds_read_b128 v[186:189], v92 offset:36864
	ds_read_b128 v[190:193], v93
	ds_read_b128 v[194:197], v90 offset:32768
	ds_read_b128 v[198:201], v93 offset:4096
	ds_read_b128 v[202:205], v90 offset:36864
	s_waitcnt lgkmcnt(6)
	v_mfma_f32_32x32x16_bf16 v[50:65], v[162:165], v[166:169], v[50:65]
	s_waitcnt lgkmcnt(4)
	v_mfma_f32_32x32x16_bf16 v[34:49], v[162:165], v[186:189], v[34:49]
	v_mfma_f32_32x32x16_bf16 v[18:33], v[182:185], v[166:169], v[18:33]
	v_mfma_f32_32x32x16_bf16 v[2:17], v[182:185], v[186:189], v[2:17]
	ds_read_b128 v[162:165], v89
	ds_read_b128 v[166:169], v89 offset:4096
	ds_read_b128 v[182:185], v88 offset:32768
	ds_read_b128 v[186:189], v88 offset:36864
	s_waitcnt lgkmcnt(6)
	v_mfma_f32_32x32x16_bf16 v[50:65], v[190:193], v[194:197], v[50:65]
	s_waitcnt lgkmcnt(4)
	v_mfma_f32_32x32x16_bf16 v[34:49], v[190:193], v[202:205], v[34:49]
	v_mfma_f32_32x32x16_bf16 v[18:33], v[198:201], v[194:197], v[18:33]
	v_mfma_f32_32x32x16_bf16 v[2:17], v[198:201], v[202:205], v[2:17]
	ds_read_b128 v[190:193], v87
	ds_read_b128 v[194:197], v87 offset:4096
	ds_read_b128 v[198:201], v86 offset:32768
	ds_read_b128 v[202:205], v86 offset:36864
	v_lshl_add_u64 v[66:67], v[66:67], 0, s[98:99]
	v_lshl_add_u64 v[70:71], v[70:71], 0, s[98:99]
	v_lshl_add_u64 v[74:75], v[74:75], 0, s[98:99]
	v_lshl_add_u64 v[78:79], v[78:79], 0, s[98:99]
	v_lshl_add_u64 v[68:69], v[68:69], 0, s[98:99]
	v_lshl_add_u64 v[72:73], v[72:73], 0, s[98:99]
	v_lshl_add_u64 v[76:77], v[76:77], 0, s[98:99]
	v_lshl_add_u64 v[80:81], v[80:81], 0, s[98:99]
	s_waitcnt lgkmcnt(0)
	s_barrier
	s_add_u32 m0, s32, 0x0
	v_mfma_f32_32x32x16_bf16 v[50:65], v[162:165], v[182:185], v[50:65]
	global_load_lds_dwordx4 v[66:67], off sc1
	s_add_u32 m0, s32, 0x1000
	v_mfma_f32_32x32x16_bf16 v[34:49], v[162:165], v[186:189], v[34:49]
	global_load_lds_dwordx4 v[70:71], off sc1
	s_add_u32 m0, s32, 0x2000
	v_mfma_f32_32x32x16_bf16 v[18:33], v[166:169], v[182:185], v[18:33]
	global_load_lds_dwordx4 v[74:75], off sc1
	s_add_u32 m0, s32, 0x3000
	v_mfma_f32_32x32x16_bf16 v[2:17], v[166:169], v[186:189], v[2:17]
	global_load_lds_dwordx4 v[78:79], off sc1
	s_add_u32 m0, s32, 0x8000
	v_mfma_f32_32x32x16_bf16 v[50:65], v[190:193], v[198:201], v[50:65]
	global_load_lds_dwordx4 v[68:69], off
	s_add_u32 m0, s32, 0x9000
	v_mfma_f32_32x32x16_bf16 v[34:49], v[190:193], v[202:205], v[34:49]
	global_load_lds_dwordx4 v[72:73], off
	s_add_u32 m0, s32, 0xa000
	v_mfma_f32_32x32x16_bf16 v[18:33], v[194:197], v[198:201], v[18:33]
	global_load_lds_dwordx4 v[76:77], off
	s_add_u32 m0, s32, 0xb000
	v_mfma_f32_32x32x16_bf16 v[2:17], v[194:197], v[202:205], v[2:17]
	global_load_lds_dwordx4 v[80:81], off
	s_waitcnt vmcnt(8)
	s_barrier
	ds_read_b128 v[162:165], v91 offset:16384
	ds_read_b128 v[166:169], v92 offset:49152
	ds_read_b128 v[182:185], v91 offset:20480
	ds_read_b128 v[186:189], v92 offset:53248
	ds_read_b128 v[190:193], v93 offset:16384
	ds_read_b128 v[194:197], v90 offset:49152
	ds_read_b128 v[198:201], v93 offset:20480
	ds_read_b128 v[202:205], v90 offset:53248
	s_waitcnt lgkmcnt(6)
	v_mfma_f32_32x32x16_bf16 v[50:65], v[162:165], v[166:169], v[50:65]
	s_waitcnt lgkmcnt(4)
	v_mfma_f32_32x32x16_bf16 v[34:49], v[162:165], v[186:189], v[34:49]
	v_mfma_f32_32x32x16_bf16 v[18:33], v[182:185], v[166:169], v[18:33]
	v_mfma_f32_32x32x16_bf16 v[2:17], v[182:185], v[186:189], v[2:17]
	ds_read_b128 v[162:165], v89 offset:16384
	ds_read_b128 v[166:169], v89 offset:20480
	ds_read_b128 v[182:185], v88 offset:49152
	ds_read_b128 v[186:189], v88 offset:53248
	s_waitcnt lgkmcnt(6)
	v_mfma_f32_32x32x16_bf16 v[50:65], v[190:193], v[194:197], v[50:65]
	s_waitcnt lgkmcnt(4)
	v_mfma_f32_32x32x16_bf16 v[34:49], v[190:193], v[202:205], v[34:49]
	v_mfma_f32_32x32x16_bf16 v[18:33], v[198:201], v[194:197], v[18:33]
	v_mfma_f32_32x32x16_bf16 v[2:17], v[198:201], v[202:205], v[2:17]
	ds_read_b128 v[190:193], v87 offset:16384
	ds_read_b128 v[194:197], v87 offset:20480
	ds_read_b128 v[198:201], v86 offset:49152
	ds_read_b128 v[202:205], v86 offset:53248
	v_lshl_add_u64 v[66:67], v[66:67], 0, s[98:99]
	v_lshl_add_u64 v[70:71], v[70:71], 0, s[98:99]
	v_lshl_add_u64 v[74:75], v[74:75], 0, s[98:99]
	v_lshl_add_u64 v[78:79], v[78:79], 0, s[98:99]
	v_lshl_add_u64 v[68:69], v[68:69], 0, s[98:99]
	v_lshl_add_u64 v[72:73], v[72:73], 0, s[98:99]
	v_lshl_add_u64 v[76:77], v[76:77], 0, s[98:99]
	v_lshl_add_u64 v[80:81], v[80:81], 0, s[98:99]
	s_waitcnt lgkmcnt(0)
	s_barrier
	s_add_u32 m0, s32, 0x4000
	v_mfma_f32_32x32x16_bf16 v[50:65], v[162:165], v[182:185], v[50:65]
	global_load_lds_dwordx4 v[66:67], off sc1
	s_add_u32 m0, s32, 0x5000
	v_mfma_f32_32x32x16_bf16 v[34:49], v[162:165], v[186:189], v[34:49]
	global_load_lds_dwordx4 v[70:71], off sc1
	s_add_u32 m0, s32, 0x6000
	v_mfma_f32_32x32x16_bf16 v[18:33], v[166:169], v[182:185], v[18:33]
	global_load_lds_dwordx4 v[74:75], off sc1
	s_add_u32 m0, s32, 0x7000
	v_mfma_f32_32x32x16_bf16 v[2:17], v[166:169], v[186:189], v[2:17]
	global_load_lds_dwordx4 v[78:79], off sc1
	s_add_u32 m0, s32, 0xc000
	v_mfma_f32_32x32x16_bf16 v[50:65], v[190:193], v[198:201], v[50:65]
	global_load_lds_dwordx4 v[68:69], off
	s_add_u32 m0, s32, 0xd000
	v_mfma_f32_32x32x16_bf16 v[34:49], v[190:193], v[202:205], v[34:49]
	global_load_lds_dwordx4 v[72:73], off
	s_add_u32 m0, s32, 0xe000
	v_mfma_f32_32x32x16_bf16 v[18:33], v[194:197], v[198:201], v[18:33]
	global_load_lds_dwordx4 v[76:77], off
	s_add_u32 m0, s32, 0xf000
	v_mfma_f32_32x32x16_bf16 v[2:17], v[194:197], v[202:205], v[2:17]
	global_load_lds_dwordx4 v[80:81], off
	s_waitcnt vmcnt(8)
	s_barrier
	ds_read_b128 v[162:165], v91
	ds_read_b128 v[166:169], v92 offset:32768
	ds_read_b128 v[182:185], v91 offset:4096
	ds_read_b128 v[186:189], v92 offset:36864
	ds_read_b128 v[190:193], v93
	ds_read_b128 v[194:197], v90 offset:32768
	ds_read_b128 v[198:201], v93 offset:4096
	ds_read_b128 v[202:205], v90 offset:36864
	s_waitcnt lgkmcnt(6)
	v_mfma_f32_32x32x16_bf16 v[50:65], v[162:165], v[166:169], v[50:65]
	s_waitcnt lgkmcnt(4)
	v_mfma_f32_32x32x16_bf16 v[34:49], v[162:165], v[186:189], v[34:49]
	v_mfma_f32_32x32x16_bf16 v[18:33], v[182:185], v[166:169], v[18:33]
	v_mfma_f32_32x32x16_bf16 v[2:17], v[182:185], v[186:189], v[2:17]
	ds_read_b128 v[162:165], v89
	ds_read_b128 v[166:169], v89 offset:4096
	ds_read_b128 v[182:185], v88 offset:32768
	ds_read_b128 v[186:189], v88 offset:36864
	s_waitcnt lgkmcnt(6)
	v_mfma_f32_32x32x16_bf16 v[50:65], v[190:193], v[194:197], v[50:65]
	s_waitcnt lgkmcnt(4)
	v_mfma_f32_32x32x16_bf16 v[34:49], v[190:193], v[202:205], v[34:49]
	v_mfma_f32_32x32x16_bf16 v[18:33], v[198:201], v[194:197], v[18:33]
	v_mfma_f32_32x32x16_bf16 v[2:17], v[198:201], v[202:205], v[2:17]
	ds_read_b128 v[190:193], v87
	ds_read_b128 v[194:197], v87 offset:4096
	ds_read_b128 v[198:201], v86 offset:32768
	ds_read_b128 v[202:205], v86 offset:36864
	v_lshl_add_u64 v[66:67], v[66:67], 0, s[98:99]
	v_lshl_add_u64 v[70:71], v[70:71], 0, s[98:99]
	v_lshl_add_u64 v[74:75], v[74:75], 0, s[98:99]
	v_lshl_add_u64 v[78:79], v[78:79], 0, s[98:99]
	v_lshl_add_u64 v[68:69], v[68:69], 0, s[98:99]
	v_lshl_add_u64 v[72:73], v[72:73], 0, s[98:99]
	v_lshl_add_u64 v[76:77], v[76:77], 0, s[98:99]
	v_lshl_add_u64 v[80:81], v[80:81], 0, s[98:99]
	s_waitcnt lgkmcnt(0)
	s_barrier
	s_add_u32 m0, s32, 0x0
	v_mfma_f32_32x32x16_bf16 v[50:65], v[162:165], v[182:185], v[50:65]
	global_load_lds_dwordx4 v[66:67], off sc1
	s_add_u32 m0, s32, 0x1000
	v_mfma_f32_32x32x16_bf16 v[34:49], v[162:165], v[186:189], v[34:49]
	global_load_lds_dwordx4 v[70:71], off sc1
	s_add_u32 m0, s32, 0x2000
	v_mfma_f32_32x32x16_bf16 v[18:33], v[166:169], v[182:185], v[18:33]
	global_load_lds_dwordx4 v[74:75], off sc1
	s_add_u32 m0, s32, 0x3000
	v_mfma_f32_32x32x16_bf16 v[2:17], v[166:169], v[186:189], v[2:17]
	global_load_lds_dwordx4 v[78:79], off sc1
	s_add_u32 m0, s32, 0x8000
	v_mfma_f32_32x32x16_bf16 v[50:65], v[190:193], v[198:201], v[50:65]
	global_load_lds_dwordx4 v[68:69], off
	s_add_u32 m0, s32, 0x9000
	v_mfma_f32_32x32x16_bf16 v[34:49], v[190:193], v[202:205], v[34:49]
	global_load_lds_dwordx4 v[72:73], off
	s_add_u32 m0, s32, 0xa000
	v_mfma_f32_32x32x16_bf16 v[18:33], v[194:197], v[198:201], v[18:33]
	global_load_lds_dwordx4 v[76:77], off
	s_add_u32 m0, s32, 0xb000
	v_mfma_f32_32x32x16_bf16 v[2:17], v[194:197], v[202:205], v[2:17]
	global_load_lds_dwordx4 v[80:81], off
	s_waitcnt vmcnt(8)
	s_barrier
	ds_read_b128 v[162:165], v91 offset:16384
	ds_read_b128 v[166:169], v92 offset:49152
	ds_read_b128 v[182:185], v91 offset:20480
	ds_read_b128 v[186:189], v92 offset:53248
	ds_read_b128 v[190:193], v93 offset:16384
	ds_read_b128 v[194:197], v90 offset:49152
	ds_read_b128 v[198:201], v93 offset:20480
	ds_read_b128 v[202:205], v90 offset:53248
	s_waitcnt lgkmcnt(6)
	v_mfma_f32_32x32x16_bf16 v[50:65], v[162:165], v[166:169], v[50:65]
	s_waitcnt lgkmcnt(4)
	v_mfma_f32_32x32x16_bf16 v[34:49], v[162:165], v[186:189], v[34:49]
	v_mfma_f32_32x32x16_bf16 v[18:33], v[182:185], v[166:169], v[18:33]
	v_mfma_f32_32x32x16_bf16 v[2:17], v[182:185], v[186:189], v[2:17]
	ds_read_b128 v[162:165], v89 offset:16384
	ds_read_b128 v[166:169], v89 offset:20480
	ds_read_b128 v[182:185], v88 offset:49152
	ds_read_b128 v[186:189], v88 offset:53248
	s_waitcnt lgkmcnt(6)
	v_mfma_f32_32x32x16_bf16 v[50:65], v[190:193], v[194:197], v[50:65]
	s_waitcnt lgkmcnt(4)
	v_mfma_f32_32x32x16_bf16 v[34:49], v[190:193], v[202:205], v[34:49]
	v_mfma_f32_32x32x16_bf16 v[18:33], v[198:201], v[194:197], v[18:33]
	v_mfma_f32_32x32x16_bf16 v[2:17], v[198:201], v[202:205], v[2:17]
	ds_read_b128 v[190:193], v87 offset:16384
	ds_read_b128 v[194:197], v87 offset:20480
	ds_read_b128 v[198:201], v86 offset:49152
	ds_read_b128 v[202:205], v86 offset:53248
	v_lshl_add_u64 v[66:67], v[66:67], 0, s[98:99]
	v_lshl_add_u64 v[70:71], v[70:71], 0, s[98:99]
	v_lshl_add_u64 v[74:75], v[74:75], 0, s[98:99]
	v_lshl_add_u64 v[78:79], v[78:79], 0, s[98:99]
	v_lshl_add_u64 v[68:69], v[68:69], 0, s[98:99]
	v_lshl_add_u64 v[72:73], v[72:73], 0, s[98:99]
	v_lshl_add_u64 v[76:77], v[76:77], 0, s[98:99]
	v_lshl_add_u64 v[80:81], v[80:81], 0, s[98:99]
	s_waitcnt lgkmcnt(0)
	s_barrier
	s_add_u32 m0, s32, 0x4000
	v_mfma_f32_32x32x16_bf16 v[50:65], v[162:165], v[182:185], v[50:65]
	global_load_lds_dwordx4 v[66:67], off sc1
	s_add_u32 m0, s32, 0x5000
	v_mfma_f32_32x32x16_bf16 v[34:49], v[162:165], v[186:189], v[34:49]
	global_load_lds_dwordx4 v[70:71], off sc1
	s_add_u32 m0, s32, 0x6000
	v_mfma_f32_32x32x16_bf16 v[18:33], v[166:169], v[182:185], v[18:33]
	global_load_lds_dwordx4 v[74:75], off sc1
	s_add_u32 m0, s32, 0x7000
	v_mfma_f32_32x32x16_bf16 v[2:17], v[166:169], v[186:189], v[2:17]
	global_load_lds_dwordx4 v[78:79], off sc1
	s_add_u32 m0, s32, 0xc000
	v_mfma_f32_32x32x16_bf16 v[50:65], v[190:193], v[198:201], v[50:65]
	global_load_lds_dwordx4 v[68:69], off
	s_add_u32 m0, s32, 0xd000
	v_mfma_f32_32x32x16_bf16 v[34:49], v[190:193], v[202:205], v[34:49]
	global_load_lds_dwordx4 v[72:73], off
	s_add_u32 m0, s32, 0xe000
	v_mfma_f32_32x32x16_bf16 v[18:33], v[194:197], v[198:201], v[18:33]
	global_load_lds_dwordx4 v[76:77], off
	s_add_u32 m0, s32, 0xf000
	v_mfma_f32_32x32x16_bf16 v[2:17], v[194:197], v[202:205], v[2:17]
	global_load_lds_dwordx4 v[80:81], off
	s_waitcnt vmcnt(8)
	s_barrier
	ds_read_b128 v[162:165], v91
	ds_read_b128 v[166:169], v92 offset:32768
	ds_read_b128 v[182:185], v91 offset:4096
	ds_read_b128 v[186:189], v92 offset:36864
	ds_read_b128 v[190:193], v93
	ds_read_b128 v[194:197], v90 offset:32768
	ds_read_b128 v[198:201], v93 offset:4096
	ds_read_b128 v[202:205], v90 offset:36864
	s_waitcnt lgkmcnt(6)
	v_mfma_f32_32x32x16_bf16 v[50:65], v[162:165], v[166:169], v[50:65]
	s_waitcnt lgkmcnt(4)
	v_mfma_f32_32x32x16_bf16 v[34:49], v[162:165], v[186:189], v[34:49]
	v_mfma_f32_32x32x16_bf16 v[18:33], v[182:185], v[166:169], v[18:33]
	v_mfma_f32_32x32x16_bf16 v[2:17], v[182:185], v[186:189], v[2:17]
	ds_read_b128 v[162:165], v89
	ds_read_b128 v[166:169], v89 offset:4096
	ds_read_b128 v[182:185], v88 offset:32768
	ds_read_b128 v[186:189], v88 offset:36864
	s_waitcnt lgkmcnt(6)
	v_mfma_f32_32x32x16_bf16 v[50:65], v[190:193], v[194:197], v[50:65]
	s_waitcnt lgkmcnt(4)
	v_mfma_f32_32x32x16_bf16 v[34:49], v[190:193], v[202:205], v[34:49]
	v_mfma_f32_32x32x16_bf16 v[18:33], v[198:201], v[194:197], v[18:33]
	v_mfma_f32_32x32x16_bf16 v[2:17], v[198:201], v[202:205], v[2:17]
	ds_read_b128 v[190:193], v87
	ds_read_b128 v[194:197], v87 offset:4096
	ds_read_b128 v[198:201], v86 offset:32768
	ds_read_b128 v[202:205], v86 offset:36864
	v_lshl_add_u64 v[66:67], v[66:67], 0, s[98:99]
	v_lshl_add_u64 v[70:71], v[70:71], 0, s[98:99]
	v_lshl_add_u64 v[74:75], v[74:75], 0, s[98:99]
	v_lshl_add_u64 v[78:79], v[78:79], 0, s[98:99]
	v_lshl_add_u64 v[68:69], v[68:69], 0, s[98:99]
	v_lshl_add_u64 v[72:73], v[72:73], 0, s[98:99]
	v_lshl_add_u64 v[76:77], v[76:77], 0, s[98:99]
	v_lshl_add_u64 v[80:81], v[80:81], 0, s[98:99]
	s_waitcnt lgkmcnt(0)
	s_barrier
	s_add_u32 m0, s32, 0x0
	v_mfma_f32_32x32x16_bf16 v[50:65], v[162:165], v[182:185], v[50:65]
	global_load_lds_dwordx4 v[66:67], off sc1
	s_add_u32 m0, s32, 0x1000
	v_mfma_f32_32x32x16_bf16 v[34:49], v[162:165], v[186:189], v[34:49]
	global_load_lds_dwordx4 v[70:71], off sc1
	s_add_u32 m0, s32, 0x2000
	v_mfma_f32_32x32x16_bf16 v[18:33], v[166:169], v[182:185], v[18:33]
	global_load_lds_dwordx4 v[74:75], off sc1
	s_add_u32 m0, s32, 0x3000
	v_mfma_f32_32x32x16_bf16 v[2:17], v[166:169], v[186:189], v[2:17]
	global_load_lds_dwordx4 v[78:79], off sc1
	s_add_u32 m0, s32, 0x8000
	v_mfma_f32_32x32x16_bf16 v[50:65], v[190:193], v[198:201], v[50:65]
	global_load_lds_dwordx4 v[68:69], off
	s_add_u32 m0, s32, 0x9000
	v_mfma_f32_32x32x16_bf16 v[34:49], v[190:193], v[202:205], v[34:49]
	global_load_lds_dwordx4 v[72:73], off
	s_add_u32 m0, s32, 0xa000
	v_mfma_f32_32x32x16_bf16 v[18:33], v[194:197], v[198:201], v[18:33]
	global_load_lds_dwordx4 v[76:77], off
	s_add_u32 m0, s32, 0xb000
	v_mfma_f32_32x32x16_bf16 v[2:17], v[194:197], v[202:205], v[2:17]
	global_load_lds_dwordx4 v[80:81], off
	s_waitcnt vmcnt(8)
	s_barrier
	ds_read_b128 v[162:165], v91 offset:16384
	ds_read_b128 v[166:169], v92 offset:49152
	ds_read_b128 v[182:185], v91 offset:20480
	ds_read_b128 v[186:189], v92 offset:53248
	ds_read_b128 v[190:193], v93 offset:16384
	ds_read_b128 v[194:197], v90 offset:49152
	ds_read_b128 v[198:201], v93 offset:20480
	ds_read_b128 v[202:205], v90 offset:53248
	s_waitcnt lgkmcnt(6)
	v_mfma_f32_32x32x16_bf16 v[50:65], v[162:165], v[166:169], v[50:65]
	s_waitcnt lgkmcnt(4)
	v_mfma_f32_32x32x16_bf16 v[34:49], v[162:165], v[186:189], v[34:49]
	v_mfma_f32_32x32x16_bf16 v[18:33], v[182:185], v[166:169], v[18:33]
	v_mfma_f32_32x32x16_bf16 v[2:17], v[182:185], v[186:189], v[2:17]
	ds_read_b128 v[162:165], v89 offset:16384
	ds_read_b128 v[166:169], v89 offset:20480
	ds_read_b128 v[182:185], v88 offset:49152
	ds_read_b128 v[186:189], v88 offset:53248
	s_waitcnt lgkmcnt(6)
	v_mfma_f32_32x32x16_bf16 v[50:65], v[190:193], v[194:197], v[50:65]
	s_waitcnt lgkmcnt(4)
	v_mfma_f32_32x32x16_bf16 v[34:49], v[190:193], v[202:205], v[34:49]
	v_mfma_f32_32x32x16_bf16 v[18:33], v[198:201], v[194:197], v[18:33]
	v_mfma_f32_32x32x16_bf16 v[2:17], v[198:201], v[202:205], v[2:17]
	ds_read_b128 v[190:193], v87 offset:16384
	ds_read_b128 v[194:197], v87 offset:20480
	ds_read_b128 v[198:201], v86 offset:49152
	ds_read_b128 v[202:205], v86 offset:53248
	v_lshl_add_u64 v[66:67], v[66:67], 0, s[98:99]
	v_lshl_add_u64 v[70:71], v[70:71], 0, s[98:99]
	v_lshl_add_u64 v[74:75], v[74:75], 0, s[98:99]
	v_lshl_add_u64 v[78:79], v[78:79], 0, s[98:99]
	v_lshl_add_u64 v[68:69], v[68:69], 0, s[98:99]
	v_lshl_add_u64 v[72:73], v[72:73], 0, s[98:99]
	v_lshl_add_u64 v[76:77], v[76:77], 0, s[98:99]
	v_lshl_add_u64 v[80:81], v[80:81], 0, s[98:99]
	s_waitcnt lgkmcnt(0)
	s_barrier
	s_add_u32 m0, s32, 0x4000
	v_mfma_f32_32x32x16_bf16 v[50:65], v[162:165], v[182:185], v[50:65]
	global_load_lds_dwordx4 v[66:67], off sc1
	s_add_u32 m0, s32, 0x5000
	v_mfma_f32_32x32x16_bf16 v[34:49], v[162:165], v[186:189], v[34:49]
	global_load_lds_dwordx4 v[70:71], off sc1
	s_add_u32 m0, s32, 0x6000
	v_mfma_f32_32x32x16_bf16 v[18:33], v[166:169], v[182:185], v[18:33]
	global_load_lds_dwordx4 v[74:75], off sc1
	s_add_u32 m0, s32, 0x7000
	v_mfma_f32_32x32x16_bf16 v[2:17], v[166:169], v[186:189], v[2:17]
	global_load_lds_dwordx4 v[78:79], off sc1
	s_add_u32 m0, s32, 0xc000
	v_mfma_f32_32x32x16_bf16 v[50:65], v[190:193], v[198:201], v[50:65]
	global_load_lds_dwordx4 v[68:69], off
	s_add_u32 m0, s32, 0xd000
	v_mfma_f32_32x32x16_bf16 v[34:49], v[190:193], v[202:205], v[34:49]
	global_load_lds_dwordx4 v[72:73], off
	s_add_u32 m0, s32, 0xe000
	v_mfma_f32_32x32x16_bf16 v[18:33], v[194:197], v[198:201], v[18:33]
	global_load_lds_dwordx4 v[76:77], off
	s_add_u32 m0, s32, 0xf000
	v_mfma_f32_32x32x16_bf16 v[2:17], v[194:197], v[202:205], v[2:17]
	global_load_lds_dwordx4 v[80:81], off
	s_waitcnt vmcnt(8)
	s_barrier
	ds_read_b128 v[162:165], v91
	ds_read_b128 v[166:169], v92 offset:32768
	ds_read_b128 v[182:185], v91 offset:4096
	ds_read_b128 v[186:189], v92 offset:36864
	ds_read_b128 v[190:193], v93
	ds_read_b128 v[194:197], v90 offset:32768
	ds_read_b128 v[198:201], v93 offset:4096
	ds_read_b128 v[202:205], v90 offset:36864
	s_waitcnt lgkmcnt(6)
	v_mfma_f32_32x32x16_bf16 v[50:65], v[162:165], v[166:169], v[50:65]
	s_waitcnt lgkmcnt(4)
	v_mfma_f32_32x32x16_bf16 v[34:49], v[162:165], v[186:189], v[34:49]
	v_mfma_f32_32x32x16_bf16 v[18:33], v[182:185], v[166:169], v[18:33]
	v_mfma_f32_32x32x16_bf16 v[2:17], v[182:185], v[186:189], v[2:17]
	ds_read_b128 v[162:165], v89
	ds_read_b128 v[166:169], v89 offset:4096
	ds_read_b128 v[182:185], v88 offset:32768
	ds_read_b128 v[186:189], v88 offset:36864
	s_waitcnt lgkmcnt(6)
	v_mfma_f32_32x32x16_bf16 v[50:65], v[190:193], v[194:197], v[50:65]
	s_waitcnt lgkmcnt(4)
	v_mfma_f32_32x32x16_bf16 v[34:49], v[190:193], v[202:205], v[34:49]
	v_mfma_f32_32x32x16_bf16 v[18:33], v[198:201], v[194:197], v[18:33]
	v_mfma_f32_32x32x16_bf16 v[2:17], v[198:201], v[202:205], v[2:17]
	ds_read_b128 v[190:193], v87
	ds_read_b128 v[194:197], v87 offset:4096
	ds_read_b128 v[198:201], v86 offset:32768
	ds_read_b128 v[202:205], v86 offset:36864
	v_lshl_add_u64 v[66:67], v[66:67], 0, s[98:99]
	v_lshl_add_u64 v[70:71], v[70:71], 0, s[98:99]
	v_lshl_add_u64 v[74:75], v[74:75], 0, s[98:99]
	v_lshl_add_u64 v[78:79], v[78:79], 0, s[98:99]
	v_lshl_add_u64 v[68:69], v[68:69], 0, s[98:99]
	v_lshl_add_u64 v[72:73], v[72:73], 0, s[98:99]
	v_lshl_add_u64 v[76:77], v[76:77], 0, s[98:99]
	v_lshl_add_u64 v[80:81], v[80:81], 0, s[98:99]
	s_waitcnt lgkmcnt(0)
	s_barrier
	s_add_u32 m0, s32, 0x0
	s_nop 0
	global_load_lds_dwordx4 v[66:67], off sc1
	s_add_u32 m0, s32, 0x1000
	s_nop 0
	global_load_lds_dwordx4 v[70:71], off sc1
	s_add_u32 m0, s32, 0x2000
	s_nop 0
	global_load_lds_dwordx4 v[74:75], off sc1
	s_add_u32 m0, s32, 0x3000
	s_nop 0
	global_load_lds_dwordx4 v[78:79], off sc1
	s_add_u32 m0, s32, 0x8000
	s_nop 0
	global_load_lds_dwordx4 v[68:69], off
	s_add_u32 m0, s32, 0x9000
	s_nop 0
	global_load_lds_dwordx4 v[72:73], off
	s_add_u32 m0, s32, 0xa000
	s_nop 0
	global_load_lds_dwordx4 v[76:77], off
	s_add_u32 m0, s32, 0xb000
	s_nop 0
	global_load_lds_dwordx4 v[80:81], off
	s_waitcnt vmcnt(8)
	s_barrier
	s_nop 0
	s_nop 0
	s_nop 0
	s_nop 0
	s_nop 0
	s_nop 0
	s_nop 0
	v_mfma_f32_32x32x16_bf16 v[50:65], v[162:165], v[182:185], v[50:65]
	v_mfma_f32_32x32x16_bf16 v[34:49], v[162:165], v[186:189], v[34:49]
	v_mfma_f32_32x32x16_bf16 v[18:33], v[166:169], v[182:185], v[18:33]
	v_mfma_f32_32x32x16_bf16 v[2:17], v[166:169], v[186:189], v[2:17]
	ds_read_b128 v[110:113], v91 offset:16384
	ds_read_b128 v[114:117], v91 offset:20480
	ds_read_b128 v[118:121], v92 offset:49152
	ds_read_b128 v[122:125], v92 offset:53248
	ds_read_b128 v[162:165], v93 offset:16384
	ds_read_b128 v[166:169], v93 offset:20480
	ds_read_b128 v[182:185], v90 offset:49152
	ds_read_b128 v[186:189], v90 offset:53248
	v_mfma_f32_32x32x16_bf16 v[50:65], v[190:193], v[198:201], v[50:65]
	v_mfma_f32_32x32x16_bf16 v[34:49], v[190:193], v[202:205], v[34:49]
	v_mfma_f32_32x32x16_bf16 v[18:33], v[194:197], v[198:201], v[18:33]
	v_mfma_f32_32x32x16_bf16 v[2:17], v[194:197], v[202:205], v[2:17]
	s_waitcnt lgkmcnt(5)
	v_mfma_f32_32x32x16_bf16 v[50:65], v[110:113], v[118:121], v[50:65]
	s_waitcnt lgkmcnt(4)
	v_mfma_f32_32x32x16_bf16 v[34:49], v[110:113], v[122:125], v[34:49]
	v_mfma_f32_32x32x16_bf16 v[18:33], v[114:117], v[118:121], v[18:33]
	v_mfma_f32_32x32x16_bf16 v[2:17], v[114:117], v[122:125], v[2:17]
	ds_read_b128 v[110:113], v89 offset:16384
	ds_read_b128 v[114:117], v89 offset:20480
	ds_read_b128 v[118:121], v88 offset:49152
	ds_read_b128 v[122:125], v88 offset:53248
	s_waitcnt lgkmcnt(5)
	v_mfma_f32_32x32x16_bf16 v[50:65], v[162:165], v[182:185], v[50:65]
	s_waitcnt lgkmcnt(4)
	v_mfma_f32_32x32x16_bf16 v[34:49], v[162:165], v[186:189], v[34:49]
	v_mfma_f32_32x32x16_bf16 v[18:33], v[166:169], v[182:185], v[18:33]
	v_mfma_f32_32x32x16_bf16 v[2:17], v[166:169], v[186:189], v[2:17]
	ds_read_b128 v[162:165], v87 offset:16384
	ds_read_b128 v[166:169], v87 offset:20480
	ds_read_b128 v[182:185], v86 offset:49152
	ds_read_b128 v[186:189], v86 offset:53248
	s_waitcnt lgkmcnt(5)
	v_mfma_f32_32x32x16_bf16 v[50:65], v[110:113], v[118:121], v[50:65]
	v_lshl_add_u64 v[66:67], v[66:67], 0, s[98:99]
	v_lshl_add_u64 v[70:71], v[70:71], 0, s[98:99]
	v_lshl_add_u64 v[74:75], v[74:75], 0, s[98:99]
	v_lshl_add_u64 v[78:79], v[78:79], 0, s[98:99]
	v_lshl_add_u64 v[68:69], v[68:69], 0, s[98:99]
	v_lshl_add_u64 v[72:73], v[72:73], 0, s[98:99]
	v_lshl_add_u64 v[76:77], v[76:77], 0, s[98:99]
	v_lshl_add_u64 v[80:81], v[80:81], 0, s[98:99]
	s_waitcnt lgkmcnt(0)
	s_barrier
	s_add_u32 m0, s32, 0x4000
	s_nop 0
	global_load_lds_dwordx4 v[66:67], off sc1
	s_add_u32 m0, s32, 0x5000
	s_nop 0
	global_load_lds_dwordx4 v[70:71], off sc1
	s_add_u32 m0, s32, 0x6000
	s_nop 0
	global_load_lds_dwordx4 v[74:75], off sc1
	s_add_u32 m0, s32, 0x7000
	s_nop 0
	global_load_lds_dwordx4 v[78:79], off sc1
	s_add_u32 m0, s32, 0xc000
	s_nop 0
	global_load_lds_dwordx4 v[68:69], off
	s_add_u32 m0, s32, 0xd000
	s_nop 0
	global_load_lds_dwordx4 v[72:73], off
	s_add_u32 m0, s32, 0xe000
	s_nop 0
	global_load_lds_dwordx4 v[76:77], off
	s_add_u32 m0, s32, 0xf000
	s_nop 0
	global_load_lds_dwordx4 v[80:81], off
	s_waitcnt vmcnt(8)
	s_barrier
	v_mfma_f32_32x32x16_bf16 v[34:49], v[110:113], v[122:125], v[34:49]
	v_mfma_f32_32x32x16_bf16 v[18:33], v[114:117], v[118:121], v[18:33]
	v_mfma_f32_32x32x16_bf16 v[2:17], v[114:117], v[122:125], v[2:17]
	ds_read_b128 v[110:113], v91
	ds_read_b128 v[114:117], v91 offset:4096
	ds_read_b128 v[118:121], v92 offset:32768
	ds_read_b128 v[122:125], v92 offset:36864
	ds_read_b128 v[126:129], v93
	ds_read_b128 v[134:137], v93 offset:4096
	ds_read_b128 v[138:141], v90 offset:32768
	ds_read_b128 v[142:145], v90 offset:36864
	v_mfma_f32_32x32x16_bf16 v[50:65], v[162:165], v[182:185], v[50:65]
	v_mfma_f32_32x32x16_bf16 v[34:49], v[162:165], v[186:189], v[34:49]
	v_mfma_f32_32x32x16_bf16 v[18:33], v[166:169], v[182:185], v[18:33]
	v_mfma_f32_32x32x16_bf16 v[2:17], v[166:169], v[186:189], v[2:17]
	s_waitcnt lgkmcnt(5)
	v_mfma_f32_32x32x16_bf16 v[50:65], v[110:113], v[118:121], v[50:65]
	s_waitcnt lgkmcnt(4)
	v_mfma_f32_32x32x16_bf16 v[34:49], v[110:113], v[122:125], v[34:49]
	v_mfma_f32_32x32x16_bf16 v[18:33], v[114:117], v[118:121], v[18:33]
	v_mfma_f32_32x32x16_bf16 v[2:17], v[114:117], v[122:125], v[2:17]
	ds_read_b128 v[110:113], v89
	ds_read_b128 v[114:117], v89 offset:4096
	ds_read_b128 v[118:121], v88 offset:32768
	ds_read_b128 v[122:125], v88 offset:36864
	s_waitcnt lgkmcnt(5)
	v_mfma_f32_32x32x16_bf16 v[50:65], v[126:129], v[138:141], v[50:65]
	s_waitcnt lgkmcnt(4)
	v_mfma_f32_32x32x16_bf16 v[34:49], v[126:129], v[142:145], v[34:49]
	v_mfma_f32_32x32x16_bf16 v[18:33], v[134:137], v[138:141], v[18:33]
	v_mfma_f32_32x32x16_bf16 v[2:17], v[134:137], v[142:145], v[2:17]
	ds_read_b128 v[126:129], v87
	ds_read_b128 v[134:137], v87 offset:4096
	ds_read_b128 v[138:141], v86 offset:32768
	ds_read_b128 v[142:145], v86 offset:36864
	s_waitcnt vmcnt(0)
	s_waitcnt lgkmcnt(0)
	s_barrier
	ds_read_b128 v[66:69], v91 offset:16384
	ds_read_b128 v[70:73], v91 offset:20480
	ds_read_b128 v[74:77], v92 offset:49152
	ds_read_b128 v[78:81], v92 offset:53248
	ds_read_b128 v[94:97], v93 offset:16384
	ds_read_b128 v[98:101], v93 offset:20480
	ds_read_b128 v[102:105], v90 offset:49152
	ds_read_b128 v[90:93], v90 offset:53248
	v_mfma_f32_32x32x16_bf16 v[50:65], v[110:113], v[118:121], v[50:65]
	v_mfma_f32_32x32x16_bf16 v[34:49], v[110:113], v[122:125], v[34:49]
	v_mfma_f32_32x32x16_bf16 v[18:33], v[114:117], v[118:121], v[18:33]
	v_mfma_f32_32x32x16_bf16 v[2:17], v[114:117], v[122:125], v[2:17]
	v_mfma_f32_32x32x16_bf16 v[50:65], v[126:129], v[138:141], v[50:65]
	v_mfma_f32_32x32x16_bf16 v[34:49], v[126:129], v[142:145], v[34:49]
	v_mfma_f32_32x32x16_bf16 v[18:33], v[134:137], v[138:141], v[18:33]
	v_mfma_f32_32x32x16_bf16 v[2:17], v[134:137], v[142:145], v[2:17]
	s_waitcnt lgkmcnt(5)
	v_mfma_f32_32x32x16_bf16 v[50:65], v[66:69], v[74:77], v[50:65]
	s_waitcnt lgkmcnt(4)
	v_mfma_f32_32x32x16_bf16 v[34:49], v[66:69], v[78:81], v[34:49]
	v_mfma_f32_32x32x16_bf16 v[18:33], v[70:73], v[74:77], v[18:33]
	v_mfma_f32_32x32x16_bf16 v[2:17], v[70:73], v[78:81], v[2:17]
	ds_read_b128 v[66:69], v89 offset:16384
	ds_read_b128 v[70:73], v89 offset:20480
	ds_read_b128 v[74:77], v88 offset:49152
	ds_read_b128 v[78:81], v88 offset:53248
	s_waitcnt lgkmcnt(5)
	v_mfma_f32_32x32x16_bf16 v[50:65], v[94:97], v[102:105], v[50:65]
	s_waitcnt lgkmcnt(4)
	v_mfma_f32_32x32x16_bf16 v[34:49], v[94:97], v[90:93], v[34:49]
	v_mfma_f32_32x32x16_bf16 v[18:33], v[98:101], v[102:105], v[18:33]
	v_mfma_f32_32x32x16_bf16 v[2:17], v[98:101], v[90:93], v[2:17]
	ds_read_b128 v[88:91], v87 offset:16384
	ds_read_b128 v[92:95], v87 offset:20480
	ds_read_b128 v[96:99], v86 offset:49152
	ds_read_b128 v[100:103], v86 offset:53248
	s_waitcnt lgkmcnt(5)
	v_mfma_f32_32x32x16_bf16 v[50:65], v[66:69], v[74:77], v[50:65]
	v_lshlrev_b32_e32 v0, 6, v85
	v_lshlrev_b32_e32 v84, 6, v84
	v_subrev_u32_e32 v0, s6, v0
	v_add_u32_e32 v0, s4, v0
	v_ashrrev_i32_e32 v0, 6, v0
	v_lshlrev_b32_e32 v85, 2, v83
	s_waitcnt lgkmcnt(0)
	v_mfma_f32_32x32x16_bf16 v[50:65], v[88:91], v[96:99], v[50:65]
	s_barrier
	v_or_b32_e32 v83, 2, v84
	v_or_b32_e32 v86, 3, v84
	v_or_b32_e32 v87, 8, v85
	s_add_i32 s5, s5, s66
	s_add_i32 s4, s4, s3
	v_mfma_f32_32x32x16_bf16 v[34:49], v[66:69], v[78:81], v[34:49]
	v_lshl_add_u32 v66, s34, 7, v84
	v_ashrrev_i32_e32 v66, 1, v66
	v_and_b32_e32 v66, 0xffffffc0, v66
	v_add_u32_e32 v66, v66, v0
	v_ashrrev_i32_e32 v67, 31, v66
	v_lshlrev_b64 v[66:67], 14, v[66:67]
	v_lshl_add_u64 v[66:67], s[50:51], 0, v[66:67]
	v_lshlrev_b32_e32 v0, 1, v82
	v_lshl_add_u64 v[66:67], v[66:67], 0, v[0:1]
	v_max_f32_e32 v0, v50, v50
	v_max_f32_e32 v0, 0, v0
	v_or_b32_e32 v68, v85, v84
	v_mul_f32_e32 v0, v0, v0
	v_cvt_pk_bf16_f32 v50, v0, s0
	v_lshlrev_b32_e32 v0, 7, v68
	v_and_b32_e32 v0, 0x2200, v0
	v_lshl_add_u64 v[68:69], v[66:67], 0, v[0:1]
	v_or_b32_e32 v82, 1, v84
	global_store_short v[68:69], v50, off
	v_or_b32_e32 v0, v85, v82
	v_max_f32_e32 v50, v51, v51
	v_max_f32_e32 v50, 0, v50
	v_lshlrev_b32_e32 v0, 7, v0
	v_mul_f32_e32 v50, v50, v50
	v_and_b32_e32 v0, 0x2280, v0
	v_mfma_f32_32x32x16_bf16 v[18:33], v[70:73], v[74:77], v[18:33]
	v_max_f32_e32 v52, v52, v52
	v_max_f32_e32 v52, 0, v52
	v_mul_f32_e32 v52, v52, v52
	v_cvt_pk_bf16_f32 v52, v52, s0
	v_max_f32_e32 v54, v54, v54
	v_max_f32_e32 v54, 0, v54
	v_mul_f32_e32 v54, v54, v54
	v_mfma_f32_32x32x16_bf16 v[2:17], v[70:73], v[78:81], v[2:17]
	v_cvt_pk_bf16_f32 v70, v50, s0
	v_lshl_add_u64 v[50:51], v[66:67], 0, v[0:1]
	v_or_b32_e32 v0, v85, v83
	v_lshlrev_b32_e32 v0, 7, v0
	v_and_b32_e32 v0, 0x2300, v0
	global_store_short v[50:51], v70, off
	v_lshl_add_u64 v[70:71], v[66:67], 0, v[0:1]
	global_store_short v[70:71], v52, off
	v_or_b32_e32 v0, v85, v86
	v_max_f32_e32 v52, v53, v53
	v_max_f32_e32 v52, 0, v52
	v_lshlrev_b32_e32 v0, 7, v0
	v_mul_f32_e32 v52, v52, v52
	v_and_b32_e32 v0, 0x2380, v0
	v_cvt_pk_bf16_f32 v72, v52, s0
	v_lshl_add_u64 v[52:53], v[66:67], 0, v[0:1]
	v_or_b32_e32 v0, v87, v84
	v_lshlrev_b32_e32 v0, 7, v0
	v_and_b32_e32 v0, 0x2600, v0
	global_store_short v[52:53], v72, off
	v_cvt_pk_bf16_f32 v54, v54, s0
	v_lshl_add_u64 v[72:73], v[66:67], 0, v[0:1]
	global_store_short v[72:73], v54, off
	v_or_b32_e32 v0, v87, v82
	v_max_f32_e32 v54, v55, v55
	v_max_f32_e32 v54, 0, v54
	v_lshlrev_b32_e32 v0, 7, v0
	v_mul_f32_e32 v54, v54, v54
	v_and_b32_e32 v0, 0x2680, v0
	v_cvt_pk_bf16_f32 v74, v54, s0
	v_lshl_add_u64 v[54:55], v[66:67], 0, v[0:1]
	v_or_b32_e32 v0, v87, v83
	v_max_f32_e32 v56, v56, v56
	v_max_f32_e32 v56, 0, v56
	v_lshlrev_b32_e32 v0, 7, v0
	v_mul_f32_e32 v56, v56, v56
	v_and_b32_e32 v0, 0x2700, v0
	global_store_short v[54:55], v74, off
	v_cvt_pk_bf16_f32 v56, v56, s0
	v_lshl_add_u64 v[74:75], v[66:67], 0, v[0:1]
	global_store_short v[74:75], v56, off
	v_or_b32_e32 v0, v87, v86
	v_max_f32_e32 v56, v57, v57
	v_max_f32_e32 v56, 0, v56
	v_lshlrev_b32_e32 v0, 7, v0
	v_mfma_f32_32x32x16_bf16 v[34:49], v[88:91], v[100:103], v[34:49]
	v_mul_f32_e32 v56, v56, v56
	v_and_b32_e32 v0, 0x2780, v0
	v_or_b32_e32 v88, 16, v85
	v_cvt_pk_bf16_f32 v76, v56, s0
	v_lshl_add_u64 v[56:57], v[66:67], 0, v[0:1]
	v_or_b32_e32 v0, v88, v84
	v_max_f32_e32 v58, v58, v58
	v_max_f32_e32 v58, 0, v58
	v_lshlrev_b32_e32 v0, 7, v0
	v_mul_f32_e32 v58, v58, v58
	v_and_b32_e32 v0, 0x2a00, v0
	global_store_short v[56:57], v76, off
	v_cvt_pk_bf16_f32 v58, v58, s0
	v_lshl_add_u64 v[76:77], v[66:67], 0, v[0:1]
	global_store_short v[76:77], v58, off
	v_or_b32_e32 v0, v88, v82
	v_max_f32_e32 v58, v59, v59
	v_max_f32_e32 v58, 0, v58
	v_lshlrev_b32_e32 v0, 7, v0
	v_mul_f32_e32 v58, v58, v58
	v_and_b32_e32 v0, 0x2a80, v0
	v_cvt_pk_bf16_f32 v78, v58, s0
	v_lshl_add_u64 v[58:59], v[66:67], 0, v[0:1]
	v_or_b32_e32 v0, v88, v83
	v_max_f32_e32 v60, v60, v60
	v_max_f32_e32 v60, 0, v60
	v_lshlrev_b32_e32 v0, 7, v0
	v_mul_f32_e32 v60, v60, v60
	v_and_b32_e32 v0, 0x2b00, v0
	global_store_short v[58:59], v78, off
	v_cvt_pk_bf16_f32 v60, v60, s0
	v_lshl_add_u64 v[78:79], v[66:67], 0, v[0:1]
	global_store_short v[78:79], v60, off
	v_or_b32_e32 v0, v88, v86
	v_max_f32_e32 v60, v61, v61
	v_max_f32_e32 v60, 0, v60
	v_lshlrev_b32_e32 v0, 7, v0
	v_mul_f32_e32 v60, v60, v60
	v_and_b32_e32 v0, 0x2b80, v0
	v_or_b32_e32 v89, 24, v85
	v_cvt_pk_bf16_f32 v80, v60, s0
	v_lshl_add_u64 v[60:61], v[66:67], 0, v[0:1]
	v_or_b32_e32 v0, v89, v84
	v_max_f32_e32 v62, v62, v62
	v_max_f32_e32 v62, 0, v62
	v_lshlrev_b32_e32 v0, 7, v0
	v_mul_f32_e32 v62, v62, v62
	v_and_b32_e32 v0, 0x2e00, v0
	global_store_short v[60:61], v80, off
	v_cvt_pk_bf16_f32 v62, v62, s0
	v_lshl_add_u64 v[80:81], v[66:67], 0, v[0:1]
	global_store_short v[80:81], v62, off
	v_or_b32_e32 v0, v89, v82
	v_max_f32_e32 v62, v63, v63
	v_max_f32_e32 v62, 0, v62
	v_lshlrev_b32_e32 v0, 7, v0
	v_mul_f32_e32 v62, v62, v62
	v_and_b32_e32 v0, 0x2e80, v0
	v_cvt_pk_bf16_f32 v82, v62, s0
	v_lshl_add_u64 v[62:63], v[66:67], 0, v[0:1]
	v_or_b32_e32 v0, v89, v83
	v_max_f32_e32 v64, v64, v64
	v_max_f32_e32 v64, 0, v64
	v_lshlrev_b32_e32 v0, 7, v0
	v_mul_f32_e32 v64, v64, v64
	v_and_b32_e32 v0, 0x2f00, v0
	global_store_short v[62:63], v82, off
	v_cvt_pk_bf16_f32 v64, v64, s0
	v_lshl_add_u64 v[82:83], v[66:67], 0, v[0:1]
	global_store_short v[82:83], v64, off
	v_or_b32_e32 v0, v89, v86
	v_max_f32_e32 v64, v65, v65
	v_max_f32_e32 v64, 0, v64
	v_lshlrev_b32_e32 v0, 7, v0
	v_mul_f32_e32 v64, v64, v64
	v_and_b32_e32 v0, 0x2f80, v0
	v_cvt_pk_bf16_f32 v86, v64, s0
	v_lshl_add_u64 v[64:65], v[66:67], 0, v[0:1]
	v_max_f32_e32 v0, v34, v34
	v_max_f32_e32 v0, 0, v0
	v_mul_f32_e32 v0, v0, v0
	v_cvt_pk_bf16_f32 v0, v0, s0
	global_store_short v[64:65], v86, off
	global_store_short v[68:69], v0, off offset:64
	v_max_f32_e32 v0, v35, v35
	v_max_f32_e32 v0, 0, v0
	v_mul_f32_e32 v0, v0, v0
	v_cvt_pk_bf16_f32 v0, v0, s0
	global_store_short v[50:51], v0, off offset:64
	v_max_f32_e32 v0, v36, v36
	v_max_f32_e32 v0, 0, v0
	v_mul_f32_e32 v0, v0, v0
	v_cvt_pk_bf16_f32 v0, v0, s0
	global_store_short v[70:71], v0, off offset:64
	v_max_f32_e32 v0, v37, v37
	v_max_f32_e32 v0, 0, v0
	v_mul_f32_e32 v0, v0, v0
	v_cvt_pk_bf16_f32 v0, v0, s0
	global_store_short v[52:53], v0, off offset:64
	v_max_f32_e32 v0, v38, v38
	v_max_f32_e32 v0, 0, v0
	v_mul_f32_e32 v0, v0, v0
	v_cvt_pk_bf16_f32 v0, v0, s0
	global_store_short v[72:73], v0, off offset:64
	v_max_f32_e32 v0, v39, v39
	v_max_f32_e32 v0, 0, v0
	v_mul_f32_e32 v0, v0, v0
	v_cvt_pk_bf16_f32 v0, v0, s0
	global_store_short v[54:55], v0, off offset:64
	v_max_f32_e32 v0, v40, v40
	v_max_f32_e32 v0, 0, v0
	v_mul_f32_e32 v0, v0, v0
	v_cvt_pk_bf16_f32 v0, v0, s0
	global_store_short v[74:75], v0, off offset:64
	v_max_f32_e32 v0, v41, v41
	v_max_f32_e32 v0, 0, v0
	v_mul_f32_e32 v0, v0, v0
	v_cvt_pk_bf16_f32 v0, v0, s0
	global_store_short v[56:57], v0, off offset:64
	v_max_f32_e32 v0, v42, v42
	v_max_f32_e32 v0, 0, v0
	v_mul_f32_e32 v0, v0, v0
	v_cvt_pk_bf16_f32 v0, v0, s0
	global_store_short v[76:77], v0, off offset:64
	v_max_f32_e32 v0, v43, v43
	v_max_f32_e32 v0, 0, v0
	v_mul_f32_e32 v0, v0, v0
	v_cvt_pk_bf16_f32 v0, v0, s0
	global_store_short v[58:59], v0, off offset:64
	v_max_f32_e32 v0, v44, v44
	v_max_f32_e32 v0, 0, v0
	v_mul_f32_e32 v0, v0, v0
	v_cvt_pk_bf16_f32 v0, v0, s0
	global_store_short v[78:79], v0, off offset:64
	v_max_f32_e32 v0, v45, v45
	v_max_f32_e32 v0, 0, v0
	v_mul_f32_e32 v0, v0, v0
	v_cvt_pk_bf16_f32 v0, v0, s0
	global_store_short v[60:61], v0, off offset:64
	v_max_f32_e32 v0, v46, v46
	v_max_f32_e32 v0, 0, v0
	v_mul_f32_e32 v0, v0, v0
	v_cvt_pk_bf16_f32 v0, v0, s0
	global_store_short v[80:81], v0, off offset:64
	v_max_f32_e32 v0, v47, v47
	v_max_f32_e32 v0, 0, v0
	v_mul_f32_e32 v0, v0, v0
	v_cvt_pk_bf16_f32 v0, v0, s0
	v_mfma_f32_32x32x16_bf16 v[18:33], v[92:95], v[96:99], v[18:33]
	global_store_short v[62:63], v0, off offset:64
	v_max_f32_e32 v0, v48, v48
	v_max_f32_e32 v0, 0, v0
	v_mul_f32_e32 v0, v0, v0
	v_cvt_pk_bf16_f32 v0, v0, s0
	global_store_short v[82:83], v0, off offset:64
	v_max_f32_e32 v0, v49, v49
	v_max_f32_e32 v0, 0, v0
	v_mul_f32_e32 v0, v0, v0
	v_cvt_pk_bf16_f32 v0, v0, s0
	v_or_b32_e32 v46, 32, v84
	global_store_short v[64:65], v0, off offset:64
	v_or_b32_e32 v0, v85, v46
	v_max_f32_e32 v18, v18, v18
	v_max_f32_e32 v18, 0, v18
	v_lshlrev_b32_e32 v0, 7, v0
	v_mul_f32_e32 v18, v18, v18
	v_and_b32_e32 v0, 0x3200, v0
	v_cvt_pk_bf16_f32 v18, v18, s0
	v_lshl_add_u64 v[34:35], v[66:67], 0, v[0:1]
	v_or_b32_e32 v48, 33, v84
	global_store_short v[34:35], v18, off
	v_or_b32_e32 v0, v85, v48
	v_max_f32_e32 v18, v19, v19
	v_max_f32_e32 v18, 0, v18
	v_lshlrev_b32_e32 v0, 7, v0
	v_mul_f32_e32 v18, v18, v18
	v_and_b32_e32 v0, 0x3280, v0
	v_or_b32_e32 v49, 34, v84
	v_cvt_pk_bf16_f32 v36, v18, s0
	v_lshl_add_u64 v[18:19], v[66:67], 0, v[0:1]
	v_or_b32_e32 v0, v85, v49
	v_max_f32_e32 v20, v20, v20
	v_max_f32_e32 v20, 0, v20
	v_lshlrev_b32_e32 v0, 7, v0
	v_mul_f32_e32 v20, v20, v20
	v_and_b32_e32 v0, 0x3300, v0
	global_store_short v[18:19], v36, off
	v_cvt_pk_bf16_f32 v20, v20, s0
	v_lshl_add_u64 v[36:37], v[66:67], 0, v[0:1]
	v_or_b32_e32 v50, 35, v84
	global_store_short v[36:37], v20, off
	v_or_b32_e32 v0, v85, v50
	v_max_f32_e32 v20, v21, v21
	v_max_f32_e32 v20, 0, v20
	v_lshlrev_b32_e32 v0, 7, v0
	v_mul_f32_e32 v20, v20, v20
	v_and_b32_e32 v0, 0x3380, v0
	v_cvt_pk_bf16_f32 v38, v20, s0
	v_lshl_add_u64 v[20:21], v[66:67], 0, v[0:1]
	v_or_b32_e32 v0, v87, v46
	v_max_f32_e32 v22, v22, v22
	v_max_f32_e32 v22, 0, v22
	v_lshlrev_b32_e32 v0, 7, v0
	v_mul_f32_e32 v22, v22, v22
	v_and_b32_e32 v0, 0x3600, v0
	global_store_short v[20:21], v38, off
	v_cvt_pk_bf16_f32 v22, v22, s0
	v_lshl_add_u64 v[38:39], v[66:67], 0, v[0:1]
	global_store_short v[38:39], v22, off
	v_or_b32_e32 v0, v87, v48
	v_max_f32_e32 v22, v23, v23
	v_max_f32_e32 v22, 0, v22
	v_lshlrev_b32_e32 v0, 7, v0
	v_mul_f32_e32 v22, v22, v22
	v_and_b32_e32 v0, 0x3680, v0
	v_cvt_pk_bf16_f32 v40, v22, s0
	v_lshl_add_u64 v[22:23], v[66:67], 0, v[0:1]
	v_or_b32_e32 v0, v87, v49
	v_max_f32_e32 v24, v24, v24
	v_max_f32_e32 v24, 0, v24
	v_lshlrev_b32_e32 v0, 7, v0
	v_mul_f32_e32 v24, v24, v24
	v_and_b32_e32 v0, 0x3700, v0
	global_store_short v[22:23], v40, off
	v_cvt_pk_bf16_f32 v24, v24, s0
	v_lshl_add_u64 v[40:41], v[66:67], 0, v[0:1]
	global_store_short v[40:41], v24, off
	v_or_b32_e32 v0, v87, v50
	v_max_f32_e32 v24, v25, v25
	v_max_f32_e32 v24, 0, v24
	v_lshlrev_b32_e32 v0, 7, v0
	v_mul_f32_e32 v24, v24, v24
	v_and_b32_e32 v0, 0x3780, v0
	v_cvt_pk_bf16_f32 v42, v24, s0
	v_lshl_add_u64 v[24:25], v[66:67], 0, v[0:1]
	v_or_b32_e32 v0, v88, v46
	v_max_f32_e32 v26, v26, v26
	v_max_f32_e32 v26, 0, v26
	v_lshlrev_b32_e32 v0, 7, v0
	v_mul_f32_e32 v26, v26, v26
	v_and_b32_e32 v0, 0x3a00, v0
	global_store_short v[24:25], v42, off
	v_cvt_pk_bf16_f32 v26, v26, s0
	v_lshl_add_u64 v[42:43], v[66:67], 0, v[0:1]
	global_store_short v[42:43], v26, off
	v_or_b32_e32 v0, v88, v48
	v_max_f32_e32 v26, v27, v27
	v_max_f32_e32 v26, 0, v26
	v_lshlrev_b32_e32 v0, 7, v0
	v_mul_f32_e32 v26, v26, v26
	v_and_b32_e32 v0, 0x3a80, v0
	v_cvt_pk_bf16_f32 v44, v26, s0
	v_lshl_add_u64 v[26:27], v[66:67], 0, v[0:1]
	v_or_b32_e32 v0, v88, v49
	v_max_f32_e32 v28, v28, v28
	v_max_f32_e32 v28, 0, v28
	v_lshlrev_b32_e32 v0, 7, v0
	v_mul_f32_e32 v28, v28, v28
	v_and_b32_e32 v0, 0x3b00, v0
	global_store_short v[26:27], v44, off
	v_cvt_pk_bf16_f32 v28, v28, s0
	v_lshl_add_u64 v[44:45], v[66:67], 0, v[0:1]
	global_store_short v[44:45], v28, off
	v_or_b32_e32 v0, v88, v50
	v_max_f32_e32 v28, v29, v29
	v_max_f32_e32 v28, 0, v28
	v_lshlrev_b32_e32 v0, 7, v0
	v_mul_f32_e32 v28, v28, v28
	v_and_b32_e32 v0, 0x3b80, v0
	v_cvt_pk_bf16_f32 v47, v28, s0
	v_lshl_add_u64 v[28:29], v[66:67], 0, v[0:1]
	v_or_b32_e32 v0, v89, v46
	v_max_f32_e32 v30, v30, v30
	v_max_f32_e32 v30, 0, v30
	v_lshlrev_b32_e32 v0, 7, v0
	v_mul_f32_e32 v30, v30, v30
	v_and_b32_e32 v0, 0x3e00, v0
	global_store_short v[28:29], v47, off
	v_cvt_pk_bf16_f32 v30, v30, s0
	v_lshl_add_u64 v[46:47], v[66:67], 0, v[0:1]
	global_store_short v[46:47], v30, off
	v_or_b32_e32 v0, v89, v48
	v_max_f32_e32 v30, v31, v31
	v_max_f32_e32 v30, 0, v30
	v_lshlrev_b32_e32 v0, 7, v0
	v_mfma_f32_32x32x16_bf16 v[2:17], v[92:95], v[100:103], v[2:17]
	v_mul_f32_e32 v30, v30, v30
	v_and_b32_e32 v0, 0x3e80, v0
	v_cvt_pk_bf16_f32 v48, v30, s0
	v_lshl_add_u64 v[30:31], v[66:67], 0, v[0:1]
	v_or_b32_e32 v0, v89, v49
	v_max_f32_e32 v32, v32, v32
	v_max_f32_e32 v32, 0, v32
	v_lshlrev_b32_e32 v0, 7, v0
	v_mul_f32_e32 v32, v32, v32
	v_and_b32_e32 v0, 0x3f00, v0
	global_store_short v[30:31], v48, off
	v_cvt_pk_bf16_f32 v32, v32, s0
	v_lshl_add_u64 v[48:49], v[66:67], 0, v[0:1]
	global_store_short v[48:49], v32, off
	v_or_b32_e32 v0, v89, v50
	v_max_f32_e32 v32, v33, v33
	v_max_f32_e32 v32, 0, v32
	v_lshlrev_b32_e32 v0, 7, v0
	v_mul_f32_e32 v32, v32, v32
	v_and_b32_e32 v0, 0x3f80, v0
	v_cvt_pk_bf16_f32 v50, v32, s0
	v_lshl_add_u64 v[32:33], v[66:67], 0, v[0:1]
	v_max_f32_e32 v0, v2, v2
	v_max_f32_e32 v0, 0, v0
	v_mul_f32_e32 v0, v0, v0
	v_cvt_pk_bf16_f32 v0, v0, s0
	global_store_short v[32:33], v50, off
	global_store_short v[34:35], v0, off offset:64
	v_max_f32_e32 v0, v3, v3
	v_max_f32_e32 v0, 0, v0
	v_mul_f32_e32 v0, v0, v0
	v_cvt_pk_bf16_f32 v0, v0, s0
	global_store_short v[18:19], v0, off offset:64
	v_max_f32_e32 v0, v4, v4
	v_max_f32_e32 v0, 0, v0
	v_mul_f32_e32 v0, v0, v0
	v_cvt_pk_bf16_f32 v0, v0, s0
	global_store_short v[36:37], v0, off offset:64
	v_max_f32_e32 v0, v5, v5
	v_max_f32_e32 v0, 0, v0
	v_mul_f32_e32 v0, v0, v0
	v_cvt_pk_bf16_f32 v0, v0, s0
	global_store_short v[20:21], v0, off offset:64
	v_max_f32_e32 v0, v6, v6
	v_max_f32_e32 v0, 0, v0
	v_mul_f32_e32 v0, v0, v0
	v_cvt_pk_bf16_f32 v0, v0, s0
	global_store_short v[38:39], v0, off offset:64
	v_max_f32_e32 v0, v7, v7
	v_max_f32_e32 v0, 0, v0
	v_mul_f32_e32 v0, v0, v0
	v_cvt_pk_bf16_f32 v0, v0, s0
	global_store_short v[22:23], v0, off offset:64
	v_max_f32_e32 v0, v8, v8
	v_max_f32_e32 v0, 0, v0
	v_mul_f32_e32 v0, v0, v0
	v_cvt_pk_bf16_f32 v0, v0, s0
	global_store_short v[40:41], v0, off offset:64
	v_max_f32_e32 v0, v9, v9
	v_max_f32_e32 v0, 0, v0
	v_mul_f32_e32 v0, v0, v0
	v_cvt_pk_bf16_f32 v0, v0, s0
	global_store_short v[24:25], v0, off offset:64
	v_max_f32_e32 v0, v10, v10
	v_max_f32_e32 v0, 0, v0
	v_mul_f32_e32 v0, v0, v0
	v_cvt_pk_bf16_f32 v0, v0, s0
	global_store_short v[42:43], v0, off offset:64
	v_max_f32_e32 v0, v11, v11
	v_max_f32_e32 v0, 0, v0
	v_mul_f32_e32 v0, v0, v0
	v_cvt_pk_bf16_f32 v0, v0, s0
	global_store_short v[26:27], v0, off offset:64
	v_max_f32_e32 v0, v12, v12
	v_max_f32_e32 v0, 0, v0
	v_mul_f32_e32 v0, v0, v0
	v_cvt_pk_bf16_f32 v0, v0, s0
	global_store_short v[44:45], v0, off offset:64
	v_max_f32_e32 v0, v13, v13
	v_max_f32_e32 v0, 0, v0
	v_mul_f32_e32 v0, v0, v0
	v_cvt_pk_bf16_f32 v0, v0, s0
	global_store_short v[28:29], v0, off offset:64
	v_max_f32_e32 v0, v14, v14
	v_max_f32_e32 v0, 0, v0
	v_mul_f32_e32 v0, v0, v0
	v_cvt_pk_bf16_f32 v0, v0, s0
	global_store_short v[46:47], v0, off offset:64
	v_max_f32_e32 v0, v15, v15
	v_max_f32_e32 v0, 0, v0
	v_mul_f32_e32 v0, v0, v0
	v_cvt_pk_bf16_f32 v0, v0, s0
	global_store_short v[30:31], v0, off offset:64
	v_max_f32_e32 v0, v16, v16
	v_max_f32_e32 v0, 0, v0
	v_mul_f32_e32 v0, v0, v0
	v_cvt_pk_bf16_f32 v0, v0, s0
	global_store_short v[48:49], v0, off offset:64
	v_max_f32_e32 v0, v17, v17
	v_max_f32_e32 v0, 0, v0
	v_mul_f32_e32 v0, v0, v0
	v_cvt_pk_bf16_f32 v0, v0, s0
	s_cmp_lt_i32 s5, s2
	global_store_short v[32:33], v0, off offset:64
	s_cmpk_lt_i32 s5, 0x1000
	s_cbranch_scc1 .LBB0_1298
	s_cmpk_ge_i32 s5, 0x1200
	s_cbranch_scc1 .Lph8_done
	s_cmpk_le_i32 s2, 0x1000
	s_cbranch_scc1 .Lph8_done
	v_readlane_b32 s6, v209, 2
	s_cmpk_ge_u32 s6, 0x100
	s_cbranch_scc1 .Lph8_done
	s_and_b32 s7, s6, 7
	s_lshl_b32 s7, s7, 2
	s_lshr_b32 s6, s6, 3
	s_and_b32 s5, s6, 3
	s_or_b32 s7, s7, s5
	s_lshr_b32 s6, s6, 2
	s_lshl_b32 s6, s6, 5
	s_or_b32 s5, s6, s7
	s_addk_i32 s5, 0x1000
	s_lshl_b32 s4, s5, 7
	s_branch .LBB0_1298

.LBB0_1355:
	s_ashr_i32 s2, s7, 31
	s_lshr_b32 s2, s2, 29
	s_add_i32 s8, s7, s2
	s_ashr_i32 s2, s8, 3
	s_ashr_i32 s3, s2, 31
	v_readlane_b32 s36, v210, 50
	s_lshl_b64 s[4:5], s[2:3], 20
	v_readlane_b32 s50, v209, 0
	v_readlane_b32 s51, v209, 1
	s_add_u32 s4, s50, s4
	v_mov_b32_e32 v52, v133
	s_addc_u32 s5, s51, s5
	s_and_b32 s3, s8, 0x1fffff8
	s_sub_i32 s3, s7, s3
	v_ashrrev_i32_e32 v34, 3, v52
	v_ashrrev_i32_e32 v35, 31, v34
	s_lshl_b32 s8, s3, 7
	v_lshlrev_b64 v[2:3], 7, v[34:35]
	v_lshl_add_u64 v[134:135], s[4:5], 0, v[2:3]
	v_lshlrev_b32_e32 v0, 4, v52
	v_add_u32_e32 v2, s8, v34
	v_and_b32_e32 v0, 0x70, v0
	v_ashrrev_i32_e32 v3, 31, v2
	v_lshl_add_u64 v[36:37], v[134:135], 0, v[0:1]
	v_lshlrev_b64 v[2:3], 13, v[2:3]
	v_lshl_add_u64 v[136:137], s[0:1], 0, v[2:3]
	v_add_co_u32_e32 v18, vcc, s53, v36
	v_lshl_add_u64 v[38:39], v[136:137], 0, v[0:1]
	v_lshrrev_b32_e32 v232, 4, v133
	v_xor_b32_e32 v232, v232, v133
	v_and_b32_e32 v232, 7, v232
	v_lshlrev_b32_e32 v232, 4, v232
	v_mov_b32_e32 v233, 0x70
	v_lshrrev_b32_e32 v238, 6, v133
	v_lshlrev_b32_e32 v238, 10, v238
	s_nop 0
	v_readfirstlane_b32 s32, v238
	v_bfi_b32 v216, v233, v232, v36
	v_mov_b32_e32 v217, v37
	v_bfi_b32 v224, v233, v232, v38
	v_mov_b32_e32 v225, v39
	v_mov_b32_e32 v234, 0x1000
	v_mov_b32_e32 v235, 0
	v_mov_b32_e32 v236, 0x40000
	v_mov_b32_e32 v237, 0
	v_lshl_add_u64 v[218:219], v[234:235], 0, v[216:217]
	v_lshl_add_u64 v[220:221], v[234:235], 1, v[216:217]
	v_lshl_add_u64 v[222:223], v[234:235], 1, v[218:219]
	v_lshl_add_u64 v[226:227], v[236:237], 0, v[224:225]
	v_lshl_add_u64 v[228:229], v[236:237], 1, v[224:225]
	v_lshl_add_u64 v[230:231], v[236:237], 1, v[226:227]
	s_add_u32 m0, s32, 0x0
	s_nop 0
	global_load_lds_dwordx4 v[216:217], off sc1
	s_add_u32 m0, s32, 0x1000
	v_lshl_add_u64 v[216:217], v[234:235], 2, v[216:217]
	global_load_lds_dwordx4 v[218:219], off sc1
	s_add_u32 m0, s32, 0x2000
	v_lshl_add_u64 v[218:219], v[234:235], 2, v[218:219]
	global_load_lds_dwordx4 v[220:221], off sc1
	s_add_u32 m0, s32, 0x3000
	v_lshl_add_u64 v[220:221], v[234:235], 2, v[220:221]
	global_load_lds_dwordx4 v[222:223], off sc1
	s_add_u32 m0, s32, 0x8000
	v_lshl_add_u64 v[222:223], v[234:235], 2, v[222:223]
	global_load_lds_dwordx4 v[224:225], off
	s_add_u32 m0, s32, 0x9000
	v_lshl_add_u64 v[224:225], 32, 2, v[224:225]
	global_load_lds_dwordx4 v[226:227], off
	s_add_u32 m0, s32, 0xa000
	v_lshl_add_u64 v[226:227], 32, 2, v[226:227]
	global_load_lds_dwordx4 v[228:229], off
	s_add_u32 m0, s32, 0xb000
	v_lshl_add_u64 v[228:229], 32, 2, v[228:229]
	global_load_lds_dwordx4 v[230:231], off
	v_lshl_add_u64 v[230:231], 32, 2, v[230:231]
	s_add_u32 m0, s32, 0x4000
	s_nop 0
	global_load_lds_dwordx4 v[216:217], off sc1
	s_add_u32 m0, s32, 0x5000
	v_lshl_add_u64 v[216:217], v[234:235], 2, v[216:217]
	global_load_lds_dwordx4 v[218:219], off sc1
	s_add_u32 m0, s32, 0x6000
	v_lshl_add_u64 v[218:219], v[234:235], 2, v[218:219]
	global_load_lds_dwordx4 v[220:221], off sc1
	s_add_u32 m0, s32, 0x7000
	v_lshl_add_u64 v[220:221], v[234:235], 2, v[220:221]
	global_load_lds_dwordx4 v[222:223], off sc1
	s_add_u32 m0, s32, 0xc000
	v_lshl_add_u64 v[222:223], v[234:235], 2, v[222:223]
	global_load_lds_dwordx4 v[224:225], off
	s_add_u32 m0, s32, 0xd000
	v_lshl_add_u64 v[224:225], 32, 2, v[224:225]
	global_load_lds_dwordx4 v[226:227], off
	s_add_u32 m0, s32, 0xe000
	v_lshl_add_u64 v[226:227], 32, 2, v[226:227]
	global_load_lds_dwordx4 v[228:229], off
	s_add_u32 m0, s32, 0xf000
	v_lshl_add_u64 v[228:229], 32, 2, v[228:229]
	global_load_lds_dwordx4 v[230:231], off
	v_lshl_add_u64 v[230:231], 32, 2, v[230:231]
	s_nop 0
	v_addc_co_u32_e32 v19, vcc, 0, v37, vcc
	s_mov_b32 s3, 0x40000
	v_add_co_u32_e32 v40, vcc, s3, v38
	s_mov_b32 s3, 0x80000
	s_nop 0
	v_addc_co_u32_e32 v41, vcc, 0, v39, vcc
	v_add_co_u32_e32 v42, vcc, s3, v38
	s_nop 0
	v_addc_co_u32_e32 v43, vcc, 0, v39, vcc
	v_add_co_u32_e32 v44, vcc, s9, v36
	s_mov_b32 s3, 0xc0000
	s_nop 0
	v_addc_co_u32_e32 v45, vcc, 0, v37, vcc
	v_add_co_u32_e32 v46, vcc, s3, v38
	s_nop 0
	v_addc_co_u32_e32 v47, vcc, 0, v39, vcc
	v_lshlrev_b32_e32 v0, 7, v34
	v_lshrrev_b32_e32 v34, 1, v34
	v_xor_b32_e32 v34, v34, v52
	v_lshlrev_b32_e32 v34, 4, v34
	s_movk_i32 s4, 0x6000
	v_and_or_b32 v146, v34, s59, v0
	v_add_co_u32_e32 v34, vcc, s4, v36
	v_and_b32_e32 v142, 31, v52
	s_nop 0
	v_addc_co_u32_e32 v35, vcc, 0, v37, vcc
	v_add_co_u32_e32 v48, vcc, s10, v36
	v_ashrrev_i32_e32 v144, 7, v52
	s_nop 0
	v_addc_co_u32_e32 v49, vcc, 0, v37, vcc
	v_add_co_u32_e32 v50, vcc, s34, v36
	v_bfe_u32 v145, v52, 5, 1
	s_nop 0
	v_addc_co_u32_e32 v51, vcc, 0, v37, vcc
	v_bfe_u32 v143, v52, 6, 1
	v_lshlrev_b32_e32 v0, 7, v142
	v_lshl_or_b32 v147, v144, 13, v0
	v_lshl_or_b32 v149, v143, 13, v0
	s_mov_b32 s3, 0
	v_readlane_b32 s37, v210, 51
	v_readlane_b32 s38, v210, 52
	v_readlane_b32 s39, v210, 53
	v_readlane_b32 s40, v210, 54
	v_readlane_b32 s41, v210, 55
	v_readlane_b32 s42, v210, 56
	v_readlane_b32 s43, v210, 57
	v_readlane_b32 s44, v210, 58
	v_readlane_b32 s45, v210, 59
	v_readlane_b32 s46, v210, 60
	v_readlane_b32 s47, v210, 61
	v_readlane_b32 s48, v210, 62
	v_readlane_b32 s49, v210, 63
	v_add_co_u32_e32 v2, vcc, s52, v36
	s_waitcnt vmcnt(8)
	s_waitcnt lgkmcnt(0)
	s_barrier
	v_addc_co_u32_e32 v3, vcc, 0, v37, vcc
	v_bfe_u32 v3, v52, 1, 3
	v_bitop3_b32 v0, v145, v3, 2 bitop3:0x36
	v_lshrrev_b32_e32 v2, 1, v52
	v_lshlrev_b32_e32 v150, 4, v0
	v_bitop3_b32 v0, v145, v3, 4 bitop3:0x36
	v_bitop3_b32 v2, v2, v145, 7 bitop3:0x6c
	v_lshlrev_b32_e32 v151, 4, v0
	v_bitop3_b32 v0, v145, v3, 6 bitop3:0x36
	v_lshlrev_b32_e32 v148, 4, v2
	v_lshlrev_b32_e32 v152, 4, v0
	v_and_b32_e32 v0, 7, v52
	v_mov_b32_e32 v2, 0
	v_lshlrev_b32_e32 v0, 4, v0
	v_mov_b32_e32 v3, v2
	v_mov_b32_e32 v4, v2
	v_mov_b32_e32 v5, v2
	v_mov_b32_e32 v6, v2
	v_mov_b32_e32 v7, v2
	v_mov_b32_e32 v8, v2
	v_mov_b32_e32 v9, v2
	v_mov_b32_e32 v10, v2
	v_mov_b32_e32 v11, v2
	v_mov_b32_e32 v12, v2
	v_mov_b32_e32 v13, v2
	v_mov_b32_e32 v14, v2
	v_mov_b32_e32 v15, v2
	v_mov_b32_e32 v16, v2
	v_mov_b32_e32 v17, v2
	v_mov_b32_e32 v34, v2
	v_mov_b32_e32 v35, v2
	v_mov_b32_e32 v36, v2
	v_mov_b32_e32 v37, v2
	v_mov_b32_e32 v38, v2
	v_mov_b32_e32 v39, v2
	v_mov_b32_e32 v40, v2
	v_mov_b32_e32 v41, v2
	v_mov_b32_e32 v42, v2
	v_mov_b32_e32 v43, v2
	v_mov_b32_e32 v44, v2
	v_mov_b32_e32 v45, v2
	v_mov_b32_e32 v46, v2
	v_mov_b32_e32 v47, v2
	v_mov_b32_e32 v48, v2
	v_mov_b32_e32 v49, v2
	v_mov_b32_e32 v18, v2
	v_mov_b32_e32 v19, v2
	v_mov_b32_e32 v20, v2
	v_mov_b32_e32 v21, v2
	v_mov_b32_e32 v22, v2
	v_mov_b32_e32 v23, v2
	v_mov_b32_e32 v24, v2
	v_mov_b32_e32 v25, v2
	v_mov_b32_e32 v26, v2
	v_mov_b32_e32 v27, v2
	v_mov_b32_e32 v28, v2
	v_mov_b32_e32 v29, v2
	v_mov_b32_e32 v30, v2
	v_mov_b32_e32 v31, v2
	v_mov_b32_e32 v32, v2
	v_mov_b32_e32 v33, v2
	v_mov_b32_e32 v50, v2
	v_mov_b32_e32 v51, v2
	v_mov_b32_e32 v52, v2
	v_mov_b32_e32 v53, v2
	v_mov_b32_e32 v54, v2
	v_mov_b32_e32 v55, v2
	v_mov_b32_e32 v56, v2
	v_mov_b32_e32 v57, v2
	v_mov_b32_e32 v58, v2
	v_mov_b32_e32 v59, v2
	v_mov_b32_e32 v60, v2
	v_mov_b32_e32 v61, v2
	v_mov_b32_e32 v62, v2
	v_mov_b32_e32 v63, v2
	v_mov_b32_e32 v64, v2
	v_mov_b32_e32 v65, v2
	s_branch .LBB0_1357
.LBB0_1356:
	v_mfma_f32_32x32x16_bf16 v[50:65], v[186:189], v[194:197], v[50:65]
	v_mfma_f32_32x32x16_bf16 v[18:33], v[186:189], v[158:161], v[18:33]
	v_mfma_f32_32x32x16_bf16 v[34:49], v[190:193], v[194:197], v[34:49]
	v_mfma_f32_32x32x16_bf16 v[2:17], v[190:193], v[158:161], v[2:17]
	s_cmp_gt_u32 s3, 60
	s_cbranch_scc1 .Ldma9_skip_b
	s_add_u32 m0, s32, 0x4000
	s_nop 0
	global_load_lds_dwordx4 v[216:217], off sc1
	s_add_u32 m0, s32, 0x5000
	v_lshl_add_u64 v[216:217], v[234:235], 2, v[216:217]
	global_load_lds_dwordx4 v[218:219], off sc1
	s_add_u32 m0, s32, 0x6000
	v_lshl_add_u64 v[218:219], v[234:235], 2, v[218:219]
	global_load_lds_dwordx4 v[220:221], off sc1
	s_add_u32 m0, s32, 0x7000
	v_lshl_add_u64 v[220:221], v[234:235], 2, v[220:221]
	global_load_lds_dwordx4 v[222:223], off sc1
	s_add_u32 m0, s32, 0xc000
	v_lshl_add_u64 v[222:223], v[234:235], 2, v[222:223]
	global_load_lds_dwordx4 v[224:225], off
	s_add_u32 m0, s32, 0xd000
	v_lshl_add_u64 v[224:225], 32, 2, v[224:225]
	global_load_lds_dwordx4 v[226:227], off
	s_add_u32 m0, s32, 0xe000
	v_lshl_add_u64 v[226:227], 32, 2, v[226:227]
	global_load_lds_dwordx4 v[228:229], off
	s_add_u32 m0, s32, 0xf000
	v_lshl_add_u64 v[228:229], 32, 2, v[228:229]
	global_load_lds_dwordx4 v[230:231], off
	v_lshl_add_u64 v[230:231], 32, 2, v[230:231]
	s_waitcnt vmcnt(8)
	s_branch .Ldma9_join_b

.LBB0_1359:
	s_cmp_gt_u32 s3, 60
	s_cbranch_scc1 .Ldma9_skip_a
	s_add_u32 m0, s32, 0x0
	s_nop 0
	global_load_lds_dwordx4 v[216:217], off sc1
	s_add_u32 m0, s32, 0x1000
	v_lshl_add_u64 v[216:217], v[234:235], 2, v[216:217]
	global_load_lds_dwordx4 v[218:219], off sc1
	s_add_u32 m0, s32, 0x2000
	v_lshl_add_u64 v[218:219], v[234:235], 2, v[218:219]
	global_load_lds_dwordx4 v[220:221], off sc1
	s_add_u32 m0, s32, 0x3000
	v_lshl_add_u64 v[220:221], v[234:235], 2, v[220:221]
	global_load_lds_dwordx4 v[222:223], off sc1
	s_add_u32 m0, s32, 0x8000
	v_lshl_add_u64 v[222:223], v[234:235], 2, v[222:223]
	global_load_lds_dwordx4 v[224:225], off
	s_add_u32 m0, s32, 0x9000
	v_lshl_add_u64 v[224:225], 32, 2, v[224:225]
	global_load_lds_dwordx4 v[226:227], off
	s_add_u32 m0, s32, 0xa000
	v_lshl_add_u64 v[226:227], 32, 2, v[226:227]
	global_load_lds_dwordx4 v[228:229], off
	s_add_u32 m0, s32, 0xb000
	v_lshl_add_u64 v[228:229], 32, 2, v[228:229]
	global_load_lds_dwordx4 v[230:231], off
	v_lshl_add_u64 v[230:231], 32, 2, v[230:231]
	s_waitcnt vmcnt(8)
	s_branch .Ldma9_join_a
